# v18 + nt stores in the RWKV in-projection epilogue (u_rw f16)
# baseline (speedup 1.0000x reference)
; __device__ __forceinline__ unsigned pk_bf16(float lo, float hi) { const f32x2 v = {lo, hi}; return __builtin_bit_cast(unsigned, __builtin_convertvector(v, b16x2)); }
; __device__ __forceinline__ float sigmoidf_(float x) { return __builtin_amdgcn_rcpf(1.0f + __expf(-x)); }
;     __device__ __forceinline__ void row(int r, int col32, int fq, const f32x4& a00, const f32x4& a01, const f32x4& a10, const f32x4& a11) const { half(r, col32, fq, a00, a01); half(r, col32 + HALF, fq, a10, a11); }
;     __device__ __forceinline__ void row(int r, int col32, int fq, const f32x4& a00, const f32x4& a01, const f32x4& a10, const f32x4& a11) const { half(r, col32, fq, a00, a01); half(r, col32 + HALF, fq, a10, a11); }
;     __device__ __forceinline__ void one(int row, int col, const f32x4& v) const {
;         if (col < 1536) {
;             const int which = col >> 9, hc = col & 511, h = hc >> 6, d = hc & 63, b = row / TP, t = row - b * TP;
;             const float s = which == 0 ? 0.125f : 1.0f;
;             u32x2 w; w.x = pk_bf16(v[0] * s, v[1] * s); w.y = pk_bf16(v[2] * s, v[3] * s);
;             *(u32x2*)(qkv + (size_t)which * (QKV_ONE / 2) + ((size_t)(b * NH + h) * TP + t) * 64 + d) = w;
;         } else if (col < 3328) {
;             h16x4 o; o[0] = (_Float16)v[0]; o[1] = (_Float16)v[1]; o[2] = (_Float16)v[2]; o[3] = (_Float16)v[3];
;             *(h16x4*)(urw + (size_t)row * RWS + (col - 1536)) = o;
;         } else {
;             const int b = row / TP, t = row - b * TP;
;             if (t >= NMETA && t < T) {
;                 u32x2 w; w.x = pk_bf16(sigmoidf_(v[0]), sigmoidf_(v[1])); w.y = pk_bf16(sigmoidf_(v[2]), sigmoidf_(v[3]));
;                 *(u32x2*)(gates + (size_t)(b * SEQ + t - NMETA) * 2048 + (col - 3328)) = w;
;             }
;         }
;     __device__ __forceinline__ void half(int row, int col32, int fq, const f32x4& v0, const f32x4& v1) const {
;     ...
;             if (col32 >= 1536 && col32 < 3072) {
;                 const int c = col32 - 1536, pos = (c & ~63) + fq * 16 + ((c & 63) >> 4) * 4;
;                 h16x8 o;
; #pragma unroll
;                 for (int j = 0; j < 4; ++j) { o[j] = (_Float16)v0[j]; o[4 + j] = (_Float16)v1[j]; }
;                 *(h16x8*)(urw + (size_t)row * RWS + pos) = o;
;             } else { one(row, col32 + 4 * fq, v0); one(row, col32 + 16 + 4 * fq, v1); }
.LBB0_159:
	s_lshl_b32 s12, s4, 8
	v_lshl_add_u32 v175, s0, 8, v145
	s_or_b32 s97, s12, s52
	s_add_i32 s0, s12, 0xfffffa00
	s_cmpk_gt_u32 s0, 0x5ff
	s_cselect_b64 s[14:15], -1, 0
	s_cmpk_gt_u32 s12, 0xcff
	s_cselect_b64 s[0:1], -1, 0
	s_ashr_i32 s77, s4, 1
	s_lshr_b32 s4, s97, 6
	s_and_b32 s96, s4, 5
	v_or_b32_e32 v134, s97, v149
	s_cmpk_lt_u32 s12, 0x200
	s_cselect_b64 vcc, -1, 0
	v_or_b32_e32 v146, 16, v134
	v_cmp_lt_i32_e64 s[8:9], s68, v134
	v_bitop3_b32 v174, s97, 44, v149 bitop3:0xc8
	v_cndmask_b32_e32 v144, 1.0, v155, vcc
	s_mul_hi_i32 s25, s77, 0x2080000
	s_mul_i32 s77, s77, 0x2080000
	v_cmp_lt_i32_e64 s[6:7], s68, v146
	v_bitop3_b32 v173, v134, 60, 16 bitop3:0xc8
	s_mov_b64 s[4:5], -1
	s_and_b64 vcc, exec, s[14:15]
	s_cbranch_vccz .LBB0_179
	s_and_saveexec_b64 s[4:5], s[8:9]
	s_xor_b64 s[4:5], exec, s[4:5]
	s_cbranch_execz .LBB0_167
	s_mov_b64 s[10:11], -1
	s_and_b64 vcc, exec, s[0:1]
	s_cbranch_vccz .LBB0_165
	v_mul_hi_i32 v146, v175, s69
	v_lshrrev_b32_e32 v147, 31, v146
	v_ashrrev_i32_e32 v146, 12, v146
	v_add_u32_e32 v146, v146, v147
	v_mul_i32_i24_e32 v147, 0xffffdf80, v146
	v_add3_u32 v147, v147, v175, -16
	v_cmp_gt_u32_e32 vcc, s65, v147
	s_and_saveexec_b64 s[10:11], vcc
	s_cbranch_execz .LBB0_164
	v_mul_f32_e32 v176, 0xbfb8aa3b, v124
	v_mul_f32_e32 v177, 0xbfb8aa3b, v125
	v_mul_f32_e32 v178, 0xbfb8aa3b, v126
	v_mul_f32_e32 v179, 0xbfb8aa3b, v127
	v_exp_f32_e32 v176, v176
	v_exp_f32_e32 v177, v177
	v_exp_f32_e32 v178, v178
	v_exp_f32_e32 v179, v179
	v_lshl_add_u32 v146, v146, 13, v147
	v_add_f32_e32 v176, 1.0, v176
	v_add_f32_e32 v177, 1.0, v177
	v_add_f32_e32 v178, 1.0, v178
	v_add_f32_e32 v179, 1.0, v179
	v_ashrrev_i32_e32 v147, 31, v146
	v_rcp_f32_e32 v176, v176
	v_rcp_f32_e32 v177, v177
	v_rcp_f32_e32 v178, v178
	v_rcp_f32_e32 v179, v179
	v_lshlrev_b64 v[146:147], 12, v[146:147]
	v_lshl_add_u64 v[146:147], s[88:89], 0, v[146:147]
	v_lshl_add_u64 v[146:147], v[134:135], 1, v[146:147]
	v_add_co_u32_e32 v146, vcc, 0xfffff000, v146
	v_cvt_pk_bf16_f32 v176, v176, v177
	v_cvt_pk_bf16_f32 v177, v178, v179
	v_addc_co_u32_e32 v147, vcc, -1, v147, vcc
	global_store_dwordx2 v[146:147], v[176:177], off offset:-2560 nt

; __device__ __forceinline__ unsigned pk_bf16(float lo, float hi) { const f32x2 v = {lo, hi}; return __builtin_bit_cast(unsigned, __builtin_convertvector(v, b16x2)); }
; __device__ __forceinline__ float sigmoidf_(float x) { return __builtin_amdgcn_rcpf(1.0f + __expf(-x)); }
;     __device__ __forceinline__ void row(int r, int col32, int fq, const f32x4& a00, const f32x4& a01, const f32x4& a10, const f32x4& a11) const { half(r, col32, fq, a00, a01); half(r, col32 + HALF, fq, a10, a11); }
;     __device__ __forceinline__ void row(int r, int col32, int fq, const f32x4& a00, const f32x4& a01, const f32x4& a10, const f32x4& a11) const { half(r, col32, fq, a00, a01); half(r, col32 + HALF, fq, a10, a11); }
;     __device__ __forceinline__ void row(int r, int col32, int fq, const f32x4& a00, const f32x4& a01, const f32x4& a10, const f32x4& a11) const { half(r, col32, fq, a00, a01); half(r, col32 + HALF, fq, a10, a11); }
;     __device__ __forceinline__ void one(int row, int col, const f32x4& v) const {
;         if (col < 1536) {
;             const int which = col >> 9, hc = col & 511, h = hc >> 6, d = hc & 63, b = row / TP, t = row - b * TP;
;             const float s = which == 0 ? 0.125f : 1.0f;
;             u32x2 w; w.x = pk_bf16(v[0] * s, v[1] * s); w.y = pk_bf16(v[2] * s, v[3] * s);
;             *(u32x2*)(qkv + (size_t)which * (QKV_ONE / 2) + ((size_t)(b * NH + h) * TP + t) * 64 + d) = w;
;         } else if (col < 3328) {
;             h16x4 o; o[0] = (_Float16)v[0]; o[1] = (_Float16)v[1]; o[2] = (_Float16)v[2]; o[3] = (_Float16)v[3];
;             *(h16x4*)(urw + (size_t)row * RWS + (col - 1536)) = o;
;         } else {
;             const int b = row / TP, t = row - b * TP;
;             if (t >= NMETA && t < T) {
;                 u32x2 w; w.x = pk_bf16(sigmoidf_(v[0]), sigmoidf_(v[1])); w.y = pk_bf16(sigmoidf_(v[2]), sigmoidf_(v[3]));
;                 *(u32x2*)(gates + (size_t)(b * SEQ + t - NMETA) * 2048 + (col - 3328)) = w;
;             }
;         }
.LBB0_165:
	s_andn2_b64 vcc, exec, s[10:11]
	s_cbranch_vccnz .LBB0_167
	v_mov_b64_e32 v[176:177], s[50:51]
	v_mad_i64_i32 v[176:177], s[10:11], v175, s73, v[176:177]
	v_cvt_pk_f16_f32 v147, v126, v127
	v_cvt_pk_f16_f32 v146, v124, v125
	v_lshl_add_u64 v[176:177], v[134:135], 1, v[176:177]
	global_store_dwordx2 v[176:177], v[146:147], off offset:-3072 nt
.LBB0_167:
	s_andn2_saveexec_b64 s[4:5], s[4:5]
	s_cbranch_execz .LBB0_169
	v_mul_hi_i32 v146, v175, s69
	v_lshrrev_b32_e32 v147, 31, v146
	v_ashrrev_i32_e32 v146, 12, v146
	v_add_u32_e32 v147, v146, v147
	v_mad_i32_i24 v146, v147, s72, v175
	v_pk_mul_f32 v[176:177], v[144:145], v[124:125] op_sel_hi:[0,1]
	v_pk_mul_f32 v[178:179], v[144:145], v[126:127] op_sel_hi:[0,1]
	v_lshl_or_b32 v147, v147, 3, s96
	v_cvt_pk_bf16_f32 v176, v176, v177
	v_cvt_pk_bf16_f32 v177, v178, v179
	v_mul_hi_i32_i24_e32 v179, 0x2080, v147
	v_mul_i32_i24_e32 v178, 0x2080, v147
	v_ashrrev_i32_e32 v147, 31, v146
	s_add_u32 s10, s50, s77
	v_lshl_add_u64 v[146:147], v[178:179], 0, v[146:147]
	s_addc_u32 s11, s51, s25
	v_lshlrev_b64 v[146:147], 7, v[146:147]
	v_lshl_add_u64 v[146:147], s[10:11], 0, v[146:147]
	v_lshlrev_b32_e32 v178, 1, v174
	v_mov_b32_e32 v179, v135
	v_lshl_add_u64 v[146:147], v[146:147], 0, v[178:179]
	global_store_dwordx2 v[146:147], v[176:177], off nt
.LBB0_169:
	s_or_b64 exec, exec, s[4:5]
	s_and_saveexec_b64 s[4:5], s[6:7]
	s_xor_b64 s[4:5], exec, s[4:5]
	s_cbranch_execz .LBB0_176
	s_mov_b64 s[10:11], -1
	s_and_b64 vcc, exec, s[0:1]
	s_cbranch_vccz .LBB0_174
	v_mul_hi_i32 v146, v175, s69
	v_lshrrev_b32_e32 v147, 31, v146
	v_ashrrev_i32_e32 v146, 12, v146
	v_add_u32_e32 v146, v146, v147
	v_mul_i32_i24_e32 v147, 0xffffdf80, v146
	v_add3_u32 v147, v147, v175, -16
	v_cmp_gt_u32_e32 vcc, s65, v147
	s_and_saveexec_b64 s[10:11], vcc
	s_cbranch_execz .LBB0_173
	v_mul_f32_e32 v176, 0xbfb8aa3b, v120
	v_mul_f32_e32 v177, 0xbfb8aa3b, v121
	v_mul_f32_e32 v178, 0xbfb8aa3b, v122
	v_mul_f32_e32 v179, 0xbfb8aa3b, v123
	v_exp_f32_e32 v176, v176
	v_exp_f32_e32 v177, v177
	v_exp_f32_e32 v178, v178
	v_exp_f32_e32 v179, v179
	v_lshl_add_u32 v146, v146, 13, v147
	v_add_f32_e32 v176, 1.0, v176
	v_add_f32_e32 v177, 1.0, v177
	v_add_f32_e32 v178, 1.0, v178
	v_add_f32_e32 v179, 1.0, v179
	v_ashrrev_i32_e32 v147, 31, v146
	v_rcp_f32_e32 v176, v176
	v_rcp_f32_e32 v177, v177
	v_rcp_f32_e32 v178, v178
	v_rcp_f32_e32 v179, v179
	v_lshlrev_b64 v[146:147], 12, v[146:147]
	v_lshl_add_u64 v[146:147], s[88:89], 0, v[146:147]
	v_lshl_add_u64 v[146:147], v[134:135], 1, v[146:147]
	v_add_co_u32_e32 v146, vcc, 0xfffff000, v146
	v_cvt_pk_bf16_f32 v176, v176, v177
	v_cvt_pk_bf16_f32 v177, v178, v179
	v_addc_co_u32_e32 v147, vcc, -1, v147, vcc
	global_store_dwordx2 v[146:147], v[176:177], off offset:-2528 nt

; __device__ __forceinline__ unsigned pk_bf16(float lo, float hi) { const f32x2 v = {lo, hi}; return __builtin_bit_cast(unsigned, __builtin_convertvector(v, b16x2)); }
;     __device__ __forceinline__ void row(int r, int col32, int fq, const f32x4& a00, const f32x4& a01, const f32x4& a10, const f32x4& a11) const { half(r, col32, fq, a00, a01); half(r, col32 + HALF, fq, a10, a11); }
;     __device__ __forceinline__ void row(int r, int col32, int fq, const f32x4& a00, const f32x4& a01, const f32x4& a10, const f32x4& a11) const { half(r, col32, fq, a00, a01); half(r, col32 + HALF, fq, a10, a11); }
;     __device__ __forceinline__ void row(int r, int col32, int fq, const f32x4& a00, const f32x4& a01, const f32x4& a10, const f32x4& a11) const { half(r, col32, fq, a00, a01); half(r, col32 + HALF, fq, a10, a11); }
;     __device__ __forceinline__ void one(int row, int col, const f32x4& v) const {
;         if (col < 1536) {
;             const int which = col >> 9, hc = col & 511, h = hc >> 6, d = hc & 63, b = row / TP, t = row - b * TP;
;             const float s = which == 0 ? 0.125f : 1.0f;
;             u32x2 w; w.x = pk_bf16(v[0] * s, v[1] * s); w.y = pk_bf16(v[2] * s, v[3] * s);
;             *(u32x2*)(qkv + (size_t)which * (QKV_ONE / 2) + ((size_t)(b * NH + h) * TP + t) * 64 + d) = w;
;         } else if (col < 3328) {
;             h16x4 o; o[0] = (_Float16)v[0]; o[1] = (_Float16)v[1]; o[2] = (_Float16)v[2]; o[3] = (_Float16)v[3];
;             *(h16x4*)(urw + (size_t)row * RWS + (col - 1536)) = o;
.LBB0_174:
	s_andn2_b64 vcc, exec, s[10:11]
	s_cbranch_vccnz .LBB0_176
	v_mov_b64_e32 v[176:177], s[50:51]
	v_mad_i64_i32 v[176:177], s[10:11], v175, s73, v[176:177]
	v_cvt_pk_f16_f32 v147, v122, v123
	v_cvt_pk_f16_f32 v146, v120, v121
	v_lshl_add_u64 v[176:177], v[134:135], 1, v[176:177]
	global_store_dwordx2 v[176:177], v[146:147], off offset:-3040 nt
.LBB0_176:
	s_andn2_saveexec_b64 s[4:5], s[4:5]
	s_cbranch_execz .LBB0_178
	v_mul_hi_i32 v146, v175, s69
	v_lshrrev_b32_e32 v147, 31, v146
	v_ashrrev_i32_e32 v146, 12, v146
	v_add_u32_e32 v147, v146, v147
	v_mad_i32_i24 v146, v147, s72, v175
	v_pk_mul_f32 v[176:177], v[144:145], v[120:121] op_sel_hi:[0,1]
	v_pk_mul_f32 v[178:179], v[144:145], v[122:123] op_sel_hi:[0,1]
	v_lshl_or_b32 v147, v147, 3, s96
	v_cvt_pk_bf16_f32 v176, v176, v177
	v_cvt_pk_bf16_f32 v177, v178, v179
	v_mul_hi_i32_i24_e32 v179, 0x2080, v147
	v_mul_i32_i24_e32 v178, 0x2080, v147
	v_ashrrev_i32_e32 v147, 31, v146
	s_add_u32 s10, s50, s77
	v_lshl_add_u64 v[146:147], v[178:179], 0, v[146:147]
	s_addc_u32 s11, s51, s25
	v_lshlrev_b64 v[146:147], 7, v[146:147]
	v_lshl_add_u64 v[146:147], s[10:11], 0, v[146:147]
	v_lshlrev_b32_e32 v178, 1, v173
	v_mov_b32_e32 v179, v135
	v_lshl_add_u64 v[146:147], v[146:147], 0, v[178:179]
	global_store_dwordx2 v[146:147], v[176:177], off nt

; __device__ __forceinline__ unsigned pk_bf16(float lo, float hi) { const f32x2 v = {lo, hi}; return __builtin_bit_cast(unsigned, __builtin_convertvector(v, b16x2)); }
; __device__ __forceinline__ float sigmoidf_(float x) { return __builtin_amdgcn_rcpf(1.0f + __expf(-x)); }
;     __device__ __forceinline__ void row(int r, int col32, int fq, const f32x4& a00, const f32x4& a01, const f32x4& a10, const f32x4& a11) const { half(r, col32, fq, a00, a01); half(r, col32 + HALF, fq, a10, a11); }
;     __device__ __forceinline__ void row(int r, int col32, int fq, const f32x4& a00, const f32x4& a01, const f32x4& a10, const f32x4& a11) const { half(r, col32, fq, a00, a01); half(r, col32 + HALF, fq, a10, a11); }
;     __device__ __forceinline__ void row(int r, int col32, int fq, const f32x4& a00, const f32x4& a01, const f32x4& a10, const f32x4& a11) const { half(r, col32, fq, a00, a01); half(r, col32 + HALF, fq, a10, a11); }
;     __device__ __forceinline__ void one(int row, int col, const f32x4& v) const {
;     ...
;         } else {
;             const int b = row / TP, t = row - b * TP;
;             if (t >= NMETA && t < T) {
;                 u32x2 w; w.x = pk_bf16(sigmoidf_(v[0]), sigmoidf_(v[1])); w.y = pk_bf16(sigmoidf_(v[2]), sigmoidf_(v[3]));
;                 *(u32x2*)(gates + (size_t)(b * SEQ + t - NMETA) * 2048 + (col - 3328)) = w;
;             }
;     __device__ __forceinline__ void half(int row, int col32, int fq, const f32x4& v0, const f32x4& v1) const {
;     ...
;             if (col32 >= 1536 && col32 < 3072) {
;                 const int c = col32 - 1536, pos = (c & ~63) + fq * 16 + ((c & 63) >> 4) * 4;
;                 h16x8 o;
; #pragma unroll
;                 for (int j = 0; j < 4; ++j) { o[j] = (_Float16)v0[j]; o[4 + j] = (_Float16)v1[j]; }
;                 *(h16x8*)(urw + (size_t)row * RWS + pos) = o;
;             } else { one(row, col32 + 4 * fq, v0); one(row, col32 + 16 + 4 * fq, v1); }
.LBB0_179:
	s_and_b32 s10, s97, 0xf40
	v_add_u32_e32 v146, s10, v150
	v_mov_b32_e32 v147, v135
	s_and_b64 vcc, exec, s[4:5]
	s_cbranch_vccz .LBB0_181
	v_cvt_pk_f16_f32 v123, v122, v123
	v_cvt_pk_f16_f32 v122, v120, v121
	v_cvt_pk_f16_f32 v120, v124, v125
	v_mov_b64_e32 v[124:125], s[50:51]
	v_mad_i64_i32 v[124:125], s[4:5], v175, s73, v[124:125]
	v_cvt_pk_f16_f32 v121, v126, v127
	v_lshl_add_u64 v[124:125], v[146:147], 1, v[124:125]
	global_store_dwordx4 v[124:125], v[120:123], off nt
.LBB0_181:
	s_or_b32 s46, s97, 0x80
	s_addk_i32 s12, 0xfa80
	s_cmpk_gt_u32 s12, 0x5ff
	v_or_b32_e32 v120, s46, v149
	s_cselect_b64 s[30:31], -1, 0
	v_cmp_lt_i32_e64 s[10:11], s68, v120
	v_or_b32_e32 v120, 0x90, v134
	s_bfe_u32 s94, s46, 0x30006
	v_bitop3_b32 v124, s46, 44, v149 bitop3:0xc8
	v_cmp_lt_i32_e64 s[4:5], s68, v120
	v_bfe_u32 v123, v120, 6, 3
	v_bitop3_b32 v122, v134, 60, v168 bitop3:0xc8
	s_mov_b64 s[12:13], -1
	s_and_b64 vcc, exec, s[30:31]
	s_cbranch_vccz .LBB0_201
	s_and_saveexec_b64 s[12:13], s[10:11]
	s_xor_b64 s[12:13], exec, s[12:13]
	s_cbranch_execz .LBB0_189
	s_mov_b64 s[34:35], -1
	s_and_b64 vcc, exec, s[0:1]
	s_cbranch_vccz .LBB0_187
	v_mul_hi_i32 v120, v175, s69
	v_lshrrev_b32_e32 v121, 31, v120
	v_ashrrev_i32_e32 v120, 12, v120
	v_add_u32_e32 v120, v120, v121
	v_mul_i32_i24_e32 v121, 0xffffdf80, v120
	v_add3_u32 v121, v121, v175, -16
	v_cmp_gt_u32_e32 vcc, s65, v121
	s_and_saveexec_b64 s[34:35], vcc
	s_cbranch_execz .LBB0_186
	v_mul_f32_e32 v127, 0xbfb8aa3b, v118
	v_mul_f32_e32 v176, 0xbfb8aa3b, v119
	v_exp_f32_e32 v127, v127
	v_exp_f32_e32 v176, v176
	v_mul_f32_e32 v125, 0xbfb8aa3b, v116
	v_mul_f32_e32 v126, 0xbfb8aa3b, v117
	v_exp_f32_e32 v125, v125
	v_exp_f32_e32 v126, v126
	v_add_f32_e32 v127, 1.0, v127
	v_add_f32_e32 v176, 1.0, v176
	v_rcp_f32_e32 v127, v127
	v_rcp_f32_e32 v176, v176
	v_lshl_add_u32 v120, v120, 13, v121
	v_add_f32_e32 v125, 1.0, v125
	v_add_f32_e32 v126, 1.0, v126
	v_ashrrev_i32_e32 v121, 31, v120
	v_rcp_f32_e32 v125, v125
	v_rcp_f32_e32 v126, v126
	v_lshlrev_b64 v[120:121], 12, v[120:121]
	v_cvt_pk_bf16_f32 v127, v127, v176
	v_lshl_add_u64 v[120:121], s[88:89], 0, v[120:121]
	v_add_u32_e32 v176, s97, v149
	v_mov_b32_e32 v177, v135
	v_lshl_add_u64 v[120:121], v[176:177], 1, v[120:121]
	v_add_co_u32_e32 v120, vcc, 0xfffff000, v120
	v_cvt_pk_bf16_f32 v126, v125, v126
	s_nop 0
	v_addc_co_u32_e32 v121, vcc, -1, v121, vcc
	global_store_dwordx2 v[120:121], v[126:127], off offset:-2304 nt

; __device__ __forceinline__ unsigned pk_bf16(float lo, float hi) { const f32x2 v = {lo, hi}; return __builtin_bit_cast(unsigned, __builtin_convertvector(v, b16x2)); }
; __device__ __forceinline__ float sigmoidf_(float x) { return __builtin_amdgcn_rcpf(1.0f + __expf(-x)); }
;     __device__ __forceinline__ void row(int r, int col32, int fq, const f32x4& a00, const f32x4& a01, const f32x4& a10, const f32x4& a11) const { half(r, col32, fq, a00, a01); half(r, col32 + HALF, fq, a10, a11); }
;     __device__ __forceinline__ void row(int r, int col32, int fq, const f32x4& a00, const f32x4& a01, const f32x4& a10, const f32x4& a11) const { half(r, col32, fq, a00, a01); half(r, col32 + HALF, fq, a10, a11); }
;     __device__ __forceinline__ void row(int r, int col32, int fq, const f32x4& a00, const f32x4& a01, const f32x4& a10, const f32x4& a11) const { half(r, col32, fq, a00, a01); half(r, col32 + HALF, fq, a10, a11); }
;     __device__ __forceinline__ void one(int row, int col, const f32x4& v) const {
;         if (col < 1536) {
;             const int which = col >> 9, hc = col & 511, h = hc >> 6, d = hc & 63, b = row / TP, t = row - b * TP;
;             const float s = which == 0 ? 0.125f : 1.0f;
;             u32x2 w; w.x = pk_bf16(v[0] * s, v[1] * s); w.y = pk_bf16(v[2] * s, v[3] * s);
;             *(u32x2*)(qkv + (size_t)which * (QKV_ONE / 2) + ((size_t)(b * NH + h) * TP + t) * 64 + d) = w;
;         } else if (col < 3328) {
;             h16x4 o; o[0] = (_Float16)v[0]; o[1] = (_Float16)v[1]; o[2] = (_Float16)v[2]; o[3] = (_Float16)v[3];
;             *(h16x4*)(urw + (size_t)row * RWS + (col - 1536)) = o;
;         } else {
;             const int b = row / TP, t = row - b * TP;
;             if (t >= NMETA && t < T) {
;                 u32x2 w; w.x = pk_bf16(sigmoidf_(v[0]), sigmoidf_(v[1])); w.y = pk_bf16(sigmoidf_(v[2]), sigmoidf_(v[3]));
;                 *(u32x2*)(gates + (size_t)(b * SEQ + t - NMETA) * 2048 + (col - 3328)) = w;
;             }
;         }
.LBB0_187:
	s_andn2_b64 vcc, exec, s[34:35]
	s_cbranch_vccnz .LBB0_189
	v_mov_b64_e32 v[126:127], s[50:51]
	v_mad_i64_i32 v[126:127], s[34:35], v175, s73, v[126:127]
	v_add_u32_e32 v176, s97, v149
	v_mov_b32_e32 v177, v135
	v_cvt_pk_f16_f32 v121, v118, v119
	v_cvt_pk_f16_f32 v120, v116, v117
	v_lshl_add_u64 v[126:127], v[176:177], 1, v[126:127]
	global_store_dwordx2 v[126:127], v[120:121], off offset:-2816 nt
.LBB0_189:
	s_or_saveexec_b64 s[12:13], s[12:13]
	v_mul_hi_i32 v121, v175, s69
	v_lshrrev_b32_e32 v120, 31, v121
	v_ashrrev_i32_e32 v121, 12, v121
	s_xor_b64 exec, exec, s[12:13]
	s_cbranch_execz .LBB0_191
	v_add_u32_e32 v125, v121, v120
	v_mad_i32_i24 v126, v125, s72, v175
	v_pk_mul_f32 v[176:177], v[144:145], v[116:117] op_sel_hi:[0,1]
	v_pk_mul_f32 v[178:179], v[144:145], v[118:119] op_sel_hi:[0,1]
	v_lshl_or_b32 v125, v125, 3, s94
	v_cvt_pk_bf16_f32 v176, v176, v177
	v_cvt_pk_bf16_f32 v177, v178, v179
	v_mul_hi_i32_i24_e32 v179, 0x2080, v125
	v_mul_i32_i24_e32 v178, 0x2080, v125
	v_ashrrev_i32_e32 v127, 31, v126
	s_add_u32 s34, s50, s77
	v_lshl_add_u64 v[126:127], v[178:179], 0, v[126:127]
	s_addc_u32 s35, s51, s25
	v_lshlrev_b64 v[126:127], 7, v[126:127]
	v_lshl_add_u64 v[126:127], s[34:35], 0, v[126:127]
	v_lshlrev_b32_e32 v178, 1, v124
	v_mov_b32_e32 v179, v135
	v_lshl_add_u64 v[126:127], v[126:127], 0, v[178:179]
	global_store_dwordx2 v[126:127], v[176:177], off nt
.LBB0_191:
	s_or_b64 exec, exec, s[12:13]
	s_and_saveexec_b64 s[12:13], s[4:5]
	s_xor_b64 s[12:13], exec, s[12:13]
	s_cbranch_execz .LBB0_198
	s_mov_b64 s[34:35], -1
	s_and_b64 vcc, exec, s[0:1]
	s_cbranch_vccz .LBB0_196
	v_add_u32_e32 v120, v121, v120
	v_mul_i32_i24_e32 v121, 0xffffdf80, v120
	v_add3_u32 v121, v121, v175, -16
	v_cmp_gt_u32_e32 vcc, s65, v121
	s_and_saveexec_b64 s[34:35], vcc
	s_cbranch_execz .LBB0_195
	v_mul_f32_e32 v125, 0xbfb8aa3b, v112
	v_mul_f32_e32 v126, 0xbfb8aa3b, v113
	v_exp_f32_e32 v125, v125
	v_exp_f32_e32 v126, v126
	v_mul_f32_e32 v127, 0xbfb8aa3b, v115
	v_exp_f32_e32 v127, v127
	v_add_f32_e32 v125, 1.0, v125
	v_add_f32_e32 v126, 1.0, v126
	v_rcp_f32_e32 v125, v125
	v_rcp_f32_e32 v126, v126
	v_lshl_add_u32 v120, v120, 13, v121
	v_add_f32_e32 v127, 1.0, v127
	v_ashrrev_i32_e32 v121, 31, v120
	v_cvt_pk_bf16_f32 v126, v125, v126
	v_mul_f32_e32 v125, 0xbfb8aa3b, v114
	v_exp_f32_e32 v125, v125
	v_rcp_f32_e32 v127, v127
	v_lshlrev_b64 v[120:121], 12, v[120:121]
	v_lshl_add_u64 v[120:121], s[88:89], 0, v[120:121]
	v_add_f32_e32 v125, 1.0, v125
	v_rcp_f32_e32 v125, v125
	v_lshl_add_u64 v[120:121], v[134:135], 1, v[120:121]
	v_add_co_u32_e32 v120, vcc, 0xfffff000, v120
	v_cvt_pk_bf16_f32 v127, v125, v127
	s_nop 0
	v_addc_co_u32_e32 v121, vcc, -1, v121, vcc
	global_store_dwordx2 v[120:121], v[126:127], off offset:-2272 nt

; __device__ __forceinline__ unsigned pk_bf16(float lo, float hi) { const f32x2 v = {lo, hi}; return __builtin_bit_cast(unsigned, __builtin_convertvector(v, b16x2)); }
;     __device__ __forceinline__ void row(int r, int col32, int fq, const f32x4& a00, const f32x4& a01, const f32x4& a10, const f32x4& a11) const { half(r, col32, fq, a00, a01); half(r, col32 + HALF, fq, a10, a11); }
;     __device__ __forceinline__ void row(int r, int col32, int fq, const f32x4& a00, const f32x4& a01, const f32x4& a10, const f32x4& a11) const { half(r, col32, fq, a00, a01); half(r, col32 + HALF, fq, a10, a11); }
;     __device__ __forceinline__ void row(int r, int col32, int fq, const f32x4& a00, const f32x4& a01, const f32x4& a10, const f32x4& a11) const { half(r, col32, fq, a00, a01); half(r, col32 + HALF, fq, a10, a11); }
;     __device__ __forceinline__ void one(int row, int col, const f32x4& v) const {
;         if (col < 1536) {
;             const int which = col >> 9, hc = col & 511, h = hc >> 6, d = hc & 63, b = row / TP, t = row - b * TP;
;             const float s = which == 0 ? 0.125f : 1.0f;
;             u32x2 w; w.x = pk_bf16(v[0] * s, v[1] * s); w.y = pk_bf16(v[2] * s, v[3] * s);
;             *(u32x2*)(qkv + (size_t)which * (QKV_ONE / 2) + ((size_t)(b * NH + h) * TP + t) * 64 + d) = w;
;         } else if (col < 3328) {
;             h16x4 o; o[0] = (_Float16)v[0]; o[1] = (_Float16)v[1]; o[2] = (_Float16)v[2]; o[3] = (_Float16)v[3];
;             *(h16x4*)(urw + (size_t)row * RWS + (col - 1536)) = o;
.LBB0_196:
	s_andn2_b64 vcc, exec, s[34:35]
	s_cbranch_vccnz .LBB0_198
	v_mov_b64_e32 v[126:127], s[50:51]
	v_mad_i64_i32 v[126:127], s[34:35], v175, s73, v[126:127]
	v_cvt_pk_f16_f32 v121, v114, v115
	v_cvt_pk_f16_f32 v120, v112, v113
	v_lshl_add_u64 v[126:127], v[134:135], 1, v[126:127]
	global_store_dwordx2 v[126:127], v[120:121], off offset:-2784 nt
.LBB0_198:
	s_andn2_saveexec_b64 s[12:13], s[12:13]
	s_cbranch_execz .LBB0_200
	v_add_u32_e32 v121, v121, v120
	v_mad_i32_i24 v120, v121, s72, v175
	v_pk_mul_f32 v[126:127], v[144:145], v[112:113] op_sel_hi:[0,1]
	v_pk_mul_f32 v[176:177], v[144:145], v[114:115] op_sel_hi:[0,1]
	v_lshl_or_b32 v121, v121, 3, v123
	v_cvt_pk_bf16_f32 v126, v126, v127
	v_cvt_pk_bf16_f32 v127, v176, v177
	v_mul_hi_i32_i24_e32 v177, 0x2080, v121
	v_mul_i32_i24_e32 v176, 0x2080, v121
	v_ashrrev_i32_e32 v121, 31, v120
	s_add_u32 s34, s50, s77
	v_lshl_add_u64 v[120:121], v[176:177], 0, v[120:121]
	s_addc_u32 s35, s51, s25
	v_lshlrev_b64 v[120:121], 7, v[120:121]
	v_lshl_add_u64 v[120:121], s[34:35], 0, v[120:121]
	v_lshlrev_b32_e32 v176, 1, v122
	v_mov_b32_e32 v177, v135
	v_lshl_add_u64 v[120:121], v[120:121], 0, v[176:177]
	global_store_dwordx2 v[120:121], v[126:127], off nt

; __device__ __forceinline__ unsigned pk_bf16(float lo, float hi) { const f32x2 v = {lo, hi}; return __builtin_bit_cast(unsigned, __builtin_convertvector(v, b16x2)); }
; __device__ __forceinline__ float sigmoidf_(float x) { return __builtin_amdgcn_rcpf(1.0f + __expf(-x)); }
;     __device__ __forceinline__ void row(int r, int col32, int fq, const f32x4& a00, const f32x4& a01, const f32x4& a10, const f32x4& a11) const { half(r, col32, fq, a00, a01); half(r, col32 + HALF, fq, a10, a11); }
;     __device__ __forceinline__ void row(int r, int col32, int fq, const f32x4& a00, const f32x4& a01, const f32x4& a10, const f32x4& a11) const { half(r, col32, fq, a00, a01); half(r, col32 + HALF, fq, a10, a11); }
;     __device__ __forceinline__ void row(int r, int col32, int fq, const f32x4& a00, const f32x4& a01, const f32x4& a10, const f32x4& a11) const { half(r, col32, fq, a00, a01); half(r, col32 + HALF, fq, a10, a11); }
;     __device__ __forceinline__ void one(int row, int col, const f32x4& v) const {
;     ...
;         } else {
;             const int b = row / TP, t = row - b * TP;
;             if (t >= NMETA && t < T) {
;                 u32x2 w; w.x = pk_bf16(sigmoidf_(v[0]), sigmoidf_(v[1])); w.y = pk_bf16(sigmoidf_(v[2]), sigmoidf_(v[3]));
;                 *(u32x2*)(gates + (size_t)(b * SEQ + t - NMETA) * 2048 + (col - 3328)) = w;
;             }
;     __device__ __forceinline__ void half(int row, int col32, int fq, const f32x4& v0, const f32x4& v1) const {
;     ...
;             if (col32 >= 1536 && col32 < 3072) {
;                 const int c = col32 - 1536, pos = (c & ~63) + fq * 16 + ((c & 63) >> 4) * 4;
;                 h16x8 o;
; #pragma unroll
;                 for (int j = 0; j < 4; ++j) { o[j] = (_Float16)v0[j]; o[4 + j] = (_Float16)v1[j]; }
;                 *(h16x8*)(urw + (size_t)row * RWS + pos) = o;
;             } else { one(row, col32 + 4 * fq, v0); one(row, col32 + 16 + 4 * fq, v1); }
.LBB0_201:
	s_and_b32 s34, s46, 0xfc0
	v_add_u32_e32 v120, s34, v150
	v_mov_b32_e32 v121, v135
	s_and_b64 vcc, exec, s[12:13]
	s_cbranch_vccz .LBB0_203
	v_cvt_pk_f16_f32 v115, v114, v115
	v_cvt_pk_f16_f32 v114, v112, v113
	v_cvt_pk_f16_f32 v112, v116, v117
	v_mov_b64_e32 v[116:117], s[50:51]
	v_mad_i64_i32 v[116:117], s[12:13], v175, s73, v[116:117]
	v_cvt_pk_f16_f32 v113, v118, v119
	v_lshl_add_u64 v[116:117], v[120:121], 1, v[116:117]
	global_store_dwordx4 v[116:117], v[112:115], off nt
.LBB0_203:
	s_nop 1
	v_cndmask_b32_e64 v113, 0, 1, s[14:15]
	v_or_b32_e32 v112, 16, v175
	v_cmp_ne_u32_e64 s[12:13], 1, v113
	s_andn2_b64 vcc, exec, s[14:15]
	s_mov_b64 s[14:15], -1
	s_cbranch_vccnz .LBB0_223
	s_and_saveexec_b64 s[14:15], s[8:9]
	s_xor_b64 s[14:15], exec, s[14:15]
	s_cbranch_execz .LBB0_211
	s_andn2_b64 vcc, exec, s[0:1]
	s_mov_b64 s[34:35], -1
	s_cbranch_vccnz .LBB0_209
	v_mul_hi_i32 v113, v112, s69
	v_lshrrev_b32_e32 v114, 31, v113
	v_ashrrev_i32_e32 v113, 12, v113
	v_add_u32_e32 v113, v113, v114
	v_mul_i32_i24_e32 v114, 0xffffdf80, v113
	v_add3_u32 v114, v114, v112, -16
	v_cmp_gt_u32_e32 vcc, s65, v114
	s_and_saveexec_b64 s[34:35], vcc
	s_cbranch_execz .LBB0_208
	v_mul_f32_e32 v115, 0xbfb8aa3b, v108
	v_mul_f32_e32 v116, 0xbfb8aa3b, v109
	v_exp_f32_e32 v115, v115
	v_exp_f32_e32 v116, v116
	v_mul_f32_e32 v117, 0xbfb8aa3b, v111
	v_exp_f32_e32 v117, v117
	v_add_f32_e32 v115, 1.0, v115
	v_add_f32_e32 v116, 1.0, v116
	v_rcp_f32_e32 v115, v115
	v_rcp_f32_e32 v116, v116
	v_add_f32_e32 v117, 1.0, v117
	v_rcp_f32_e32 v117, v117
	v_lshl_add_u32 v114, v113, 13, v114
	v_cvt_pk_bf16_f32 v116, v115, v116
	v_mul_f32_e32 v115, 0xbfb8aa3b, v110
	v_exp_f32_e32 v115, v115
	s_nop 0
	v_add_f32_e32 v115, 1.0, v115
	v_rcp_f32_e32 v115, v115
	s_nop 0
	v_cvt_pk_bf16_f32 v117, v115, v117
	v_ashrrev_i32_e32 v115, 31, v114
	v_lshlrev_b64 v[114:115], 12, v[114:115]
	v_lshl_add_u64 v[114:115], s[88:89], 0, v[114:115]
	v_lshl_add_u64 v[114:115], v[134:135], 1, v[114:115]
	v_add_co_u32_e32 v114, vcc, 0xfffff000, v114
	s_nop 1
	v_addc_co_u32_e32 v115, vcc, -1, v115, vcc
	global_store_dwordx2 v[114:115], v[116:117], off offset:-2560 nt

; __device__ __forceinline__ unsigned pk_bf16(float lo, float hi) { const f32x2 v = {lo, hi}; return __builtin_bit_cast(unsigned, __builtin_convertvector(v, b16x2)); }
; __device__ __forceinline__ float sigmoidf_(float x) { return __builtin_amdgcn_rcpf(1.0f + __expf(-x)); }
;     __device__ __forceinline__ void row(int r, int col32, int fq, const f32x4& a00, const f32x4& a01, const f32x4& a10, const f32x4& a11) const { half(r, col32, fq, a00, a01); half(r, col32 + HALF, fq, a10, a11); }
;     __device__ __forceinline__ void row(int r, int col32, int fq, const f32x4& a00, const f32x4& a01, const f32x4& a10, const f32x4& a11) const { half(r, col32, fq, a00, a01); half(r, col32 + HALF, fq, a10, a11); }
;     __device__ __forceinline__ void row(int r, int col32, int fq, const f32x4& a00, const f32x4& a01, const f32x4& a10, const f32x4& a11) const { half(r, col32, fq, a00, a01); half(r, col32 + HALF, fq, a10, a11); }
;     __device__ __forceinline__ void one(int row, int col, const f32x4& v) const {
;         if (col < 1536) {
;             const int which = col >> 9, hc = col & 511, h = hc >> 6, d = hc & 63, b = row / TP, t = row - b * TP;
;             const float s = which == 0 ? 0.125f : 1.0f;
;             u32x2 w; w.x = pk_bf16(v[0] * s, v[1] * s); w.y = pk_bf16(v[2] * s, v[3] * s);
;             *(u32x2*)(qkv + (size_t)which * (QKV_ONE / 2) + ((size_t)(b * NH + h) * TP + t) * 64 + d) = w;
;         } else if (col < 3328) {
;             h16x4 o; o[0] = (_Float16)v[0]; o[1] = (_Float16)v[1]; o[2] = (_Float16)v[2]; o[3] = (_Float16)v[3];
;             *(h16x4*)(urw + (size_t)row * RWS + (col - 1536)) = o;
;         } else {
;             const int b = row / TP, t = row - b * TP;
;             if (t >= NMETA && t < T) {
;                 u32x2 w; w.x = pk_bf16(sigmoidf_(v[0]), sigmoidf_(v[1])); w.y = pk_bf16(sigmoidf_(v[2]), sigmoidf_(v[3]));
;                 *(u32x2*)(gates + (size_t)(b * SEQ + t - NMETA) * 2048 + (col - 3328)) = w;
;             }
;         }
.LBB0_209:
	s_andn2_b64 vcc, exec, s[34:35]
	s_cbranch_vccnz .LBB0_211
	v_mov_b64_e32 v[116:117], s[50:51]
	v_mad_i64_i32 v[116:117], s[34:35], v112, s73, v[116:117]
	v_cvt_pk_f16_f32 v115, v110, v111
	v_cvt_pk_f16_f32 v114, v108, v109
	v_lshl_add_u64 v[116:117], v[134:135], 1, v[116:117]
	global_store_dwordx2 v[116:117], v[114:115], off offset:-3072 nt
.LBB0_211:
	s_andn2_saveexec_b64 s[14:15], s[14:15]
	s_cbranch_execz .LBB0_213
	v_mul_hi_i32 v113, v112, s69
	v_lshrrev_b32_e32 v114, 31, v113
	v_ashrrev_i32_e32 v113, 12, v113
	v_add_u32_e32 v113, v113, v114
	v_mad_i32_i24 v114, v113, s72, v112
	v_pk_mul_f32 v[116:117], v[144:145], v[108:109] op_sel_hi:[0,1]
	v_pk_mul_f32 v[118:119], v[144:145], v[110:111] op_sel_hi:[0,1]
	v_lshl_or_b32 v113, v113, 3, s96
	v_cvt_pk_bf16_f32 v116, v116, v117
	v_cvt_pk_bf16_f32 v117, v118, v119
	v_mul_hi_i32_i24_e32 v119, 0x2080, v113
	v_mul_i32_i24_e32 v118, 0x2080, v113
	v_ashrrev_i32_e32 v115, 31, v114
	s_add_u32 s34, s50, s77
	v_lshl_add_u64 v[114:115], v[118:119], 0, v[114:115]
	s_addc_u32 s35, s51, s25
	v_lshlrev_b64 v[114:115], 7, v[114:115]
	v_lshl_add_u64 v[114:115], s[34:35], 0, v[114:115]
	v_lshlrev_b32_e32 v118, 1, v174
	v_mov_b32_e32 v119, v135
	v_lshl_add_u64 v[114:115], v[114:115], 0, v[118:119]
	global_store_dwordx2 v[114:115], v[116:117], off nt
.LBB0_213:
	s_or_b64 exec, exec, s[14:15]
	s_and_saveexec_b64 s[14:15], s[6:7]
	s_xor_b64 s[14:15], exec, s[14:15]
	s_cbranch_execz .LBB0_220
	s_andn2_b64 vcc, exec, s[0:1]
	s_mov_b64 s[34:35], -1
	s_cbranch_vccnz .LBB0_218
	v_mul_hi_i32 v113, v112, s69
	v_lshrrev_b32_e32 v114, 31, v113
	v_ashrrev_i32_e32 v113, 12, v113
	v_add_u32_e32 v113, v113, v114
	v_mul_i32_i24_e32 v114, 0xffffdf80, v113
	v_add3_u32 v114, v114, v112, -16
	v_cmp_gt_u32_e32 vcc, s65, v114
	s_and_saveexec_b64 s[34:35], vcc
	s_cbranch_execz .LBB0_217
	v_mul_f32_e32 v115, 0xbfb8aa3b, v104
	v_mul_f32_e32 v116, 0xbfb8aa3b, v105
	v_exp_f32_e32 v115, v115
	v_exp_f32_e32 v116, v116
	v_mul_f32_e32 v117, 0xbfb8aa3b, v107
	v_exp_f32_e32 v117, v117
	v_add_f32_e32 v115, 1.0, v115
	v_add_f32_e32 v116, 1.0, v116
	v_rcp_f32_e32 v115, v115
	v_rcp_f32_e32 v116, v116
	v_add_f32_e32 v117, 1.0, v117
	v_rcp_f32_e32 v117, v117
	v_lshl_add_u32 v114, v113, 13, v114
	v_cvt_pk_bf16_f32 v116, v115, v116
	v_mul_f32_e32 v115, 0xbfb8aa3b, v106
	v_exp_f32_e32 v115, v115
	s_nop 0
	v_add_f32_e32 v115, 1.0, v115
	v_rcp_f32_e32 v115, v115
	s_nop 0
	v_cvt_pk_bf16_f32 v117, v115, v117
	v_ashrrev_i32_e32 v115, 31, v114
	v_lshlrev_b64 v[114:115], 12, v[114:115]
	v_lshl_add_u64 v[114:115], s[88:89], 0, v[114:115]
	v_lshl_add_u64 v[114:115], v[134:135], 1, v[114:115]
	v_add_co_u32_e32 v114, vcc, 0xfffff000, v114
	s_nop 1
	v_addc_co_u32_e32 v115, vcc, -1, v115, vcc
	global_store_dwordx2 v[114:115], v[116:117], off offset:-2528 nt

; __device__ __forceinline__ unsigned pk_bf16(float lo, float hi) { const f32x2 v = {lo, hi}; return __builtin_bit_cast(unsigned, __builtin_convertvector(v, b16x2)); }
;     __device__ __forceinline__ void row(int r, int col32, int fq, const f32x4& a00, const f32x4& a01, const f32x4& a10, const f32x4& a11) const { half(r, col32, fq, a00, a01); half(r, col32 + HALF, fq, a10, a11); }
;     __device__ __forceinline__ void row(int r, int col32, int fq, const f32x4& a00, const f32x4& a01, const f32x4& a10, const f32x4& a11) const { half(r, col32, fq, a00, a01); half(r, col32 + HALF, fq, a10, a11); }
;     __device__ __forceinline__ void row(int r, int col32, int fq, const f32x4& a00, const f32x4& a01, const f32x4& a10, const f32x4& a11) const { half(r, col32, fq, a00, a01); half(r, col32 + HALF, fq, a10, a11); }
;     __device__ __forceinline__ void one(int row, int col, const f32x4& v) const {
;         if (col < 1536) {
;             const int which = col >> 9, hc = col & 511, h = hc >> 6, d = hc & 63, b = row / TP, t = row - b * TP;
;             const float s = which == 0 ? 0.125f : 1.0f;
;             u32x2 w; w.x = pk_bf16(v[0] * s, v[1] * s); w.y = pk_bf16(v[2] * s, v[3] * s);
;             *(u32x2*)(qkv + (size_t)which * (QKV_ONE / 2) + ((size_t)(b * NH + h) * TP + t) * 64 + d) = w;
;         } else if (col < 3328) {
;             h16x4 o; o[0] = (_Float16)v[0]; o[1] = (_Float16)v[1]; o[2] = (_Float16)v[2]; o[3] = (_Float16)v[3];
;             *(h16x4*)(urw + (size_t)row * RWS + (col - 1536)) = o;
.LBB0_218:
	s_andn2_b64 vcc, exec, s[34:35]
	s_cbranch_vccnz .LBB0_220
	v_mov_b64_e32 v[116:117], s[50:51]
	v_mad_i64_i32 v[116:117], s[34:35], v112, s73, v[116:117]
	v_cvt_pk_f16_f32 v115, v106, v107
	v_cvt_pk_f16_f32 v114, v104, v105
	v_lshl_add_u64 v[116:117], v[134:135], 1, v[116:117]
	global_store_dwordx2 v[116:117], v[114:115], off offset:-3040 nt
.LBB0_220:
	s_andn2_saveexec_b64 s[14:15], s[14:15]
	s_cbranch_execz .LBB0_222
	v_mul_hi_i32 v113, v112, s69
	v_lshrrev_b32_e32 v114, 31, v113
	v_ashrrev_i32_e32 v113, 12, v113
	v_add_u32_e32 v113, v113, v114
	v_mad_i32_i24 v114, v113, s72, v112
	v_pk_mul_f32 v[116:117], v[144:145], v[104:105] op_sel_hi:[0,1]
	v_pk_mul_f32 v[118:119], v[144:145], v[106:107] op_sel_hi:[0,1]
	v_lshl_or_b32 v113, v113, 3, s96
	v_cvt_pk_bf16_f32 v116, v116, v117
	v_cvt_pk_bf16_f32 v117, v118, v119
	v_mul_hi_i32_i24_e32 v119, 0x2080, v113
	v_mul_i32_i24_e32 v118, 0x2080, v113
	v_ashrrev_i32_e32 v115, 31, v114
	s_add_u32 s34, s50, s77
	v_lshl_add_u64 v[114:115], v[118:119], 0, v[114:115]
	s_addc_u32 s35, s51, s25
	v_lshlrev_b64 v[114:115], 7, v[114:115]
	v_lshl_add_u64 v[114:115], s[34:35], 0, v[114:115]
	v_lshlrev_b32_e32 v118, 1, v173
	v_mov_b32_e32 v119, v135
	v_lshl_add_u64 v[114:115], v[114:115], 0, v[118:119]
	global_store_dwordx2 v[114:115], v[116:117], off nt

; __device__ __forceinline__ unsigned pk_bf16(float lo, float hi) { const f32x2 v = {lo, hi}; return __builtin_bit_cast(unsigned, __builtin_convertvector(v, b16x2)); }
; __device__ __forceinline__ float sigmoidf_(float x) { return __builtin_amdgcn_rcpf(1.0f + __expf(-x)); }
;     __device__ __forceinline__ void row(int r, int col32, int fq, const f32x4& a00, const f32x4& a01, const f32x4& a10, const f32x4& a11) const { half(r, col32, fq, a00, a01); half(r, col32 + HALF, fq, a10, a11); }
;     __device__ __forceinline__ void row(int r, int col32, int fq, const f32x4& a00, const f32x4& a01, const f32x4& a10, const f32x4& a11) const { half(r, col32, fq, a00, a01); half(r, col32 + HALF, fq, a10, a11); }
;     __device__ __forceinline__ void row(int r, int col32, int fq, const f32x4& a00, const f32x4& a01, const f32x4& a10, const f32x4& a11) const { half(r, col32, fq, a00, a01); half(r, col32 + HALF, fq, a10, a11); }
;     __device__ __forceinline__ void one(int row, int col, const f32x4& v) const {
;     ...
;         } else {
;             const int b = row / TP, t = row - b * TP;
;             if (t >= NMETA && t < T) {
;                 u32x2 w; w.x = pk_bf16(sigmoidf_(v[0]), sigmoidf_(v[1])); w.y = pk_bf16(sigmoidf_(v[2]), sigmoidf_(v[3]));
;                 *(u32x2*)(gates + (size_t)(b * SEQ + t - NMETA) * 2048 + (col - 3328)) = w;
;             }
;     __device__ __forceinline__ void half(int row, int col32, int fq, const f32x4& v0, const f32x4& v1) const {
;     ...
;             if (col32 >= 1536 && col32 < 3072) {
;                 const int c = col32 - 1536, pos = (c & ~63) + fq * 16 + ((c & 63) >> 4) * 4;
;                 h16x8 o;
; #pragma unroll
;                 for (int j = 0; j < 4; ++j) { o[j] = (_Float16)v0[j]; o[4 + j] = (_Float16)v1[j]; }
;                 *(h16x8*)(urw + (size_t)row * RWS + pos) = o;
;             } else { one(row, col32 + 4 * fq, v0); one(row, col32 + 16 + 4 * fq, v1); }
.LBB0_223:
	s_and_b64 vcc, exec, s[14:15]
	s_cbranch_vccz .LBB0_225
	v_cvt_pk_f16_f32 v107, v106, v107
	v_cvt_pk_f16_f32 v106, v104, v105
	v_cvt_pk_f16_f32 v104, v108, v109
	v_mov_b64_e32 v[108:109], s[50:51]
	v_mad_i64_i32 v[108:109], s[14:15], v112, s73, v[108:109]
	v_cvt_pk_f16_f32 v105, v110, v111
	v_lshl_add_u64 v[108:109], v[146:147], 1, v[108:109]
	global_store_dwordx4 v[108:109], v[104:107], off nt
.LBB0_225:
	s_nop 1
	v_cndmask_b32_e64 v104, 0, 1, s[30:31]
	v_cmp_ne_u32_e64 s[14:15], 1, v104
	s_andn2_b64 vcc, exec, s[30:31]
	s_mov_b64 s[30:31], -1
	s_cbranch_vccnz .LBB0_245
	s_and_saveexec_b64 s[30:31], s[10:11]
	s_xor_b64 s[30:31], exec, s[30:31]
	s_cbranch_execz .LBB0_233
	s_andn2_b64 vcc, exec, s[0:1]
	s_mov_b64 s[34:35], -1
	s_cbranch_vccnz .LBB0_231
	v_mul_hi_i32 v104, v112, s69
	v_lshrrev_b32_e32 v105, 31, v104
	v_ashrrev_i32_e32 v104, 12, v104
	v_add_u32_e32 v104, v104, v105
	v_mul_i32_i24_e32 v105, 0xffffdf80, v104
	v_add3_u32 v105, v105, v112, -16
	v_cmp_gt_u32_e32 vcc, s65, v105
	s_and_saveexec_b64 s[34:35], vcc
	s_cbranch_execz .LBB0_230
	v_mul_f32_e32 v106, 0xbfb8aa3b, v100
	v_mul_f32_e32 v107, 0xbfb8aa3b, v101
	v_mul_f32_e32 v108, 0xbfb8aa3b, v102
	v_mul_f32_e32 v109, 0xbfb8aa3b, v103
	v_exp_f32_e32 v106, v106
	v_exp_f32_e32 v107, v107
	v_exp_f32_e32 v108, v108
	v_exp_f32_e32 v109, v109
	v_add_f32_e32 v106, 1.0, v106
	v_add_f32_e32 v107, 1.0, v107
	v_add_f32_e32 v108, 1.0, v108
	v_add_f32_e32 v109, 1.0, v109
	v_rcp_f32_e32 v106, v106
	v_rcp_f32_e32 v107, v107
	v_rcp_f32_e32 v108, v108
	v_rcp_f32_e32 v109, v109
	v_lshl_add_u32 v104, v104, 13, v105
	v_ashrrev_i32_e32 v105, 31, v104
	v_lshlrev_b64 v[104:105], 12, v[104:105]
	v_cvt_pk_bf16_f32 v106, v106, v107
	v_cvt_pk_bf16_f32 v107, v108, v109
	v_lshl_add_u64 v[104:105], s[88:89], 0, v[104:105]
	v_add_u32_e32 v108, s97, v149
	v_mov_b32_e32 v109, v135
	v_lshl_add_u64 v[104:105], v[108:109], 1, v[104:105]
	v_add_co_u32_e32 v104, vcc, 0xfffff000, v104
	s_nop 1
	v_addc_co_u32_e32 v105, vcc, -1, v105, vcc
	global_store_dwordx2 v[104:105], v[106:107], off offset:-2304 nt

; __device__ __forceinline__ unsigned pk_bf16(float lo, float hi) { const f32x2 v = {lo, hi}; return __builtin_bit_cast(unsigned, __builtin_convertvector(v, b16x2)); }
; __device__ __forceinline__ float sigmoidf_(float x) { return __builtin_amdgcn_rcpf(1.0f + __expf(-x)); }
;     __device__ __forceinline__ void row(int r, int col32, int fq, const f32x4& a00, const f32x4& a01, const f32x4& a10, const f32x4& a11) const { half(r, col32, fq, a00, a01); half(r, col32 + HALF, fq, a10, a11); }
;     __device__ __forceinline__ void row(int r, int col32, int fq, const f32x4& a00, const f32x4& a01, const f32x4& a10, const f32x4& a11) const { half(r, col32, fq, a00, a01); half(r, col32 + HALF, fq, a10, a11); }
;     __device__ __forceinline__ void row(int r, int col32, int fq, const f32x4& a00, const f32x4& a01, const f32x4& a10, const f32x4& a11) const { half(r, col32, fq, a00, a01); half(r, col32 + HALF, fq, a10, a11); }
;     __device__ __forceinline__ void one(int row, int col, const f32x4& v) const {
;         if (col < 1536) {
;             const int which = col >> 9, hc = col & 511, h = hc >> 6, d = hc & 63, b = row / TP, t = row - b * TP;
;             const float s = which == 0 ? 0.125f : 1.0f;
;             u32x2 w; w.x = pk_bf16(v[0] * s, v[1] * s); w.y = pk_bf16(v[2] * s, v[3] * s);
;             *(u32x2*)(qkv + (size_t)which * (QKV_ONE / 2) + ((size_t)(b * NH + h) * TP + t) * 64 + d) = w;
;         } else if (col < 3328) {
;             h16x4 o; o[0] = (_Float16)v[0]; o[1] = (_Float16)v[1]; o[2] = (_Float16)v[2]; o[3] = (_Float16)v[3];
;             *(h16x4*)(urw + (size_t)row * RWS + (col - 1536)) = o;
;         } else {
;             const int b = row / TP, t = row - b * TP;
;             if (t >= NMETA && t < T) {
;                 u32x2 w; w.x = pk_bf16(sigmoidf_(v[0]), sigmoidf_(v[1])); w.y = pk_bf16(sigmoidf_(v[2]), sigmoidf_(v[3]));
;                 *(u32x2*)(gates + (size_t)(b * SEQ + t - NMETA) * 2048 + (col - 3328)) = w;
;             }
;         }
.LBB0_231:
	s_andn2_b64 vcc, exec, s[34:35]
	s_cbranch_vccnz .LBB0_233
	v_mov_b64_e32 v[106:107], s[50:51]
	v_mad_i64_i32 v[106:107], s[34:35], v112, s73, v[106:107]
	v_add_u32_e32 v108, s97, v149
	v_mov_b32_e32 v109, v135
	v_cvt_pk_f16_f32 v105, v102, v103
	v_cvt_pk_f16_f32 v104, v100, v101
	v_lshl_add_u64 v[106:107], v[108:109], 1, v[106:107]
	global_store_dwordx2 v[106:107], v[104:105], off offset:-2816 nt
.LBB0_233:
	s_or_saveexec_b64 s[30:31], s[30:31]
	v_mul_hi_i32 v105, v112, s69
	v_lshrrev_b32_e32 v104, 31, v105
	v_ashrrev_i32_e32 v105, 12, v105
	s_xor_b64 exec, exec, s[30:31]
	s_cbranch_execz .LBB0_235
	v_add_u32_e32 v107, v105, v104
	v_mad_i32_i24 v106, v107, s72, v112
	v_pk_mul_f32 v[108:109], v[144:145], v[100:101] op_sel_hi:[0,1]
	v_pk_mul_f32 v[110:111], v[144:145], v[102:103] op_sel_hi:[0,1]
	v_lshl_or_b32 v107, v107, 3, s94
	v_cvt_pk_bf16_f32 v108, v108, v109
	v_cvt_pk_bf16_f32 v109, v110, v111
	v_mul_hi_i32_i24_e32 v111, 0x2080, v107
	v_mul_i32_i24_e32 v110, 0x2080, v107
	v_ashrrev_i32_e32 v107, 31, v106
	s_add_u32 s34, s50, s77
	v_lshl_add_u64 v[106:107], v[110:111], 0, v[106:107]
	s_addc_u32 s35, s51, s25
	v_lshlrev_b64 v[106:107], 7, v[106:107]
	v_lshl_add_u64 v[106:107], s[34:35], 0, v[106:107]
	v_lshlrev_b32_e32 v110, 1, v124
	v_mov_b32_e32 v111, v135
	v_lshl_add_u64 v[106:107], v[106:107], 0, v[110:111]
	global_store_dwordx2 v[106:107], v[108:109], off nt
.LBB0_235:
	s_or_b64 exec, exec, s[30:31]
	s_and_saveexec_b64 s[30:31], s[4:5]
	s_xor_b64 s[30:31], exec, s[30:31]
	s_cbranch_execz .LBB0_242
	s_andn2_b64 vcc, exec, s[0:1]
	s_mov_b64 s[34:35], -1
	s_cbranch_vccnz .LBB0_240
	v_add_u32_e32 v104, v105, v104
	v_mul_i32_i24_e32 v105, 0xffffdf80, v104
	v_add3_u32 v105, v105, v112, -16
	v_cmp_gt_u32_e32 vcc, s65, v105
	s_and_saveexec_b64 s[34:35], vcc
	s_cbranch_execz .LBB0_239
	v_mul_f32_e32 v106, 0xbfb8aa3b, v96
	v_mul_f32_e32 v107, 0xbfb8aa3b, v97
	v_exp_f32_e32 v106, v106
	v_exp_f32_e32 v107, v107
	v_mul_f32_e32 v108, 0xbfb8aa3b, v99
	v_exp_f32_e32 v108, v108
	v_add_f32_e32 v106, 1.0, v106
	v_add_f32_e32 v107, 1.0, v107
	v_rcp_f32_e32 v106, v106
	v_rcp_f32_e32 v107, v107
	v_lshl_add_u32 v104, v104, 13, v105
	v_add_f32_e32 v108, 1.0, v108
	v_ashrrev_i32_e32 v105, 31, v104
	v_cvt_pk_bf16_f32 v106, v106, v107
	v_mul_f32_e32 v107, 0xbfb8aa3b, v98
	v_exp_f32_e32 v107, v107
	v_rcp_f32_e32 v108, v108
	v_lshlrev_b64 v[104:105], 12, v[104:105]
	v_lshl_add_u64 v[104:105], s[88:89], 0, v[104:105]
	v_add_f32_e32 v107, 1.0, v107
	v_rcp_f32_e32 v107, v107
	v_lshl_add_u64 v[104:105], v[134:135], 1, v[104:105]
	v_add_co_u32_e32 v104, vcc, 0xfffff000, v104
	v_cvt_pk_bf16_f32 v107, v107, v108
	s_nop 0
	v_addc_co_u32_e32 v105, vcc, -1, v105, vcc
	global_store_dwordx2 v[104:105], v[106:107], off offset:-2272 nt

; __device__ __forceinline__ unsigned pk_bf16(float lo, float hi) { const f32x2 v = {lo, hi}; return __builtin_bit_cast(unsigned, __builtin_convertvector(v, b16x2)); }
;     __device__ __forceinline__ void row(int r, int col32, int fq, const f32x4& a00, const f32x4& a01, const f32x4& a10, const f32x4& a11) const { half(r, col32, fq, a00, a01); half(r, col32 + HALF, fq, a10, a11); }
;     __device__ __forceinline__ void row(int r, int col32, int fq, const f32x4& a00, const f32x4& a01, const f32x4& a10, const f32x4& a11) const { half(r, col32, fq, a00, a01); half(r, col32 + HALF, fq, a10, a11); }
;     __device__ __forceinline__ void row(int r, int col32, int fq, const f32x4& a00, const f32x4& a01, const f32x4& a10, const f32x4& a11) const { half(r, col32, fq, a00, a01); half(r, col32 + HALF, fq, a10, a11); }
;     __device__ __forceinline__ void one(int row, int col, const f32x4& v) const {
;         if (col < 1536) {
;             const int which = col >> 9, hc = col & 511, h = hc >> 6, d = hc & 63, b = row / TP, t = row - b * TP;
;             const float s = which == 0 ? 0.125f : 1.0f;
;             u32x2 w; w.x = pk_bf16(v[0] * s, v[1] * s); w.y = pk_bf16(v[2] * s, v[3] * s);
;             *(u32x2*)(qkv + (size_t)which * (QKV_ONE / 2) + ((size_t)(b * NH + h) * TP + t) * 64 + d) = w;
;         } else if (col < 3328) {
;             h16x4 o; o[0] = (_Float16)v[0]; o[1] = (_Float16)v[1]; o[2] = (_Float16)v[2]; o[3] = (_Float16)v[3];
;             *(h16x4*)(urw + (size_t)row * RWS + (col - 1536)) = o;
.LBB0_240:
	s_andn2_b64 vcc, exec, s[34:35]
	s_cbranch_vccnz .LBB0_242
	v_mov_b64_e32 v[106:107], s[50:51]
	v_mad_i64_i32 v[106:107], s[34:35], v112, s73, v[106:107]
	v_cvt_pk_f16_f32 v105, v98, v99
	v_cvt_pk_f16_f32 v104, v96, v97
	v_lshl_add_u64 v[106:107], v[134:135], 1, v[106:107]
	global_store_dwordx2 v[106:107], v[104:105], off offset:-2784 nt
.LBB0_242:
	s_andn2_saveexec_b64 s[30:31], s[30:31]
	s_cbranch_execz .LBB0_244
	v_add_u32_e32 v105, v105, v104
	v_mad_i32_i24 v104, v105, s72, v112
	v_pk_mul_f32 v[106:107], v[144:145], v[96:97] op_sel_hi:[0,1]
	v_pk_mul_f32 v[108:109], v[144:145], v[98:99] op_sel_hi:[0,1]
	v_lshl_or_b32 v105, v105, 3, v123
	v_cvt_pk_bf16_f32 v106, v106, v107
	v_cvt_pk_bf16_f32 v107, v108, v109
	v_mul_hi_i32_i24_e32 v109, 0x2080, v105
	v_mul_i32_i24_e32 v108, 0x2080, v105
	v_ashrrev_i32_e32 v105, 31, v104
	s_add_u32 s34, s50, s77
	v_lshl_add_u64 v[104:105], v[108:109], 0, v[104:105]
	s_addc_u32 s35, s51, s25
	v_lshlrev_b64 v[104:105], 7, v[104:105]
	v_lshl_add_u64 v[104:105], s[34:35], 0, v[104:105]
	v_lshlrev_b32_e32 v108, 1, v122
	v_mov_b32_e32 v109, v135
	v_lshl_add_u64 v[104:105], v[104:105], 0, v[108:109]
	global_store_dwordx2 v[104:105], v[106:107], off nt

; __device__ __forceinline__ unsigned pk_bf16(float lo, float hi) { const f32x2 v = {lo, hi}; return __builtin_bit_cast(unsigned, __builtin_convertvector(v, b16x2)); }
; __device__ __forceinline__ float sigmoidf_(float x) { return __builtin_amdgcn_rcpf(1.0f + __expf(-x)); }
;     __device__ __forceinline__ void row(int r, int col32, int fq, const f32x4& a00, const f32x4& a01, const f32x4& a10, const f32x4& a11) const { half(r, col32, fq, a00, a01); half(r, col32 + HALF, fq, a10, a11); }
;     __device__ __forceinline__ void row(int r, int col32, int fq, const f32x4& a00, const f32x4& a01, const f32x4& a10, const f32x4& a11) const { half(r, col32, fq, a00, a01); half(r, col32 + HALF, fq, a10, a11); }
;     __device__ __forceinline__ void row(int r, int col32, int fq, const f32x4& a00, const f32x4& a01, const f32x4& a10, const f32x4& a11) const { half(r, col32, fq, a00, a01); half(r, col32 + HALF, fq, a10, a11); }
;     __device__ __forceinline__ void one(int row, int col, const f32x4& v) const {
;     ...
;         } else {
;             const int b = row / TP, t = row - b * TP;
;             if (t >= NMETA && t < T) {
;                 u32x2 w; w.x = pk_bf16(sigmoidf_(v[0]), sigmoidf_(v[1])); w.y = pk_bf16(sigmoidf_(v[2]), sigmoidf_(v[3]));
;                 *(u32x2*)(gates + (size_t)(b * SEQ + t - NMETA) * 2048 + (col - 3328)) = w;
;             }
;     __device__ __forceinline__ void half(int row, int col32, int fq, const f32x4& v0, const f32x4& v1) const {
;     ...
;             if (col32 >= 1536 && col32 < 3072) {
;                 const int c = col32 - 1536, pos = (c & ~63) + fq * 16 + ((c & 63) >> 4) * 4;
;                 h16x8 o;
; #pragma unroll
;                 for (int j = 0; j < 4; ++j) { o[j] = (_Float16)v0[j]; o[4 + j] = (_Float16)v1[j]; }
;                 *(h16x8*)(urw + (size_t)row * RWS + pos) = o;
;             } else { one(row, col32 + 4 * fq, v0); one(row, col32 + 16 + 4 * fq, v1); }
.LBB0_245:
	s_and_b64 vcc, exec, s[30:31]
	s_cbranch_vccz .LBB0_247
	v_cvt_pk_f16_f32 v99, v98, v99
	v_cvt_pk_f16_f32 v98, v96, v97
	v_cvt_pk_f16_f32 v96, v100, v101
	v_mov_b64_e32 v[100:101], s[50:51]
	v_mad_i64_i32 v[100:101], s[30:31], v112, s73, v[100:101]
	v_cvt_pk_f16_f32 v97, v102, v103
	v_lshl_add_u64 v[100:101], v[120:121], 1, v[100:101]
	global_store_dwordx4 v[100:101], v[96:99], off nt
.LBB0_247:
	s_nop 1
	v_or_b32_e32 v96, 32, v175
	s_and_b64 vcc, exec, s[12:13]
	s_mov_b64 s[30:31], -1
	s_cbranch_vccnz .LBB0_287
	s_and_saveexec_b64 s[30:31], s[8:9]
	s_xor_b64 s[30:31], exec, s[30:31]
	s_cbranch_execz .LBB0_255
	s_andn2_b64 vcc, exec, s[0:1]
	s_mov_b64 s[34:35], -1
	s_cbranch_vccnz .LBB0_253
	v_mul_hi_i32 v97, v96, s69
	v_lshrrev_b32_e32 v98, 31, v97
	v_ashrrev_i32_e32 v97, 12, v97
	v_add_u32_e32 v97, v97, v98
	v_mul_i32_i24_e32 v98, 0xffffdf80, v97
	v_add3_u32 v98, v98, v96, -16
	v_cmp_gt_u32_e32 vcc, s65, v98
	s_and_saveexec_b64 s[34:35], vcc
	s_cbranch_execz .LBB0_252
	v_mul_f32_e32 v99, 0xbfb8aa3b, v92
	v_mul_f32_e32 v100, 0xbfb8aa3b, v93
	v_exp_f32_e32 v99, v99
	v_exp_f32_e32 v100, v100
	v_mul_f32_e32 v101, 0xbfb8aa3b, v95
	v_exp_f32_e32 v101, v101
	v_add_f32_e32 v99, 1.0, v99
	v_add_f32_e32 v100, 1.0, v100
	v_rcp_f32_e32 v99, v99
	v_rcp_f32_e32 v100, v100
	v_add_f32_e32 v101, 1.0, v101
	v_rcp_f32_e32 v101, v101
	v_lshl_add_u32 v98, v97, 13, v98
	v_cvt_pk_bf16_f32 v100, v99, v100
	v_mul_f32_e32 v99, 0xbfb8aa3b, v94
	v_exp_f32_e32 v99, v99
	s_nop 0
	v_add_f32_e32 v99, 1.0, v99
	v_rcp_f32_e32 v99, v99
	s_nop 0
	v_cvt_pk_bf16_f32 v101, v99, v101
	v_ashrrev_i32_e32 v99, 31, v98
	v_lshlrev_b64 v[98:99], 12, v[98:99]
	v_lshl_add_u64 v[98:99], s[88:89], 0, v[98:99]
	v_lshl_add_u64 v[98:99], v[134:135], 1, v[98:99]
	v_add_co_u32_e32 v98, vcc, 0xfffff000, v98
	s_nop 1
	v_addc_co_u32_e32 v99, vcc, -1, v99, vcc
	global_store_dwordx2 v[98:99], v[100:101], off offset:-2560 nt

; __device__ __forceinline__ unsigned pk_bf16(float lo, float hi) { const f32x2 v = {lo, hi}; return __builtin_bit_cast(unsigned, __builtin_convertvector(v, b16x2)); }
; __device__ __forceinline__ float sigmoidf_(float x) { return __builtin_amdgcn_rcpf(1.0f + __expf(-x)); }
;     __device__ __forceinline__ void row(int r, int col32, int fq, const f32x4& a00, const f32x4& a01, const f32x4& a10, const f32x4& a11) const { half(r, col32, fq, a00, a01); half(r, col32 + HALF, fq, a10, a11); }
;     __device__ __forceinline__ void row(int r, int col32, int fq, const f32x4& a00, const f32x4& a01, const f32x4& a10, const f32x4& a11) const { half(r, col32, fq, a00, a01); half(r, col32 + HALF, fq, a10, a11); }
;     __device__ __forceinline__ void row(int r, int col32, int fq, const f32x4& a00, const f32x4& a01, const f32x4& a10, const f32x4& a11) const { half(r, col32, fq, a00, a01); half(r, col32 + HALF, fq, a10, a11); }
;     __device__ __forceinline__ void one(int row, int col, const f32x4& v) const {
;         if (col < 1536) {
;             const int which = col >> 9, hc = col & 511, h = hc >> 6, d = hc & 63, b = row / TP, t = row - b * TP;
;             const float s = which == 0 ? 0.125f : 1.0f;
;             u32x2 w; w.x = pk_bf16(v[0] * s, v[1] * s); w.y = pk_bf16(v[2] * s, v[3] * s);
;             *(u32x2*)(qkv + (size_t)which * (QKV_ONE / 2) + ((size_t)(b * NH + h) * TP + t) * 64 + d) = w;
;         } else if (col < 3328) {
;             h16x4 o; o[0] = (_Float16)v[0]; o[1] = (_Float16)v[1]; o[2] = (_Float16)v[2]; o[3] = (_Float16)v[3];
;             *(h16x4*)(urw + (size_t)row * RWS + (col - 1536)) = o;
;         } else {
;             const int b = row / TP, t = row - b * TP;
;             if (t >= NMETA && t < T) {
;                 u32x2 w; w.x = pk_bf16(sigmoidf_(v[0]), sigmoidf_(v[1])); w.y = pk_bf16(sigmoidf_(v[2]), sigmoidf_(v[3]));
;                 *(u32x2*)(gates + (size_t)(b * SEQ + t - NMETA) * 2048 + (col - 3328)) = w;
;             }
;         }
.LBB0_253:
	s_andn2_b64 vcc, exec, s[34:35]
	s_cbranch_vccnz .LBB0_255
	v_mov_b64_e32 v[100:101], s[50:51]
	v_mad_i64_i32 v[100:101], s[34:35], v96, s73, v[100:101]
	v_cvt_pk_f16_f32 v99, v94, v95
	v_cvt_pk_f16_f32 v98, v92, v93
	v_lshl_add_u64 v[100:101], v[134:135], 1, v[100:101]
	global_store_dwordx2 v[100:101], v[98:99], off offset:-3072 nt
.LBB0_255:
	s_andn2_saveexec_b64 s[30:31], s[30:31]
	s_cbranch_execz .LBB0_257
	v_mul_hi_i32 v97, v96, s69
	v_lshrrev_b32_e32 v98, 31, v97
	v_ashrrev_i32_e32 v97, 12, v97
	v_add_u32_e32 v97, v97, v98
	v_mad_i32_i24 v98, v97, s72, v96
	v_pk_mul_f32 v[100:101], v[144:145], v[92:93] op_sel_hi:[0,1]
	v_pk_mul_f32 v[102:103], v[144:145], v[94:95] op_sel_hi:[0,1]
	v_lshl_or_b32 v97, v97, 3, s96
	v_cvt_pk_bf16_f32 v100, v100, v101
	v_cvt_pk_bf16_f32 v101, v102, v103
	v_mul_hi_i32_i24_e32 v103, 0x2080, v97
	v_mul_i32_i24_e32 v102, 0x2080, v97
	v_ashrrev_i32_e32 v99, 31, v98
	s_add_u32 s34, s50, s77
	v_lshl_add_u64 v[98:99], v[102:103], 0, v[98:99]
	s_addc_u32 s35, s51, s25
	v_lshlrev_b64 v[98:99], 7, v[98:99]
	v_lshl_add_u64 v[98:99], s[34:35], 0, v[98:99]
	v_lshlrev_b32_e32 v102, 1, v174
	v_mov_b32_e32 v103, v135
	v_lshl_add_u64 v[98:99], v[98:99], 0, v[102:103]
	global_store_dwordx2 v[98:99], v[100:101], off nt
.LBB0_257:
	s_or_b64 exec, exec, s[30:31]
	s_and_saveexec_b64 s[30:31], s[6:7]
	s_xor_b64 s[30:31], exec, s[30:31]
	s_cbranch_execz .LBB0_264
	s_andn2_b64 vcc, exec, s[0:1]
	s_mov_b64 s[34:35], -1
	s_cbranch_vccnz .LBB0_262
	v_mul_hi_i32 v97, v96, s69
	v_lshrrev_b32_e32 v98, 31, v97
	v_ashrrev_i32_e32 v97, 12, v97
	v_add_u32_e32 v97, v97, v98
	v_mul_i32_i24_e32 v98, 0xffffdf80, v97
	v_add3_u32 v98, v98, v96, -16
	v_cmp_gt_u32_e32 vcc, s65, v98
	s_and_saveexec_b64 s[34:35], vcc
	s_cbranch_execz .LBB0_261
	v_mul_f32_e32 v99, 0xbfb8aa3b, v88
	v_mul_f32_e32 v100, 0xbfb8aa3b, v89
	v_exp_f32_e32 v99, v99
	v_exp_f32_e32 v100, v100
	v_mul_f32_e32 v101, 0xbfb8aa3b, v91
	v_exp_f32_e32 v101, v101
	v_add_f32_e32 v99, 1.0, v99
	v_add_f32_e32 v100, 1.0, v100
	v_rcp_f32_e32 v99, v99
	v_rcp_f32_e32 v100, v100
	v_add_f32_e32 v101, 1.0, v101
	v_rcp_f32_e32 v101, v101
	v_lshl_add_u32 v98, v97, 13, v98
	v_cvt_pk_bf16_f32 v100, v99, v100
	v_mul_f32_e32 v99, 0xbfb8aa3b, v90
	v_exp_f32_e32 v99, v99
	s_nop 0
	v_add_f32_e32 v99, 1.0, v99
	v_rcp_f32_e32 v99, v99
	s_nop 0
	v_cvt_pk_bf16_f32 v101, v99, v101
	v_ashrrev_i32_e32 v99, 31, v98
	v_lshlrev_b64 v[98:99], 12, v[98:99]
	v_lshl_add_u64 v[98:99], s[88:89], 0, v[98:99]
	v_lshl_add_u64 v[98:99], v[134:135], 1, v[98:99]
	v_add_co_u32_e32 v98, vcc, 0xfffff000, v98
	s_nop 1
	v_addc_co_u32_e32 v99, vcc, -1, v99, vcc
	global_store_dwordx2 v[98:99], v[100:101], off offset:-2528 nt

; __device__ __forceinline__ unsigned pk_bf16(float lo, float hi) { const f32x2 v = {lo, hi}; return __builtin_bit_cast(unsigned, __builtin_convertvector(v, b16x2)); }
;     __device__ __forceinline__ void row(int r, int col32, int fq, const f32x4& a00, const f32x4& a01, const f32x4& a10, const f32x4& a11) const { half(r, col32, fq, a00, a01); half(r, col32 + HALF, fq, a10, a11); }
;     __device__ __forceinline__ void row(int r, int col32, int fq, const f32x4& a00, const f32x4& a01, const f32x4& a10, const f32x4& a11) const { half(r, col32, fq, a00, a01); half(r, col32 + HALF, fq, a10, a11); }
;     __device__ __forceinline__ void row(int r, int col32, int fq, const f32x4& a00, const f32x4& a01, const f32x4& a10, const f32x4& a11) const { half(r, col32, fq, a00, a01); half(r, col32 + HALF, fq, a10, a11); }
;     __device__ __forceinline__ void one(int row, int col, const f32x4& v) const {
;         if (col < 1536) {
;             const int which = col >> 9, hc = col & 511, h = hc >> 6, d = hc & 63, b = row / TP, t = row - b * TP;
;             const float s = which == 0 ? 0.125f : 1.0f;
;             u32x2 w; w.x = pk_bf16(v[0] * s, v[1] * s); w.y = pk_bf16(v[2] * s, v[3] * s);
;             *(u32x2*)(qkv + (size_t)which * (QKV_ONE / 2) + ((size_t)(b * NH + h) * TP + t) * 64 + d) = w;
;         } else if (col < 3328) {
;             h16x4 o; o[0] = (_Float16)v[0]; o[1] = (_Float16)v[1]; o[2] = (_Float16)v[2]; o[3] = (_Float16)v[3];
;             *(h16x4*)(urw + (size_t)row * RWS + (col - 1536)) = o;
.LBB0_262:
	s_andn2_b64 vcc, exec, s[34:35]
	s_cbranch_vccnz .LBB0_264
	v_mov_b64_e32 v[100:101], s[50:51]
	v_mad_i64_i32 v[100:101], s[34:35], v96, s73, v[100:101]
	v_cvt_pk_f16_f32 v99, v90, v91
	v_cvt_pk_f16_f32 v98, v88, v89
	v_lshl_add_u64 v[100:101], v[134:135], 1, v[100:101]
	global_store_dwordx2 v[100:101], v[98:99], off offset:-3040 nt
.LBB0_264:
	s_andn2_saveexec_b64 s[30:31], s[30:31]
	s_cbranch_execz .LBB0_266
	v_mul_hi_i32 v97, v96, s69
	v_lshrrev_b32_e32 v98, 31, v97
	v_ashrrev_i32_e32 v97, 12, v97
	v_add_u32_e32 v97, v97, v98
	v_mad_i32_i24 v98, v97, s72, v96
	v_pk_mul_f32 v[100:101], v[144:145], v[88:89] op_sel_hi:[0,1]
	v_pk_mul_f32 v[102:103], v[144:145], v[90:91] op_sel_hi:[0,1]
	v_lshl_or_b32 v97, v97, 3, s96
	v_cvt_pk_bf16_f32 v100, v100, v101
	v_cvt_pk_bf16_f32 v101, v102, v103
	v_mul_hi_i32_i24_e32 v103, 0x2080, v97
	v_mul_i32_i24_e32 v102, 0x2080, v97
	v_ashrrev_i32_e32 v99, 31, v98
	s_add_u32 s34, s50, s77
	v_lshl_add_u64 v[98:99], v[102:103], 0, v[98:99]
	s_addc_u32 s35, s51, s25
	v_lshlrev_b64 v[98:99], 7, v[98:99]
	v_lshl_add_u64 v[98:99], s[34:35], 0, v[98:99]
	v_lshlrev_b32_e32 v102, 1, v173
	v_mov_b32_e32 v103, v135
	v_lshl_add_u64 v[98:99], v[98:99], 0, v[102:103]
	global_store_dwordx2 v[98:99], v[100:101], off nt

; __device__ __forceinline__ unsigned pk_bf16(float lo, float hi) { const f32x2 v = {lo, hi}; return __builtin_bit_cast(unsigned, __builtin_convertvector(v, b16x2)); }
; __device__ __forceinline__ float sigmoidf_(float x) { return __builtin_amdgcn_rcpf(1.0f + __expf(-x)); }
;     __device__ __forceinline__ void row(int r, int col32, int fq, const f32x4& a00, const f32x4& a01, const f32x4& a10, const f32x4& a11) const { half(r, col32, fq, a00, a01); half(r, col32 + HALF, fq, a10, a11); }
;     __device__ __forceinline__ void row(int r, int col32, int fq, const f32x4& a00, const f32x4& a01, const f32x4& a10, const f32x4& a11) const { half(r, col32, fq, a00, a01); half(r, col32 + HALF, fq, a10, a11); }
;     __device__ __forceinline__ void row(int r, int col32, int fq, const f32x4& a00, const f32x4& a01, const f32x4& a10, const f32x4& a11) const { half(r, col32, fq, a00, a01); half(r, col32 + HALF, fq, a10, a11); }
;     __device__ __forceinline__ void one(int row, int col, const f32x4& v) const {
;     ...
;         } else {
;             const int b = row / TP, t = row - b * TP;
;             if (t >= NMETA && t < T) {
;                 u32x2 w; w.x = pk_bf16(sigmoidf_(v[0]), sigmoidf_(v[1])); w.y = pk_bf16(sigmoidf_(v[2]), sigmoidf_(v[3]));
;                 *(u32x2*)(gates + (size_t)(b * SEQ + t - NMETA) * 2048 + (col - 3328)) = w;
;             }
.LBB0_268:
	s_and_saveexec_b64 s[30:31], s[10:11]
	s_xor_b64 s[30:31], exec, s[30:31]
	s_cbranch_execz .LBB0_275
	s_andn2_b64 vcc, exec, s[0:1]
	s_mov_b64 s[34:35], -1
	s_cbranch_vccnz .LBB0_273
	v_mul_hi_i32 v88, v96, s69
	v_lshrrev_b32_e32 v89, 31, v88
	v_ashrrev_i32_e32 v88, 12, v88
	v_add_u32_e32 v88, v88, v89
	v_mul_i32_i24_e32 v89, 0xffffdf80, v88
	v_add3_u32 v89, v89, v96, -16
	v_cmp_gt_u32_e32 vcc, s65, v89
	s_and_saveexec_b64 s[34:35], vcc
	s_cbranch_execz .LBB0_272
	v_mul_f32_e32 v90, 0xbfb8aa3b, v84
	v_mul_f32_e32 v91, 0xbfb8aa3b, v85
	v_mul_f32_e32 v92, 0xbfb8aa3b, v86
	v_mul_f32_e32 v93, 0xbfb8aa3b, v87
	v_exp_f32_e32 v90, v90
	v_exp_f32_e32 v91, v91
	v_exp_f32_e32 v92, v92
	v_exp_f32_e32 v93, v93
	v_add_f32_e32 v90, 1.0, v90
	v_add_f32_e32 v91, 1.0, v91
	v_add_f32_e32 v92, 1.0, v92
	v_add_f32_e32 v93, 1.0, v93
	v_rcp_f32_e32 v90, v90
	v_rcp_f32_e32 v91, v91
	v_rcp_f32_e32 v92, v92
	v_rcp_f32_e32 v93, v93
	v_lshl_add_u32 v88, v88, 13, v89
	v_ashrrev_i32_e32 v89, 31, v88
	v_lshlrev_b64 v[88:89], 12, v[88:89]
	v_cvt_pk_bf16_f32 v90, v90, v91
	v_cvt_pk_bf16_f32 v91, v92, v93
	v_lshl_add_u64 v[88:89], s[88:89], 0, v[88:89]
	v_add_u32_e32 v92, s97, v149
	v_mov_b32_e32 v93, v135
	v_lshl_add_u64 v[88:89], v[92:93], 1, v[88:89]
	v_add_co_u32_e32 v88, vcc, 0xfffff000, v88
	s_nop 1
	v_addc_co_u32_e32 v89, vcc, -1, v89, vcc
	global_store_dwordx2 v[88:89], v[90:91], off offset:-2304 nt

; __device__ __forceinline__ unsigned pk_bf16(float lo, float hi) { const f32x2 v = {lo, hi}; return __builtin_bit_cast(unsigned, __builtin_convertvector(v, b16x2)); }
; __device__ __forceinline__ float sigmoidf_(float x) { return __builtin_amdgcn_rcpf(1.0f + __expf(-x)); }
;     __device__ __forceinline__ void row(int r, int col32, int fq, const f32x4& a00, const f32x4& a01, const f32x4& a10, const f32x4& a11) const { half(r, col32, fq, a00, a01); half(r, col32 + HALF, fq, a10, a11); }
;     __device__ __forceinline__ void row(int r, int col32, int fq, const f32x4& a00, const f32x4& a01, const f32x4& a10, const f32x4& a11) const { half(r, col32, fq, a00, a01); half(r, col32 + HALF, fq, a10, a11); }
;     __device__ __forceinline__ void row(int r, int col32, int fq, const f32x4& a00, const f32x4& a01, const f32x4& a10, const f32x4& a11) const { half(r, col32, fq, a00, a01); half(r, col32 + HALF, fq, a10, a11); }
;     __device__ __forceinline__ void one(int row, int col, const f32x4& v) const {
;         if (col < 1536) {
;             const int which = col >> 9, hc = col & 511, h = hc >> 6, d = hc & 63, b = row / TP, t = row - b * TP;
;             const float s = which == 0 ? 0.125f : 1.0f;
;             u32x2 w; w.x = pk_bf16(v[0] * s, v[1] * s); w.y = pk_bf16(v[2] * s, v[3] * s);
;             *(u32x2*)(qkv + (size_t)which * (QKV_ONE / 2) + ((size_t)(b * NH + h) * TP + t) * 64 + d) = w;
;         } else if (col < 3328) {
;             h16x4 o; o[0] = (_Float16)v[0]; o[1] = (_Float16)v[1]; o[2] = (_Float16)v[2]; o[3] = (_Float16)v[3];
;             *(h16x4*)(urw + (size_t)row * RWS + (col - 1536)) = o;
;         } else {
;             const int b = row / TP, t = row - b * TP;
;             if (t >= NMETA && t < T) {
;                 u32x2 w; w.x = pk_bf16(sigmoidf_(v[0]), sigmoidf_(v[1])); w.y = pk_bf16(sigmoidf_(v[2]), sigmoidf_(v[3]));
;                 *(u32x2*)(gates + (size_t)(b * SEQ + t - NMETA) * 2048 + (col - 3328)) = w;
;             }
;         }
.LBB0_273:
	s_andn2_b64 vcc, exec, s[34:35]
	s_cbranch_vccnz .LBB0_275
	v_mov_b64_e32 v[90:91], s[50:51]
	v_mad_i64_i32 v[90:91], s[34:35], v96, s73, v[90:91]
	v_add_u32_e32 v92, s97, v149
	v_mov_b32_e32 v93, v135
	v_cvt_pk_f16_f32 v89, v86, v87
	v_cvt_pk_f16_f32 v88, v84, v85
	v_lshl_add_u64 v[90:91], v[92:93], 1, v[90:91]
	global_store_dwordx2 v[90:91], v[88:89], off offset:-2816 nt
.LBB0_275:
	s_or_saveexec_b64 s[30:31], s[30:31]
	v_mul_hi_i32 v89, v96, s69
	v_lshrrev_b32_e32 v88, 31, v89
	v_ashrrev_i32_e32 v89, 12, v89
	s_xor_b64 exec, exec, s[30:31]
	s_cbranch_execz .LBB0_277
	v_add_u32_e32 v91, v89, v88
	v_mad_i32_i24 v90, v91, s72, v96
	v_pk_mul_f32 v[92:93], v[144:145], v[84:85] op_sel_hi:[0,1]
	v_pk_mul_f32 v[94:95], v[144:145], v[86:87] op_sel_hi:[0,1]
	v_lshl_or_b32 v91, v91, 3, s94
	v_cvt_pk_bf16_f32 v92, v92, v93
	v_cvt_pk_bf16_f32 v93, v94, v95
	v_mul_hi_i32_i24_e32 v95, 0x2080, v91
	v_mul_i32_i24_e32 v94, 0x2080, v91
	v_ashrrev_i32_e32 v91, 31, v90
	s_add_u32 s34, s50, s77
	v_lshl_add_u64 v[90:91], v[94:95], 0, v[90:91]
	s_addc_u32 s35, s51, s25
	v_lshlrev_b64 v[90:91], 7, v[90:91]
	v_lshl_add_u64 v[90:91], s[34:35], 0, v[90:91]
	v_lshlrev_b32_e32 v94, 1, v124
	v_mov_b32_e32 v95, v135
	v_lshl_add_u64 v[90:91], v[90:91], 0, v[94:95]
	global_store_dwordx2 v[90:91], v[92:93], off nt
.LBB0_277:
	s_or_b64 exec, exec, s[30:31]
	s_and_saveexec_b64 s[30:31], s[4:5]
	s_xor_b64 s[30:31], exec, s[30:31]
	s_cbranch_execz .LBB0_284
	s_andn2_b64 vcc, exec, s[0:1]
	s_mov_b64 s[34:35], -1
	s_cbranch_vccnz .LBB0_282
	v_add_u32_e32 v88, v89, v88
	v_mul_i32_i24_e32 v89, 0xffffdf80, v88
	v_add3_u32 v89, v89, v96, -16
	v_cmp_gt_u32_e32 vcc, s65, v89
	s_and_saveexec_b64 s[34:35], vcc
	s_cbranch_execz .LBB0_281
	v_mul_f32_e32 v90, 0xbfb8aa3b, v80
	v_mul_f32_e32 v91, 0xbfb8aa3b, v81
	v_exp_f32_e32 v90, v90
	v_exp_f32_e32 v91, v91
	v_mul_f32_e32 v92, 0xbfb8aa3b, v83
	v_exp_f32_e32 v92, v92
	v_add_f32_e32 v90, 1.0, v90
	v_add_f32_e32 v91, 1.0, v91
	v_rcp_f32_e32 v90, v90
	v_rcp_f32_e32 v91, v91
	v_lshl_add_u32 v88, v88, 13, v89
	v_add_f32_e32 v92, 1.0, v92
	v_ashrrev_i32_e32 v89, 31, v88
	v_cvt_pk_bf16_f32 v90, v90, v91
	v_mul_f32_e32 v91, 0xbfb8aa3b, v82
	v_exp_f32_e32 v91, v91
	v_rcp_f32_e32 v92, v92
	v_lshlrev_b64 v[88:89], 12, v[88:89]
	v_lshl_add_u64 v[88:89], s[88:89], 0, v[88:89]
	v_add_f32_e32 v91, 1.0, v91
	v_rcp_f32_e32 v91, v91
	v_lshl_add_u64 v[88:89], v[134:135], 1, v[88:89]
	v_add_co_u32_e32 v88, vcc, 0xfffff000, v88
	v_cvt_pk_bf16_f32 v91, v91, v92
	s_nop 0
	v_addc_co_u32_e32 v89, vcc, -1, v89, vcc
	global_store_dwordx2 v[88:89], v[90:91], off offset:-2272 nt

; __device__ __forceinline__ unsigned pk_bf16(float lo, float hi) { const f32x2 v = {lo, hi}; return __builtin_bit_cast(unsigned, __builtin_convertvector(v, b16x2)); }
;     __device__ __forceinline__ void row(int r, int col32, int fq, const f32x4& a00, const f32x4& a01, const f32x4& a10, const f32x4& a11) const { half(r, col32, fq, a00, a01); half(r, col32 + HALF, fq, a10, a11); }
;     __device__ __forceinline__ void row(int r, int col32, int fq, const f32x4& a00, const f32x4& a01, const f32x4& a10, const f32x4& a11) const { half(r, col32, fq, a00, a01); half(r, col32 + HALF, fq, a10, a11); }
;     __device__ __forceinline__ void row(int r, int col32, int fq, const f32x4& a00, const f32x4& a01, const f32x4& a10, const f32x4& a11) const { half(r, col32, fq, a00, a01); half(r, col32 + HALF, fq, a10, a11); }
;     __device__ __forceinline__ void one(int row, int col, const f32x4& v) const {
;         if (col < 1536) {
;             const int which = col >> 9, hc = col & 511, h = hc >> 6, d = hc & 63, b = row / TP, t = row - b * TP;
;             const float s = which == 0 ? 0.125f : 1.0f;
;             u32x2 w; w.x = pk_bf16(v[0] * s, v[1] * s); w.y = pk_bf16(v[2] * s, v[3] * s);
;             *(u32x2*)(qkv + (size_t)which * (QKV_ONE / 2) + ((size_t)(b * NH + h) * TP + t) * 64 + d) = w;
;         } else if (col < 3328) {
;             h16x4 o; o[0] = (_Float16)v[0]; o[1] = (_Float16)v[1]; o[2] = (_Float16)v[2]; o[3] = (_Float16)v[3];
;             *(h16x4*)(urw + (size_t)row * RWS + (col - 1536)) = o;
.LBB0_282:
	s_andn2_b64 vcc, exec, s[34:35]
	s_cbranch_vccnz .LBB0_284
	v_mov_b64_e32 v[90:91], s[50:51]
	v_mad_i64_i32 v[90:91], s[34:35], v96, s73, v[90:91]
	v_cvt_pk_f16_f32 v89, v82, v83
	v_cvt_pk_f16_f32 v88, v80, v81
	v_lshl_add_u64 v[90:91], v[134:135], 1, v[90:91]
	global_store_dwordx2 v[90:91], v[88:89], off offset:-2784 nt
.LBB0_284:
	s_andn2_saveexec_b64 s[30:31], s[30:31]
	s_cbranch_execz .LBB0_286
	v_add_u32_e32 v89, v89, v88
	v_mad_i32_i24 v88, v89, s72, v96
	v_pk_mul_f32 v[90:91], v[144:145], v[80:81] op_sel_hi:[0,1]
	v_pk_mul_f32 v[92:93], v[144:145], v[82:83] op_sel_hi:[0,1]
	v_lshl_or_b32 v89, v89, 3, v123
	v_cvt_pk_bf16_f32 v90, v90, v91
	v_cvt_pk_bf16_f32 v91, v92, v93
	v_mul_hi_i32_i24_e32 v93, 0x2080, v89
	v_mul_i32_i24_e32 v92, 0x2080, v89
	v_ashrrev_i32_e32 v89, 31, v88
	s_add_u32 s34, s50, s77
	v_lshl_add_u64 v[88:89], v[92:93], 0, v[88:89]
	s_addc_u32 s35, s51, s25
	v_lshlrev_b64 v[88:89], 7, v[88:89]
	v_lshl_add_u64 v[88:89], s[34:35], 0, v[88:89]
	v_lshlrev_b32_e32 v92, 1, v122
	v_mov_b32_e32 v93, v135
	v_lshl_add_u64 v[88:89], v[88:89], 0, v[92:93]
	global_store_dwordx2 v[88:89], v[90:91], off nt

; __device__ __forceinline__ unsigned pk_bf16(float lo, float hi) { const f32x2 v = {lo, hi}; return __builtin_bit_cast(unsigned, __builtin_convertvector(v, b16x2)); }
; __device__ __forceinline__ float sigmoidf_(float x) { return __builtin_amdgcn_rcpf(1.0f + __expf(-x)); }
;     __device__ __forceinline__ void row(int r, int col32, int fq, const f32x4& a00, const f32x4& a01, const f32x4& a10, const f32x4& a11) const { half(r, col32, fq, a00, a01); half(r, col32 + HALF, fq, a10, a11); }
;     __device__ __forceinline__ void row(int r, int col32, int fq, const f32x4& a00, const f32x4& a01, const f32x4& a10, const f32x4& a11) const { half(r, col32, fq, a00, a01); half(r, col32 + HALF, fq, a10, a11); }
;     __device__ __forceinline__ void row(int r, int col32, int fq, const f32x4& a00, const f32x4& a01, const f32x4& a10, const f32x4& a11) const { half(r, col32, fq, a00, a01); half(r, col32 + HALF, fq, a10, a11); }
;     __device__ __forceinline__ void one(int row, int col, const f32x4& v) const {
;     ...
;         } else {
;             const int b = row / TP, t = row - b * TP;
;             if (t >= NMETA && t < T) {
;                 u32x2 w; w.x = pk_bf16(sigmoidf_(v[0]), sigmoidf_(v[1])); w.y = pk_bf16(sigmoidf_(v[2]), sigmoidf_(v[3]));
;                 *(u32x2*)(gates + (size_t)(b * SEQ + t - NMETA) * 2048 + (col - 3328)) = w;
;             }
;     __device__ __forceinline__ void half(int row, int col32, int fq, const f32x4& v0, const f32x4& v1) const {
;     ...
;             if (col32 >= 1536 && col32 < 3072) {
;                 const int c = col32 - 1536, pos = (c & ~63) + fq * 16 + ((c & 63) >> 4) * 4;
;                 h16x8 o;
; #pragma unroll
;                 for (int j = 0; j < 4; ++j) { o[j] = (_Float16)v0[j]; o[4 + j] = (_Float16)v1[j]; }
;                 *(h16x8*)(urw + (size_t)row * RWS + pos) = o;
;             } else { one(row, col32 + 4 * fq, v0); one(row, col32 + 16 + 4 * fq, v1); }
.LBB0_287:
	s_and_b64 vcc, exec, s[30:31]
	s_cbranch_vccz .LBB0_267
	v_cvt_pk_f16_f32 v91, v90, v91
	v_cvt_pk_f16_f32 v90, v88, v89
	v_cvt_pk_f16_f32 v88, v92, v93
	v_mov_b64_e32 v[92:93], s[50:51]
	v_mad_i64_i32 v[92:93], s[30:31], v96, s73, v[92:93]
	v_cvt_pk_f16_f32 v89, v94, v95
	v_lshl_add_u64 v[92:93], v[146:147], 1, v[92:93]
	global_store_dwordx4 v[92:93], v[88:91], off nt
	s_and_b64 vcc, exec, s[14:15]
	s_mov_b64 s[30:31], -1
	s_cbranch_vccz .LBB0_268
.LBB0_289:
	s_and_b64 vcc, exec, s[30:31]
	s_cbranch_vccz .LBB0_291
	v_cvt_pk_f16_f32 v83, v82, v83
	v_cvt_pk_f16_f32 v82, v80, v81
	v_cvt_pk_f16_f32 v80, v84, v85
	v_mov_b64_e32 v[84:85], s[50:51]
	v_mad_i64_i32 v[84:85], s[30:31], v96, s73, v[84:85]
	v_cvt_pk_f16_f32 v81, v86, v87
	v_lshl_add_u64 v[84:85], v[120:121], 1, v[84:85]
	global_store_dwordx4 v[84:85], v[80:83], off nt
.LBB0_291:
	s_nop 1
	v_or_b32_e32 v80, 48, v175
	s_and_b64 vcc, exec, s[12:13]
	s_mov_b64 s[30:31], -1
	s_cbranch_vccnz .LBB0_331
	s_and_saveexec_b64 s[30:31], s[8:9]
	s_xor_b64 s[30:31], exec, s[30:31]
	s_cbranch_execz .LBB0_299
	s_andn2_b64 vcc, exec, s[0:1]
	s_mov_b64 s[34:35], -1
	s_cbranch_vccnz .LBB0_297
	v_mul_hi_i32 v81, v80, s69
	v_lshrrev_b32_e32 v82, 31, v81
	v_ashrrev_i32_e32 v81, 12, v81
	v_add_u32_e32 v81, v81, v82
	v_mul_i32_i24_e32 v82, 0xffffdf80, v81
	v_add3_u32 v82, v82, v80, -16
	v_cmp_gt_u32_e32 vcc, s65, v82
	s_and_saveexec_b64 s[34:35], vcc
	s_cbranch_execz .LBB0_296
	v_mul_f32_e32 v83, 0xbfb8aa3b, v76
	v_mul_f32_e32 v84, 0xbfb8aa3b, v77
	v_exp_f32_e32 v83, v83
	v_exp_f32_e32 v84, v84
	v_mul_f32_e32 v85, 0xbfb8aa3b, v79
	v_exp_f32_e32 v85, v85
	v_add_f32_e32 v83, 1.0, v83
	v_add_f32_e32 v84, 1.0, v84
	v_rcp_f32_e32 v83, v83
	v_rcp_f32_e32 v84, v84
	v_add_f32_e32 v85, 1.0, v85
	v_rcp_f32_e32 v85, v85
	v_lshl_add_u32 v82, v81, 13, v82
	v_cvt_pk_bf16_f32 v84, v83, v84
	v_mul_f32_e32 v83, 0xbfb8aa3b, v78
	v_exp_f32_e32 v83, v83
	s_nop 0
	v_add_f32_e32 v83, 1.0, v83
	v_rcp_f32_e32 v83, v83
	s_nop 0
	v_cvt_pk_bf16_f32 v85, v83, v85
	v_ashrrev_i32_e32 v83, 31, v82
	v_lshlrev_b64 v[82:83], 12, v[82:83]
	v_lshl_add_u64 v[82:83], s[88:89], 0, v[82:83]
	v_lshl_add_u64 v[82:83], v[134:135], 1, v[82:83]
	v_add_co_u32_e32 v82, vcc, 0xfffff000, v82
	s_nop 1
	v_addc_co_u32_e32 v83, vcc, -1, v83, vcc
	global_store_dwordx2 v[82:83], v[84:85], off offset:-2560 nt

; __device__ __forceinline__ unsigned pk_bf16(float lo, float hi) { const f32x2 v = {lo, hi}; return __builtin_bit_cast(unsigned, __builtin_convertvector(v, b16x2)); }
; __device__ __forceinline__ float sigmoidf_(float x) { return __builtin_amdgcn_rcpf(1.0f + __expf(-x)); }
;     __device__ __forceinline__ void row(int r, int col32, int fq, const f32x4& a00, const f32x4& a01, const f32x4& a10, const f32x4& a11) const { half(r, col32, fq, a00, a01); half(r, col32 + HALF, fq, a10, a11); }
;     __device__ __forceinline__ void row(int r, int col32, int fq, const f32x4& a00, const f32x4& a01, const f32x4& a10, const f32x4& a11) const { half(r, col32, fq, a00, a01); half(r, col32 + HALF, fq, a10, a11); }
;     __device__ __forceinline__ void row(int r, int col32, int fq, const f32x4& a00, const f32x4& a01, const f32x4& a10, const f32x4& a11) const { half(r, col32, fq, a00, a01); half(r, col32 + HALF, fq, a10, a11); }
;     __device__ __forceinline__ void one(int row, int col, const f32x4& v) const {
;         if (col < 1536) {
;             const int which = col >> 9, hc = col & 511, h = hc >> 6, d = hc & 63, b = row / TP, t = row - b * TP;
;             const float s = which == 0 ? 0.125f : 1.0f;
;             u32x2 w; w.x = pk_bf16(v[0] * s, v[1] * s); w.y = pk_bf16(v[2] * s, v[3] * s);
;             *(u32x2*)(qkv + (size_t)which * (QKV_ONE / 2) + ((size_t)(b * NH + h) * TP + t) * 64 + d) = w;
;         } else if (col < 3328) {
;             h16x4 o; o[0] = (_Float16)v[0]; o[1] = (_Float16)v[1]; o[2] = (_Float16)v[2]; o[3] = (_Float16)v[3];
;             *(h16x4*)(urw + (size_t)row * RWS + (col - 1536)) = o;
;         } else {
;             const int b = row / TP, t = row - b * TP;
;             if (t >= NMETA && t < T) {
;                 u32x2 w; w.x = pk_bf16(sigmoidf_(v[0]), sigmoidf_(v[1])); w.y = pk_bf16(sigmoidf_(v[2]), sigmoidf_(v[3]));
;                 *(u32x2*)(gates + (size_t)(b * SEQ + t - NMETA) * 2048 + (col - 3328)) = w;
;             }
;         }
.LBB0_297:
	s_andn2_b64 vcc, exec, s[34:35]
	s_cbranch_vccnz .LBB0_299
	v_mov_b64_e32 v[84:85], s[50:51]
	v_mad_i64_i32 v[84:85], s[34:35], v80, s73, v[84:85]
	v_cvt_pk_f16_f32 v83, v78, v79
	v_cvt_pk_f16_f32 v82, v76, v77
	v_lshl_add_u64 v[84:85], v[134:135], 1, v[84:85]
	global_store_dwordx2 v[84:85], v[82:83], off offset:-3072 nt
.LBB0_299:
	s_andn2_saveexec_b64 s[30:31], s[30:31]
	s_cbranch_execz .LBB0_301
	v_mul_hi_i32 v81, v80, s69
	v_lshrrev_b32_e32 v82, 31, v81
	v_ashrrev_i32_e32 v81, 12, v81
	v_add_u32_e32 v81, v81, v82
	v_mad_i32_i24 v82, v81, s72, v80
	v_pk_mul_f32 v[84:85], v[144:145], v[76:77] op_sel_hi:[0,1]
	v_pk_mul_f32 v[86:87], v[144:145], v[78:79] op_sel_hi:[0,1]
	v_lshl_or_b32 v81, v81, 3, s96
	v_cvt_pk_bf16_f32 v84, v84, v85
	v_cvt_pk_bf16_f32 v85, v86, v87
	v_mul_hi_i32_i24_e32 v87, 0x2080, v81
	v_mul_i32_i24_e32 v86, 0x2080, v81
	v_ashrrev_i32_e32 v83, 31, v82
	s_add_u32 s34, s50, s77
	v_lshl_add_u64 v[82:83], v[86:87], 0, v[82:83]
	s_addc_u32 s35, s51, s25
	v_lshlrev_b64 v[82:83], 7, v[82:83]
	v_lshl_add_u64 v[82:83], s[34:35], 0, v[82:83]
	v_lshlrev_b32_e32 v86, 1, v174
	v_mov_b32_e32 v87, v135
	v_lshl_add_u64 v[82:83], v[82:83], 0, v[86:87]
	global_store_dwordx2 v[82:83], v[84:85], off nt
.LBB0_301:
	s_or_b64 exec, exec, s[30:31]
	s_and_saveexec_b64 s[30:31], s[6:7]
	s_xor_b64 s[30:31], exec, s[30:31]
	s_cbranch_execz .LBB0_308
	s_andn2_b64 vcc, exec, s[0:1]
	s_mov_b64 s[34:35], -1
	s_cbranch_vccnz .LBB0_306
	v_mul_hi_i32 v81, v80, s69
	v_lshrrev_b32_e32 v82, 31, v81
	v_ashrrev_i32_e32 v81, 12, v81
	v_add_u32_e32 v81, v81, v82
	v_mul_i32_i24_e32 v82, 0xffffdf80, v81
	v_add3_u32 v82, v82, v80, -16
	v_cmp_gt_u32_e32 vcc, s65, v82
	s_and_saveexec_b64 s[34:35], vcc
	s_cbranch_execz .LBB0_305
	v_mul_f32_e32 v83, 0xbfb8aa3b, v72
	v_mul_f32_e32 v84, 0xbfb8aa3b, v73
	v_exp_f32_e32 v83, v83
	v_exp_f32_e32 v84, v84
	v_mul_f32_e32 v85, 0xbfb8aa3b, v75
	v_exp_f32_e32 v85, v85
	v_add_f32_e32 v83, 1.0, v83
	v_add_f32_e32 v84, 1.0, v84
	v_rcp_f32_e32 v83, v83
	v_rcp_f32_e32 v84, v84
	v_add_f32_e32 v85, 1.0, v85
	v_rcp_f32_e32 v85, v85
	v_lshl_add_u32 v82, v81, 13, v82
	v_cvt_pk_bf16_f32 v84, v83, v84
	v_mul_f32_e32 v83, 0xbfb8aa3b, v74
	v_exp_f32_e32 v83, v83
	s_nop 0
	v_add_f32_e32 v83, 1.0, v83
	v_rcp_f32_e32 v83, v83
	s_nop 0
	v_cvt_pk_bf16_f32 v85, v83, v85
	v_ashrrev_i32_e32 v83, 31, v82
	v_lshlrev_b64 v[82:83], 12, v[82:83]
	v_lshl_add_u64 v[82:83], s[88:89], 0, v[82:83]
	v_lshl_add_u64 v[82:83], v[134:135], 1, v[82:83]
	v_add_co_u32_e32 v82, vcc, 0xfffff000, v82
	s_nop 1
	v_addc_co_u32_e32 v83, vcc, -1, v83, vcc
	global_store_dwordx2 v[82:83], v[84:85], off offset:-2528 nt

; __device__ __forceinline__ unsigned pk_bf16(float lo, float hi) { const f32x2 v = {lo, hi}; return __builtin_bit_cast(unsigned, __builtin_convertvector(v, b16x2)); }
;     __device__ __forceinline__ void row(int r, int col32, int fq, const f32x4& a00, const f32x4& a01, const f32x4& a10, const f32x4& a11) const { half(r, col32, fq, a00, a01); half(r, col32 + HALF, fq, a10, a11); }
;     __device__ __forceinline__ void row(int r, int col32, int fq, const f32x4& a00, const f32x4& a01, const f32x4& a10, const f32x4& a11) const { half(r, col32, fq, a00, a01); half(r, col32 + HALF, fq, a10, a11); }
;     __device__ __forceinline__ void row(int r, int col32, int fq, const f32x4& a00, const f32x4& a01, const f32x4& a10, const f32x4& a11) const { half(r, col32, fq, a00, a01); half(r, col32 + HALF, fq, a10, a11); }
;     __device__ __forceinline__ void one(int row, int col, const f32x4& v) const {
;         if (col < 1536) {
;             const int which = col >> 9, hc = col & 511, h = hc >> 6, d = hc & 63, b = row / TP, t = row - b * TP;
;             const float s = which == 0 ? 0.125f : 1.0f;
;             u32x2 w; w.x = pk_bf16(v[0] * s, v[1] * s); w.y = pk_bf16(v[2] * s, v[3] * s);
;             *(u32x2*)(qkv + (size_t)which * (QKV_ONE / 2) + ((size_t)(b * NH + h) * TP + t) * 64 + d) = w;
;         } else if (col < 3328) {
;             h16x4 o; o[0] = (_Float16)v[0]; o[1] = (_Float16)v[1]; o[2] = (_Float16)v[2]; o[3] = (_Float16)v[3];
;             *(h16x4*)(urw + (size_t)row * RWS + (col - 1536)) = o;
.LBB0_306:
	s_andn2_b64 vcc, exec, s[34:35]
	s_cbranch_vccnz .LBB0_308
	v_mov_b64_e32 v[84:85], s[50:51]
	v_mad_i64_i32 v[84:85], s[34:35], v80, s73, v[84:85]
	v_cvt_pk_f16_f32 v83, v74, v75
	v_cvt_pk_f16_f32 v82, v72, v73
	v_lshl_add_u64 v[84:85], v[134:135], 1, v[84:85]
	global_store_dwordx2 v[84:85], v[82:83], off offset:-3040 nt
.LBB0_308:
	s_andn2_saveexec_b64 s[30:31], s[30:31]
	s_cbranch_execz .LBB0_310
	v_mul_hi_i32 v81, v80, s69
	v_lshrrev_b32_e32 v82, 31, v81
	v_ashrrev_i32_e32 v81, 12, v81
	v_add_u32_e32 v81, v81, v82
	v_mad_i32_i24 v82, v81, s72, v80
	v_pk_mul_f32 v[84:85], v[144:145], v[72:73] op_sel_hi:[0,1]
	v_pk_mul_f32 v[86:87], v[144:145], v[74:75] op_sel_hi:[0,1]
	v_lshl_or_b32 v81, v81, 3, s96
	v_cvt_pk_bf16_f32 v84, v84, v85
	v_cvt_pk_bf16_f32 v85, v86, v87
	v_mul_hi_i32_i24_e32 v87, 0x2080, v81
	v_mul_i32_i24_e32 v86, 0x2080, v81
	v_ashrrev_i32_e32 v83, 31, v82
	s_add_u32 s34, s50, s77
	v_lshl_add_u64 v[82:83], v[86:87], 0, v[82:83]
	s_addc_u32 s35, s51, s25
	v_lshlrev_b64 v[82:83], 7, v[82:83]
	v_lshl_add_u64 v[82:83], s[34:35], 0, v[82:83]
	v_lshlrev_b32_e32 v86, 1, v173
	v_mov_b32_e32 v87, v135
	v_lshl_add_u64 v[82:83], v[82:83], 0, v[86:87]
	global_store_dwordx2 v[82:83], v[84:85], off nt

; __device__ __forceinline__ unsigned pk_bf16(float lo, float hi) { const f32x2 v = {lo, hi}; return __builtin_bit_cast(unsigned, __builtin_convertvector(v, b16x2)); }
; __device__ __forceinline__ float sigmoidf_(float x) { return __builtin_amdgcn_rcpf(1.0f + __expf(-x)); }
;     __device__ __forceinline__ void row(int r, int col32, int fq, const f32x4& a00, const f32x4& a01, const f32x4& a10, const f32x4& a11) const { half(r, col32, fq, a00, a01); half(r, col32 + HALF, fq, a10, a11); }
;     __device__ __forceinline__ void row(int r, int col32, int fq, const f32x4& a00, const f32x4& a01, const f32x4& a10, const f32x4& a11) const { half(r, col32, fq, a00, a01); half(r, col32 + HALF, fq, a10, a11); }
;     __device__ __forceinline__ void row(int r, int col32, int fq, const f32x4& a00, const f32x4& a01, const f32x4& a10, const f32x4& a11) const { half(r, col32, fq, a00, a01); half(r, col32 + HALF, fq, a10, a11); }
;     __device__ __forceinline__ void one(int row, int col, const f32x4& v) const {
;     ...
;         } else {
;             const int b = row / TP, t = row - b * TP;
;             if (t >= NMETA && t < T) {
;                 u32x2 w; w.x = pk_bf16(sigmoidf_(v[0]), sigmoidf_(v[1])); w.y = pk_bf16(sigmoidf_(v[2]), sigmoidf_(v[3]));
;                 *(u32x2*)(gates + (size_t)(b * SEQ + t - NMETA) * 2048 + (col - 3328)) = w;
;             }
.LBB0_312:
	s_and_saveexec_b64 s[30:31], s[10:11]
	s_xor_b64 s[30:31], exec, s[30:31]
	s_cbranch_execz .LBB0_319
	s_andn2_b64 vcc, exec, s[0:1]
	s_mov_b64 s[34:35], -1
	s_cbranch_vccnz .LBB0_317
	v_mul_hi_i32 v72, v80, s69
	v_lshrrev_b32_e32 v73, 31, v72
	v_ashrrev_i32_e32 v72, 12, v72
	v_add_u32_e32 v72, v72, v73
	v_mul_i32_i24_e32 v73, 0xffffdf80, v72
	v_add3_u32 v73, v73, v80, -16
	v_cmp_gt_u32_e32 vcc, s65, v73
	s_and_saveexec_b64 s[34:35], vcc
	s_cbranch_execz .LBB0_316
	v_mul_f32_e32 v74, 0xbfb8aa3b, v68
	v_mul_f32_e32 v75, 0xbfb8aa3b, v69
	v_mul_f32_e32 v76, 0xbfb8aa3b, v70
	v_mul_f32_e32 v77, 0xbfb8aa3b, v71
	v_exp_f32_e32 v74, v74
	v_exp_f32_e32 v75, v75
	v_exp_f32_e32 v76, v76
	v_exp_f32_e32 v77, v77
	v_add_f32_e32 v74, 1.0, v74
	v_add_f32_e32 v75, 1.0, v75
	v_add_f32_e32 v76, 1.0, v76
	v_add_f32_e32 v77, 1.0, v77
	v_rcp_f32_e32 v74, v74
	v_rcp_f32_e32 v75, v75
	v_rcp_f32_e32 v76, v76
	v_rcp_f32_e32 v77, v77
	v_lshl_add_u32 v72, v72, 13, v73
	v_ashrrev_i32_e32 v73, 31, v72
	v_lshlrev_b64 v[72:73], 12, v[72:73]
	v_cvt_pk_bf16_f32 v74, v74, v75
	v_cvt_pk_bf16_f32 v75, v76, v77
	v_lshl_add_u64 v[72:73], s[88:89], 0, v[72:73]
	v_add_u32_e32 v76, s97, v149
	v_mov_b32_e32 v77, v135
	v_lshl_add_u64 v[72:73], v[76:77], 1, v[72:73]
	v_add_co_u32_e32 v72, vcc, 0xfffff000, v72
	s_nop 1
	v_addc_co_u32_e32 v73, vcc, -1, v73, vcc
	global_store_dwordx2 v[72:73], v[74:75], off offset:-2304 nt

; __device__ __forceinline__ unsigned pk_bf16(float lo, float hi) { const f32x2 v = {lo, hi}; return __builtin_bit_cast(unsigned, __builtin_convertvector(v, b16x2)); }
; __device__ __forceinline__ float sigmoidf_(float x) { return __builtin_amdgcn_rcpf(1.0f + __expf(-x)); }
;     __device__ __forceinline__ void row(int r, int col32, int fq, const f32x4& a00, const f32x4& a01, const f32x4& a10, const f32x4& a11) const { half(r, col32, fq, a00, a01); half(r, col32 + HALF, fq, a10, a11); }
;     __device__ __forceinline__ void row(int r, int col32, int fq, const f32x4& a00, const f32x4& a01, const f32x4& a10, const f32x4& a11) const { half(r, col32, fq, a00, a01); half(r, col32 + HALF, fq, a10, a11); }
;     __device__ __forceinline__ void row(int r, int col32, int fq, const f32x4& a00, const f32x4& a01, const f32x4& a10, const f32x4& a11) const { half(r, col32, fq, a00, a01); half(r, col32 + HALF, fq, a10, a11); }
;     __device__ __forceinline__ void one(int row, int col, const f32x4& v) const {
;         if (col < 1536) {
;             const int which = col >> 9, hc = col & 511, h = hc >> 6, d = hc & 63, b = row / TP, t = row - b * TP;
;             const float s = which == 0 ? 0.125f : 1.0f;
;             u32x2 w; w.x = pk_bf16(v[0] * s, v[1] * s); w.y = pk_bf16(v[2] * s, v[3] * s);
;             *(u32x2*)(qkv + (size_t)which * (QKV_ONE / 2) + ((size_t)(b * NH + h) * TP + t) * 64 + d) = w;
;         } else if (col < 3328) {
;             h16x4 o; o[0] = (_Float16)v[0]; o[1] = (_Float16)v[1]; o[2] = (_Float16)v[2]; o[3] = (_Float16)v[3];
;             *(h16x4*)(urw + (size_t)row * RWS + (col - 1536)) = o;
;         } else {
;             const int b = row / TP, t = row - b * TP;
;             if (t >= NMETA && t < T) {
;                 u32x2 w; w.x = pk_bf16(sigmoidf_(v[0]), sigmoidf_(v[1])); w.y = pk_bf16(sigmoidf_(v[2]), sigmoidf_(v[3]));
;                 *(u32x2*)(gates + (size_t)(b * SEQ + t - NMETA) * 2048 + (col - 3328)) = w;
;             }
;         }
.LBB0_317:
	s_andn2_b64 vcc, exec, s[34:35]
	s_cbranch_vccnz .LBB0_319
	v_mov_b64_e32 v[74:75], s[50:51]
	v_mad_i64_i32 v[74:75], s[34:35], v80, s73, v[74:75]
	v_add_u32_e32 v76, s97, v149
	v_mov_b32_e32 v77, v135
	v_cvt_pk_f16_f32 v73, v70, v71
	v_cvt_pk_f16_f32 v72, v68, v69
	v_lshl_add_u64 v[74:75], v[76:77], 1, v[74:75]
	global_store_dwordx2 v[74:75], v[72:73], off offset:-2816 nt
.LBB0_319:
	s_or_saveexec_b64 s[30:31], s[30:31]
	v_mul_hi_i32 v73, v80, s69
	v_lshrrev_b32_e32 v72, 31, v73
	v_ashrrev_i32_e32 v73, 12, v73
	s_xor_b64 exec, exec, s[30:31]
	s_cbranch_execz .LBB0_321
	v_add_u32_e32 v75, v73, v72
	v_mad_i32_i24 v74, v75, s72, v80
	v_pk_mul_f32 v[76:77], v[144:145], v[68:69] op_sel_hi:[0,1]
	v_pk_mul_f32 v[78:79], v[144:145], v[70:71] op_sel_hi:[0,1]
	v_lshl_or_b32 v75, v75, 3, s94
	v_cvt_pk_bf16_f32 v76, v76, v77
	v_cvt_pk_bf16_f32 v77, v78, v79
	v_mul_hi_i32_i24_e32 v79, 0x2080, v75
	v_mul_i32_i24_e32 v78, 0x2080, v75
	v_ashrrev_i32_e32 v75, 31, v74
	s_add_u32 s34, s50, s77
	v_lshl_add_u64 v[74:75], v[78:79], 0, v[74:75]
	s_addc_u32 s35, s51, s25
	v_lshlrev_b64 v[74:75], 7, v[74:75]
	v_lshl_add_u64 v[74:75], s[34:35], 0, v[74:75]
	v_lshlrev_b32_e32 v78, 1, v124
	v_mov_b32_e32 v79, v135
	v_lshl_add_u64 v[74:75], v[74:75], 0, v[78:79]
	global_store_dwordx2 v[74:75], v[76:77], off nt
.LBB0_321:
	s_or_b64 exec, exec, s[30:31]
	s_and_saveexec_b64 s[30:31], s[4:5]
	s_xor_b64 s[30:31], exec, s[30:31]
	s_cbranch_execz .LBB0_328
	s_andn2_b64 vcc, exec, s[0:1]
	s_mov_b64 s[34:35], -1
	s_cbranch_vccnz .LBB0_326
	v_add_u32_e32 v72, v73, v72
	v_mul_i32_i24_e32 v73, 0xffffdf80, v72
	v_add3_u32 v73, v73, v80, -16
	v_cmp_gt_u32_e32 vcc, s65, v73
	s_and_saveexec_b64 s[34:35], vcc
	s_cbranch_execz .LBB0_325
	v_mul_f32_e32 v74, 0xbfb8aa3b, v64
	v_mul_f32_e32 v75, 0xbfb8aa3b, v65
	v_exp_f32_e32 v74, v74
	v_exp_f32_e32 v75, v75
	v_mul_f32_e32 v76, 0xbfb8aa3b, v67
	v_exp_f32_e32 v76, v76
	v_add_f32_e32 v74, 1.0, v74
	v_add_f32_e32 v75, 1.0, v75
	v_rcp_f32_e32 v74, v74
	v_rcp_f32_e32 v75, v75
	v_lshl_add_u32 v72, v72, 13, v73
	v_add_f32_e32 v76, 1.0, v76
	v_ashrrev_i32_e32 v73, 31, v72
	v_cvt_pk_bf16_f32 v74, v74, v75
	v_mul_f32_e32 v75, 0xbfb8aa3b, v66
	v_exp_f32_e32 v75, v75
	v_rcp_f32_e32 v76, v76
	v_lshlrev_b64 v[72:73], 12, v[72:73]
	v_lshl_add_u64 v[72:73], s[88:89], 0, v[72:73]
	v_add_f32_e32 v75, 1.0, v75
	v_rcp_f32_e32 v75, v75
	v_lshl_add_u64 v[72:73], v[134:135], 1, v[72:73]
	v_add_co_u32_e32 v72, vcc, 0xfffff000, v72
	v_cvt_pk_bf16_f32 v75, v75, v76
	s_nop 0
	v_addc_co_u32_e32 v73, vcc, -1, v73, vcc
	global_store_dwordx2 v[72:73], v[74:75], off offset:-2272 nt

; __device__ __forceinline__ unsigned pk_bf16(float lo, float hi) { const f32x2 v = {lo, hi}; return __builtin_bit_cast(unsigned, __builtin_convertvector(v, b16x2)); }
;     __device__ __forceinline__ void row(int r, int col32, int fq, const f32x4& a00, const f32x4& a01, const f32x4& a10, const f32x4& a11) const { half(r, col32, fq, a00, a01); half(r, col32 + HALF, fq, a10, a11); }
;     __device__ __forceinline__ void row(int r, int col32, int fq, const f32x4& a00, const f32x4& a01, const f32x4& a10, const f32x4& a11) const { half(r, col32, fq, a00, a01); half(r, col32 + HALF, fq, a10, a11); }
;     __device__ __forceinline__ void row(int r, int col32, int fq, const f32x4& a00, const f32x4& a01, const f32x4& a10, const f32x4& a11) const { half(r, col32, fq, a00, a01); half(r, col32 + HALF, fq, a10, a11); }
;     __device__ __forceinline__ void one(int row, int col, const f32x4& v) const {
;         if (col < 1536) {
;             const int which = col >> 9, hc = col & 511, h = hc >> 6, d = hc & 63, b = row / TP, t = row - b * TP;
;             const float s = which == 0 ? 0.125f : 1.0f;
;             u32x2 w; w.x = pk_bf16(v[0] * s, v[1] * s); w.y = pk_bf16(v[2] * s, v[3] * s);
;             *(u32x2*)(qkv + (size_t)which * (QKV_ONE / 2) + ((size_t)(b * NH + h) * TP + t) * 64 + d) = w;
;         } else if (col < 3328) {
;             h16x4 o; o[0] = (_Float16)v[0]; o[1] = (_Float16)v[1]; o[2] = (_Float16)v[2]; o[3] = (_Float16)v[3];
;             *(h16x4*)(urw + (size_t)row * RWS + (col - 1536)) = o;
.LBB0_326:
	s_andn2_b64 vcc, exec, s[34:35]
	s_cbranch_vccnz .LBB0_328
	v_mov_b64_e32 v[74:75], s[50:51]
	v_mad_i64_i32 v[74:75], s[34:35], v80, s73, v[74:75]
	v_cvt_pk_f16_f32 v73, v66, v67
	v_cvt_pk_f16_f32 v72, v64, v65
	v_lshl_add_u64 v[74:75], v[134:135], 1, v[74:75]
	global_store_dwordx2 v[74:75], v[72:73], off offset:-2784 nt
.LBB0_328:
	s_andn2_saveexec_b64 s[30:31], s[30:31]
	s_cbranch_execz .LBB0_330
	v_add_u32_e32 v73, v73, v72
	v_mad_i32_i24 v72, v73, s72, v80
	v_pk_mul_f32 v[74:75], v[144:145], v[64:65] op_sel_hi:[0,1]
	v_pk_mul_f32 v[76:77], v[144:145], v[66:67] op_sel_hi:[0,1]
	v_lshl_or_b32 v73, v73, 3, v123
	v_cvt_pk_bf16_f32 v74, v74, v75
	v_cvt_pk_bf16_f32 v75, v76, v77
	v_mul_hi_i32_i24_e32 v77, 0x2080, v73
	v_mul_i32_i24_e32 v76, 0x2080, v73
	v_ashrrev_i32_e32 v73, 31, v72
	s_add_u32 s34, s50, s77
	v_lshl_add_u64 v[72:73], v[76:77], 0, v[72:73]
	s_addc_u32 s35, s51, s25
	v_lshlrev_b64 v[72:73], 7, v[72:73]
	v_lshl_add_u64 v[72:73], s[34:35], 0, v[72:73]
	v_lshlrev_b32_e32 v76, 1, v122
	v_mov_b32_e32 v77, v135
	v_lshl_add_u64 v[72:73], v[72:73], 0, v[76:77]
	global_store_dwordx2 v[72:73], v[74:75], off nt

; __device__ __forceinline__ unsigned pk_bf16(float lo, float hi) { const f32x2 v = {lo, hi}; return __builtin_bit_cast(unsigned, __builtin_convertvector(v, b16x2)); }
; __device__ __forceinline__ float sigmoidf_(float x) { return __builtin_amdgcn_rcpf(1.0f + __expf(-x)); }
;     __device__ __forceinline__ void row(int r, int col32, int fq, const f32x4& a00, const f32x4& a01, const f32x4& a10, const f32x4& a11) const { half(r, col32, fq, a00, a01); half(r, col32 + HALF, fq, a10, a11); }
;     __device__ __forceinline__ void row(int r, int col32, int fq, const f32x4& a00, const f32x4& a01, const f32x4& a10, const f32x4& a11) const { half(r, col32, fq, a00, a01); half(r, col32 + HALF, fq, a10, a11); }
;     __device__ __forceinline__ void row(int r, int col32, int fq, const f32x4& a00, const f32x4& a01, const f32x4& a10, const f32x4& a11) const { half(r, col32, fq, a00, a01); half(r, col32 + HALF, fq, a10, a11); }
;     __device__ __forceinline__ void one(int row, int col, const f32x4& v) const {
;     ...
;         } else {
;             const int b = row / TP, t = row - b * TP;
;             if (t >= NMETA && t < T) {
;                 u32x2 w; w.x = pk_bf16(sigmoidf_(v[0]), sigmoidf_(v[1])); w.y = pk_bf16(sigmoidf_(v[2]), sigmoidf_(v[3]));
;                 *(u32x2*)(gates + (size_t)(b * SEQ + t - NMETA) * 2048 + (col - 3328)) = w;
;             }
;     __device__ __forceinline__ void half(int row, int col32, int fq, const f32x4& v0, const f32x4& v1) const {
;     ...
;             if (col32 >= 1536 && col32 < 3072) {
;                 const int c = col32 - 1536, pos = (c & ~63) + fq * 16 + ((c & 63) >> 4) * 4;
;                 h16x8 o;
; #pragma unroll
;                 for (int j = 0; j < 4; ++j) { o[j] = (_Float16)v0[j]; o[4 + j] = (_Float16)v1[j]; }
;                 *(h16x8*)(urw + (size_t)row * RWS + pos) = o;
;             } else { one(row, col32 + 4 * fq, v0); one(row, col32 + 16 + 4 * fq, v1); }
.LBB0_331:
	s_and_b64 vcc, exec, s[30:31]
	s_cbranch_vccz .LBB0_311
	v_cvt_pk_f16_f32 v75, v74, v75
	v_cvt_pk_f16_f32 v74, v72, v73
	v_cvt_pk_f16_f32 v72, v76, v77
	v_mov_b64_e32 v[76:77], s[50:51]
	v_mad_i64_i32 v[76:77], s[30:31], v80, s73, v[76:77]
	v_cvt_pk_f16_f32 v73, v78, v79
	v_lshl_add_u64 v[76:77], v[146:147], 1, v[76:77]
	global_store_dwordx4 v[76:77], v[72:75], off nt
	s_and_b64 vcc, exec, s[14:15]
	s_mov_b64 s[30:31], -1
	s_cbranch_vccz .LBB0_312
.LBB0_333:
	s_and_b64 vcc, exec, s[30:31]
	s_cbranch_vccz .LBB0_335
	v_cvt_pk_f16_f32 v67, v66, v67
	v_cvt_pk_f16_f32 v66, v64, v65
	v_cvt_pk_f16_f32 v64, v68, v69
	v_mov_b64_e32 v[68:69], s[50:51]
	v_mad_i64_i32 v[68:69], s[30:31], v80, s73, v[68:69]
	v_cvt_pk_f16_f32 v65, v70, v71
	v_lshl_add_u64 v[68:69], v[120:121], 1, v[68:69]
	global_store_dwordx4 v[68:69], v[64:67], off nt
.LBB0_335:
	s_nop 1
	v_add_u32_e32 v64, 0x80, v175
	s_and_b64 vcc, exec, s[12:13]
	s_mov_b64 s[30:31], -1
	s_cbranch_vccnz .LBB0_375
	s_and_saveexec_b64 s[30:31], s[8:9]
	s_xor_b64 s[30:31], exec, s[30:31]
	s_cbranch_execz .LBB0_343
	s_andn2_b64 vcc, exec, s[0:1]
	s_mov_b64 s[34:35], -1
	s_cbranch_vccnz .LBB0_341
	v_mul_hi_i32 v65, v64, s69
	v_lshrrev_b32_e32 v66, 31, v65
	v_ashrrev_i32_e32 v65, 12, v65
	v_add_u32_e32 v65, v65, v66
	v_mul_i32_i24_e32 v66, 0xffffdf80, v65
	v_add3_u32 v66, v66, v64, -16
	v_cmp_gt_u32_e32 vcc, s65, v66
	s_and_saveexec_b64 s[34:35], vcc
	s_cbranch_execz .LBB0_340
	v_mul_f32_e32 v67, 0xbfb8aa3b, v60
	v_mul_f32_e32 v68, 0xbfb8aa3b, v61
	v_exp_f32_e32 v67, v67
	v_exp_f32_e32 v68, v68
	v_mul_f32_e32 v69, 0xbfb8aa3b, v63
	v_exp_f32_e32 v69, v69
	v_add_f32_e32 v67, 1.0, v67
	v_add_f32_e32 v68, 1.0, v68
	v_rcp_f32_e32 v67, v67
	v_rcp_f32_e32 v68, v68
	v_add_f32_e32 v69, 1.0, v69
	v_rcp_f32_e32 v69, v69
	v_lshl_add_u32 v66, v65, 13, v66
	v_cvt_pk_bf16_f32 v68, v67, v68
	v_mul_f32_e32 v67, 0xbfb8aa3b, v62
	v_exp_f32_e32 v67, v67
	s_nop 0
	v_add_f32_e32 v67, 1.0, v67
	v_rcp_f32_e32 v67, v67
	s_nop 0
	v_cvt_pk_bf16_f32 v69, v67, v69
	v_ashrrev_i32_e32 v67, 31, v66
	v_lshlrev_b64 v[66:67], 12, v[66:67]
	v_lshl_add_u64 v[66:67], s[88:89], 0, v[66:67]
	v_lshl_add_u64 v[66:67], v[134:135], 1, v[66:67]
	v_add_co_u32_e32 v66, vcc, 0xfffff000, v66
	s_nop 1
	v_addc_co_u32_e32 v67, vcc, -1, v67, vcc
	global_store_dwordx2 v[66:67], v[68:69], off offset:-2560 nt

; __device__ __forceinline__ unsigned pk_bf16(float lo, float hi) { const f32x2 v = {lo, hi}; return __builtin_bit_cast(unsigned, __builtin_convertvector(v, b16x2)); }
; __device__ __forceinline__ float sigmoidf_(float x) { return __builtin_amdgcn_rcpf(1.0f + __expf(-x)); }
;     __device__ __forceinline__ void row(int r, int col32, int fq, const f32x4& a00, const f32x4& a01, const f32x4& a10, const f32x4& a11) const { half(r, col32, fq, a00, a01); half(r, col32 + HALF, fq, a10, a11); }
;     __device__ __forceinline__ void row(int r, int col32, int fq, const f32x4& a00, const f32x4& a01, const f32x4& a10, const f32x4& a11) const { half(r, col32, fq, a00, a01); half(r, col32 + HALF, fq, a10, a11); }
;     __device__ __forceinline__ void row(int r, int col32, int fq, const f32x4& a00, const f32x4& a01, const f32x4& a10, const f32x4& a11) const { half(r, col32, fq, a00, a01); half(r, col32 + HALF, fq, a10, a11); }
;     __device__ __forceinline__ void one(int row, int col, const f32x4& v) const {
;         if (col < 1536) {
;             const int which = col >> 9, hc = col & 511, h = hc >> 6, d = hc & 63, b = row / TP, t = row - b * TP;
;             const float s = which == 0 ? 0.125f : 1.0f;
;             u32x2 w; w.x = pk_bf16(v[0] * s, v[1] * s); w.y = pk_bf16(v[2] * s, v[3] * s);
;             *(u32x2*)(qkv + (size_t)which * (QKV_ONE / 2) + ((size_t)(b * NH + h) * TP + t) * 64 + d) = w;
;         } else if (col < 3328) {
;             h16x4 o; o[0] = (_Float16)v[0]; o[1] = (_Float16)v[1]; o[2] = (_Float16)v[2]; o[3] = (_Float16)v[3];
;             *(h16x4*)(urw + (size_t)row * RWS + (col - 1536)) = o;
;         } else {
;             const int b = row / TP, t = row - b * TP;
;             if (t >= NMETA && t < T) {
;                 u32x2 w; w.x = pk_bf16(sigmoidf_(v[0]), sigmoidf_(v[1])); w.y = pk_bf16(sigmoidf_(v[2]), sigmoidf_(v[3]));
;                 *(u32x2*)(gates + (size_t)(b * SEQ + t - NMETA) * 2048 + (col - 3328)) = w;
;             }
;         }
.LBB0_341:
	s_andn2_b64 vcc, exec, s[34:35]
	s_cbranch_vccnz .LBB0_343
	v_mov_b64_e32 v[68:69], s[50:51]
	v_mad_i64_i32 v[68:69], s[34:35], v64, s73, v[68:69]
	v_cvt_pk_f16_f32 v67, v62, v63
	v_cvt_pk_f16_f32 v66, v60, v61
	v_lshl_add_u64 v[68:69], v[134:135], 1, v[68:69]
	global_store_dwordx2 v[68:69], v[66:67], off offset:-3072 nt
.LBB0_343:
	s_andn2_saveexec_b64 s[30:31], s[30:31]
	s_cbranch_execz .LBB0_345
	v_mul_hi_i32 v65, v64, s69
	v_lshrrev_b32_e32 v66, 31, v65
	v_ashrrev_i32_e32 v65, 12, v65
	v_add_u32_e32 v65, v65, v66
	v_mad_i32_i24 v66, v65, s72, v64
	v_pk_mul_f32 v[68:69], v[144:145], v[60:61] op_sel_hi:[0,1]
	v_pk_mul_f32 v[70:71], v[144:145], v[62:63] op_sel_hi:[0,1]
	v_lshl_or_b32 v65, v65, 3, s96
	v_cvt_pk_bf16_f32 v68, v68, v69
	v_cvt_pk_bf16_f32 v69, v70, v71
	v_mul_hi_i32_i24_e32 v71, 0x2080, v65
	v_mul_i32_i24_e32 v70, 0x2080, v65
	v_ashrrev_i32_e32 v67, 31, v66
	s_add_u32 s34, s50, s77
	v_lshl_add_u64 v[66:67], v[70:71], 0, v[66:67]
	s_addc_u32 s35, s51, s25
	v_lshlrev_b64 v[66:67], 7, v[66:67]
	v_lshl_add_u64 v[66:67], s[34:35], 0, v[66:67]
	v_lshlrev_b32_e32 v70, 1, v174
	v_mov_b32_e32 v71, v135
	v_lshl_add_u64 v[66:67], v[66:67], 0, v[70:71]
	global_store_dwordx2 v[66:67], v[68:69], off nt
.LBB0_345:
	s_or_b64 exec, exec, s[30:31]
	s_and_saveexec_b64 s[30:31], s[6:7]
	s_xor_b64 s[30:31], exec, s[30:31]
	s_cbranch_execz .LBB0_352
	s_andn2_b64 vcc, exec, s[0:1]
	s_mov_b64 s[34:35], -1
	s_cbranch_vccnz .LBB0_350
	v_mul_hi_i32 v65, v64, s69
	v_lshrrev_b32_e32 v66, 31, v65
	v_ashrrev_i32_e32 v65, 12, v65
	v_add_u32_e32 v65, v65, v66
	v_mul_i32_i24_e32 v66, 0xffffdf80, v65
	v_add3_u32 v66, v66, v64, -16
	v_cmp_gt_u32_e32 vcc, s65, v66
	s_and_saveexec_b64 s[34:35], vcc
	s_cbranch_execz .LBB0_349
	v_mul_f32_e32 v67, 0xbfb8aa3b, v56
	v_mul_f32_e32 v68, 0xbfb8aa3b, v57
	v_exp_f32_e32 v67, v67
	v_exp_f32_e32 v68, v68
	v_mul_f32_e32 v69, 0xbfb8aa3b, v59
	v_exp_f32_e32 v69, v69
	v_add_f32_e32 v67, 1.0, v67
	v_add_f32_e32 v68, 1.0, v68
	v_rcp_f32_e32 v67, v67
	v_rcp_f32_e32 v68, v68
	v_add_f32_e32 v69, 1.0, v69
	v_rcp_f32_e32 v69, v69
	v_lshl_add_u32 v66, v65, 13, v66
	v_cvt_pk_bf16_f32 v68, v67, v68
	v_mul_f32_e32 v67, 0xbfb8aa3b, v58
	v_exp_f32_e32 v67, v67
	s_nop 0
	v_add_f32_e32 v67, 1.0, v67
	v_rcp_f32_e32 v67, v67
	s_nop 0
	v_cvt_pk_bf16_f32 v69, v67, v69
	v_ashrrev_i32_e32 v67, 31, v66
	v_lshlrev_b64 v[66:67], 12, v[66:67]
	v_lshl_add_u64 v[66:67], s[88:89], 0, v[66:67]
	v_lshl_add_u64 v[66:67], v[134:135], 1, v[66:67]
	v_add_co_u32_e32 v66, vcc, 0xfffff000, v66
	s_nop 1
	v_addc_co_u32_e32 v67, vcc, -1, v67, vcc
	global_store_dwordx2 v[66:67], v[68:69], off offset:-2528 nt

; __device__ __forceinline__ unsigned pk_bf16(float lo, float hi) { const f32x2 v = {lo, hi}; return __builtin_bit_cast(unsigned, __builtin_convertvector(v, b16x2)); }
;     __device__ __forceinline__ void row(int r, int col32, int fq, const f32x4& a00, const f32x4& a01, const f32x4& a10, const f32x4& a11) const { half(r, col32, fq, a00, a01); half(r, col32 + HALF, fq, a10, a11); }
;     __device__ __forceinline__ void row(int r, int col32, int fq, const f32x4& a00, const f32x4& a01, const f32x4& a10, const f32x4& a11) const { half(r, col32, fq, a00, a01); half(r, col32 + HALF, fq, a10, a11); }
;     __device__ __forceinline__ void row(int r, int col32, int fq, const f32x4& a00, const f32x4& a01, const f32x4& a10, const f32x4& a11) const { half(r, col32, fq, a00, a01); half(r, col32 + HALF, fq, a10, a11); }
;     __device__ __forceinline__ void one(int row, int col, const f32x4& v) const {
;         if (col < 1536) {
;             const int which = col >> 9, hc = col & 511, h = hc >> 6, d = hc & 63, b = row / TP, t = row - b * TP;
;             const float s = which == 0 ? 0.125f : 1.0f;
;             u32x2 w; w.x = pk_bf16(v[0] * s, v[1] * s); w.y = pk_bf16(v[2] * s, v[3] * s);
;             *(u32x2*)(qkv + (size_t)which * (QKV_ONE / 2) + ((size_t)(b * NH + h) * TP + t) * 64 + d) = w;
;         } else if (col < 3328) {
;             h16x4 o; o[0] = (_Float16)v[0]; o[1] = (_Float16)v[1]; o[2] = (_Float16)v[2]; o[3] = (_Float16)v[3];
;             *(h16x4*)(urw + (size_t)row * RWS + (col - 1536)) = o;
.LBB0_350:
	s_andn2_b64 vcc, exec, s[34:35]
	s_cbranch_vccnz .LBB0_352
	v_mov_b64_e32 v[68:69], s[50:51]
	v_mad_i64_i32 v[68:69], s[34:35], v64, s73, v[68:69]
	v_cvt_pk_f16_f32 v67, v58, v59
	v_cvt_pk_f16_f32 v66, v56, v57
	v_lshl_add_u64 v[68:69], v[134:135], 1, v[68:69]
	global_store_dwordx2 v[68:69], v[66:67], off offset:-3040 nt
.LBB0_352:
	s_andn2_saveexec_b64 s[30:31], s[30:31]
	s_cbranch_execz .LBB0_354
	v_mul_hi_i32 v65, v64, s69
	v_lshrrev_b32_e32 v66, 31, v65
	v_ashrrev_i32_e32 v65, 12, v65
	v_add_u32_e32 v65, v65, v66
	v_mad_i32_i24 v66, v65, s72, v64
	v_pk_mul_f32 v[68:69], v[144:145], v[56:57] op_sel_hi:[0,1]
	v_pk_mul_f32 v[70:71], v[144:145], v[58:59] op_sel_hi:[0,1]
	v_lshl_or_b32 v65, v65, 3, s96
	v_cvt_pk_bf16_f32 v68, v68, v69
	v_cvt_pk_bf16_f32 v69, v70, v71
	v_mul_hi_i32_i24_e32 v71, 0x2080, v65
	v_mul_i32_i24_e32 v70, 0x2080, v65
	v_ashrrev_i32_e32 v67, 31, v66
	s_add_u32 s34, s50, s77
	v_lshl_add_u64 v[66:67], v[70:71], 0, v[66:67]
	s_addc_u32 s35, s51, s25
	v_lshlrev_b64 v[66:67], 7, v[66:67]
	v_lshl_add_u64 v[66:67], s[34:35], 0, v[66:67]
	v_lshlrev_b32_e32 v70, 1, v173
	v_mov_b32_e32 v71, v135
	v_lshl_add_u64 v[66:67], v[66:67], 0, v[70:71]
	global_store_dwordx2 v[66:67], v[68:69], off nt

; __device__ __forceinline__ unsigned pk_bf16(float lo, float hi) { const f32x2 v = {lo, hi}; return __builtin_bit_cast(unsigned, __builtin_convertvector(v, b16x2)); }
; __device__ __forceinline__ float sigmoidf_(float x) { return __builtin_amdgcn_rcpf(1.0f + __expf(-x)); }
;     __device__ __forceinline__ void row(int r, int col32, int fq, const f32x4& a00, const f32x4& a01, const f32x4& a10, const f32x4& a11) const { half(r, col32, fq, a00, a01); half(r, col32 + HALF, fq, a10, a11); }
;     __device__ __forceinline__ void row(int r, int col32, int fq, const f32x4& a00, const f32x4& a01, const f32x4& a10, const f32x4& a11) const { half(r, col32, fq, a00, a01); half(r, col32 + HALF, fq, a10, a11); }
;     __device__ __forceinline__ void row(int r, int col32, int fq, const f32x4& a00, const f32x4& a01, const f32x4& a10, const f32x4& a11) const { half(r, col32, fq, a00, a01); half(r, col32 + HALF, fq, a10, a11); }
;     __device__ __forceinline__ void one(int row, int col, const f32x4& v) const {
;     ...
;         } else {
;             const int b = row / TP, t = row - b * TP;
;             if (t >= NMETA && t < T) {
;                 u32x2 w; w.x = pk_bf16(sigmoidf_(v[0]), sigmoidf_(v[1])); w.y = pk_bf16(sigmoidf_(v[2]), sigmoidf_(v[3]));
;                 *(u32x2*)(gates + (size_t)(b * SEQ + t - NMETA) * 2048 + (col - 3328)) = w;
;             }
.LBB0_356:
	s_and_saveexec_b64 s[30:31], s[10:11]
	s_xor_b64 s[30:31], exec, s[30:31]
	s_cbranch_execz .LBB0_363
	s_andn2_b64 vcc, exec, s[0:1]
	s_mov_b64 s[34:35], -1
	s_cbranch_vccnz .LBB0_361
	v_mul_hi_i32 v56, v64, s69
	v_lshrrev_b32_e32 v57, 31, v56
	v_ashrrev_i32_e32 v56, 12, v56
	v_add_u32_e32 v56, v56, v57
	v_mul_i32_i24_e32 v57, 0xffffdf80, v56
	v_add3_u32 v57, v57, v64, -16
	v_cmp_gt_u32_e32 vcc, s65, v57
	s_and_saveexec_b64 s[34:35], vcc
	s_cbranch_execz .LBB0_360
	v_mul_f32_e32 v58, 0xbfb8aa3b, v52
	v_mul_f32_e32 v59, 0xbfb8aa3b, v53
	v_mul_f32_e32 v60, 0xbfb8aa3b, v54
	v_mul_f32_e32 v61, 0xbfb8aa3b, v55
	v_exp_f32_e32 v58, v58
	v_exp_f32_e32 v59, v59
	v_exp_f32_e32 v60, v60
	v_exp_f32_e32 v61, v61
	v_add_f32_e32 v58, 1.0, v58
	v_add_f32_e32 v59, 1.0, v59
	v_add_f32_e32 v60, 1.0, v60
	v_add_f32_e32 v61, 1.0, v61
	v_rcp_f32_e32 v58, v58
	v_rcp_f32_e32 v59, v59
	v_rcp_f32_e32 v60, v60
	v_rcp_f32_e32 v61, v61
	v_lshl_add_u32 v56, v56, 13, v57
	v_ashrrev_i32_e32 v57, 31, v56
	v_lshlrev_b64 v[56:57], 12, v[56:57]
	v_cvt_pk_bf16_f32 v58, v58, v59
	v_cvt_pk_bf16_f32 v59, v60, v61
	v_lshl_add_u64 v[56:57], s[88:89], 0, v[56:57]
	v_add_u32_e32 v60, s97, v149
	v_mov_b32_e32 v61, v135
	v_lshl_add_u64 v[56:57], v[60:61], 1, v[56:57]
	v_add_co_u32_e32 v56, vcc, 0xfffff000, v56
	s_nop 1
	v_addc_co_u32_e32 v57, vcc, -1, v57, vcc
	global_store_dwordx2 v[56:57], v[58:59], off offset:-2304 nt

; __device__ __forceinline__ unsigned pk_bf16(float lo, float hi) { const f32x2 v = {lo, hi}; return __builtin_bit_cast(unsigned, __builtin_convertvector(v, b16x2)); }
; __device__ __forceinline__ float sigmoidf_(float x) { return __builtin_amdgcn_rcpf(1.0f + __expf(-x)); }
;     __device__ __forceinline__ void row(int r, int col32, int fq, const f32x4& a00, const f32x4& a01, const f32x4& a10, const f32x4& a11) const { half(r, col32, fq, a00, a01); half(r, col32 + HALF, fq, a10, a11); }
;     __device__ __forceinline__ void row(int r, int col32, int fq, const f32x4& a00, const f32x4& a01, const f32x4& a10, const f32x4& a11) const { half(r, col32, fq, a00, a01); half(r, col32 + HALF, fq, a10, a11); }
;     __device__ __forceinline__ void row(int r, int col32, int fq, const f32x4& a00, const f32x4& a01, const f32x4& a10, const f32x4& a11) const { half(r, col32, fq, a00, a01); half(r, col32 + HALF, fq, a10, a11); }
;     __device__ __forceinline__ void one(int row, int col, const f32x4& v) const {
;         if (col < 1536) {
;             const int which = col >> 9, hc = col & 511, h = hc >> 6, d = hc & 63, b = row / TP, t = row - b * TP;
;             const float s = which == 0 ? 0.125f : 1.0f;
;             u32x2 w; w.x = pk_bf16(v[0] * s, v[1] * s); w.y = pk_bf16(v[2] * s, v[3] * s);
;             *(u32x2*)(qkv + (size_t)which * (QKV_ONE / 2) + ((size_t)(b * NH + h) * TP + t) * 64 + d) = w;
;         } else if (col < 3328) {
;             h16x4 o; o[0] = (_Float16)v[0]; o[1] = (_Float16)v[1]; o[2] = (_Float16)v[2]; o[3] = (_Float16)v[3];
;             *(h16x4*)(urw + (size_t)row * RWS + (col - 1536)) = o;
;         } else {
;             const int b = row / TP, t = row - b * TP;
;             if (t >= NMETA && t < T) {
;                 u32x2 w; w.x = pk_bf16(sigmoidf_(v[0]), sigmoidf_(v[1])); w.y = pk_bf16(sigmoidf_(v[2]), sigmoidf_(v[3]));
;                 *(u32x2*)(gates + (size_t)(b * SEQ + t - NMETA) * 2048 + (col - 3328)) = w;
;             }
;         }
.LBB0_361:
	s_andn2_b64 vcc, exec, s[34:35]
	s_cbranch_vccnz .LBB0_363
	v_mov_b64_e32 v[58:59], s[50:51]
	v_mad_i64_i32 v[58:59], s[34:35], v64, s73, v[58:59]
	v_add_u32_e32 v60, s97, v149
	v_mov_b32_e32 v61, v135
	v_cvt_pk_f16_f32 v57, v54, v55
	v_cvt_pk_f16_f32 v56, v52, v53
	v_lshl_add_u64 v[58:59], v[60:61], 1, v[58:59]
	global_store_dwordx2 v[58:59], v[56:57], off offset:-2816 nt
.LBB0_363:
	s_or_saveexec_b64 s[30:31], s[30:31]
	v_mul_hi_i32 v57, v64, s69
	v_lshrrev_b32_e32 v56, 31, v57
	v_ashrrev_i32_e32 v57, 12, v57
	s_xor_b64 exec, exec, s[30:31]
	s_cbranch_execz .LBB0_365
	v_add_u32_e32 v59, v57, v56
	v_mad_i32_i24 v58, v59, s72, v64
	v_pk_mul_f32 v[60:61], v[144:145], v[52:53] op_sel_hi:[0,1]
	v_pk_mul_f32 v[62:63], v[144:145], v[54:55] op_sel_hi:[0,1]
	v_lshl_or_b32 v59, v59, 3, s94
	v_cvt_pk_bf16_f32 v60, v60, v61
	v_cvt_pk_bf16_f32 v61, v62, v63
	v_mul_hi_i32_i24_e32 v63, 0x2080, v59
	v_mul_i32_i24_e32 v62, 0x2080, v59
	v_ashrrev_i32_e32 v59, 31, v58
	s_add_u32 s34, s50, s77
	v_lshl_add_u64 v[58:59], v[62:63], 0, v[58:59]
	s_addc_u32 s35, s51, s25
	v_lshlrev_b64 v[58:59], 7, v[58:59]
	v_lshl_add_u64 v[58:59], s[34:35], 0, v[58:59]
	v_lshlrev_b32_e32 v62, 1, v124
	v_mov_b32_e32 v63, v135
	v_lshl_add_u64 v[58:59], v[58:59], 0, v[62:63]
	global_store_dwordx2 v[58:59], v[60:61], off nt
.LBB0_365:
	s_or_b64 exec, exec, s[30:31]
	s_and_saveexec_b64 s[30:31], s[4:5]
	s_xor_b64 s[30:31], exec, s[30:31]
	s_cbranch_execz .LBB0_372
	s_andn2_b64 vcc, exec, s[0:1]
	s_mov_b64 s[34:35], -1
	s_cbranch_vccnz .LBB0_370
	v_add_u32_e32 v56, v57, v56
	v_mul_i32_i24_e32 v57, 0xffffdf80, v56
	v_add3_u32 v57, v57, v64, -16
	v_cmp_gt_u32_e32 vcc, s65, v57
	s_and_saveexec_b64 s[34:35], vcc
	s_cbranch_execz .LBB0_369
	v_mul_f32_e32 v58, 0xbfb8aa3b, v48
	v_mul_f32_e32 v59, 0xbfb8aa3b, v49
	v_exp_f32_e32 v58, v58
	v_exp_f32_e32 v59, v59
	v_mul_f32_e32 v60, 0xbfb8aa3b, v51
	v_exp_f32_e32 v60, v60
	v_add_f32_e32 v58, 1.0, v58
	v_add_f32_e32 v59, 1.0, v59
	v_rcp_f32_e32 v58, v58
	v_rcp_f32_e32 v59, v59
	v_lshl_add_u32 v56, v56, 13, v57
	v_add_f32_e32 v60, 1.0, v60
	v_ashrrev_i32_e32 v57, 31, v56
	v_cvt_pk_bf16_f32 v58, v58, v59
	v_mul_f32_e32 v59, 0xbfb8aa3b, v50
	v_exp_f32_e32 v59, v59
	v_rcp_f32_e32 v60, v60
	v_lshlrev_b64 v[56:57], 12, v[56:57]
	v_lshl_add_u64 v[56:57], s[88:89], 0, v[56:57]
	v_add_f32_e32 v59, 1.0, v59
	v_rcp_f32_e32 v59, v59
	v_lshl_add_u64 v[56:57], v[134:135], 1, v[56:57]
	v_add_co_u32_e32 v56, vcc, 0xfffff000, v56
	v_cvt_pk_bf16_f32 v59, v59, v60
	s_nop 0
	v_addc_co_u32_e32 v57, vcc, -1, v57, vcc
	global_store_dwordx2 v[56:57], v[58:59], off offset:-2272 nt

; __device__ __forceinline__ unsigned pk_bf16(float lo, float hi) { const f32x2 v = {lo, hi}; return __builtin_bit_cast(unsigned, __builtin_convertvector(v, b16x2)); }
;     __device__ __forceinline__ void row(int r, int col32, int fq, const f32x4& a00, const f32x4& a01, const f32x4& a10, const f32x4& a11) const { half(r, col32, fq, a00, a01); half(r, col32 + HALF, fq, a10, a11); }
;     __device__ __forceinline__ void row(int r, int col32, int fq, const f32x4& a00, const f32x4& a01, const f32x4& a10, const f32x4& a11) const { half(r, col32, fq, a00, a01); half(r, col32 + HALF, fq, a10, a11); }
;     __device__ __forceinline__ void row(int r, int col32, int fq, const f32x4& a00, const f32x4& a01, const f32x4& a10, const f32x4& a11) const { half(r, col32, fq, a00, a01); half(r, col32 + HALF, fq, a10, a11); }
;     __device__ __forceinline__ void one(int row, int col, const f32x4& v) const {
;         if (col < 1536) {
;             const int which = col >> 9, hc = col & 511, h = hc >> 6, d = hc & 63, b = row / TP, t = row - b * TP;
;             const float s = which == 0 ? 0.125f : 1.0f;
;             u32x2 w; w.x = pk_bf16(v[0] * s, v[1] * s); w.y = pk_bf16(v[2] * s, v[3] * s);
;             *(u32x2*)(qkv + (size_t)which * (QKV_ONE / 2) + ((size_t)(b * NH + h) * TP + t) * 64 + d) = w;
;         } else if (col < 3328) {
;             h16x4 o; o[0] = (_Float16)v[0]; o[1] = (_Float16)v[1]; o[2] = (_Float16)v[2]; o[3] = (_Float16)v[3];
;             *(h16x4*)(urw + (size_t)row * RWS + (col - 1536)) = o;
.LBB0_370:
	s_andn2_b64 vcc, exec, s[34:35]
	s_cbranch_vccnz .LBB0_372
	v_mov_b64_e32 v[58:59], s[50:51]
	v_mad_i64_i32 v[58:59], s[34:35], v64, s73, v[58:59]
	v_cvt_pk_f16_f32 v57, v50, v51
	v_cvt_pk_f16_f32 v56, v48, v49
	v_lshl_add_u64 v[58:59], v[134:135], 1, v[58:59]
	global_store_dwordx2 v[58:59], v[56:57], off offset:-2784 nt
.LBB0_372:
	s_andn2_saveexec_b64 s[30:31], s[30:31]
	s_cbranch_execz .LBB0_374
	v_add_u32_e32 v57, v57, v56
	v_mad_i32_i24 v56, v57, s72, v64
	v_pk_mul_f32 v[58:59], v[144:145], v[48:49] op_sel_hi:[0,1]
	v_pk_mul_f32 v[60:61], v[144:145], v[50:51] op_sel_hi:[0,1]
	v_lshl_or_b32 v57, v57, 3, v123
	v_cvt_pk_bf16_f32 v58, v58, v59
	v_cvt_pk_bf16_f32 v59, v60, v61
	v_mul_hi_i32_i24_e32 v61, 0x2080, v57
	v_mul_i32_i24_e32 v60, 0x2080, v57
	v_ashrrev_i32_e32 v57, 31, v56
	s_add_u32 s34, s50, s77
	v_lshl_add_u64 v[56:57], v[60:61], 0, v[56:57]
	s_addc_u32 s35, s51, s25
	v_lshlrev_b64 v[56:57], 7, v[56:57]
	v_lshl_add_u64 v[56:57], s[34:35], 0, v[56:57]
	v_lshlrev_b32_e32 v60, 1, v122
	v_mov_b32_e32 v61, v135
	v_lshl_add_u64 v[56:57], v[56:57], 0, v[60:61]
	global_store_dwordx2 v[56:57], v[58:59], off nt

; __device__ __forceinline__ unsigned pk_bf16(float lo, float hi) { const f32x2 v = {lo, hi}; return __builtin_bit_cast(unsigned, __builtin_convertvector(v, b16x2)); }
; __device__ __forceinline__ float sigmoidf_(float x) { return __builtin_amdgcn_rcpf(1.0f + __expf(-x)); }
;     __device__ __forceinline__ void row(int r, int col32, int fq, const f32x4& a00, const f32x4& a01, const f32x4& a10, const f32x4& a11) const { half(r, col32, fq, a00, a01); half(r, col32 + HALF, fq, a10, a11); }
;     __device__ __forceinline__ void row(int r, int col32, int fq, const f32x4& a00, const f32x4& a01, const f32x4& a10, const f32x4& a11) const { half(r, col32, fq, a00, a01); half(r, col32 + HALF, fq, a10, a11); }
;     __device__ __forceinline__ void row(int r, int col32, int fq, const f32x4& a00, const f32x4& a01, const f32x4& a10, const f32x4& a11) const { half(r, col32, fq, a00, a01); half(r, col32 + HALF, fq, a10, a11); }
;     __device__ __forceinline__ void one(int row, int col, const f32x4& v) const {
;     ...
;         } else {
;             const int b = row / TP, t = row - b * TP;
;             if (t >= NMETA && t < T) {
;                 u32x2 w; w.x = pk_bf16(sigmoidf_(v[0]), sigmoidf_(v[1])); w.y = pk_bf16(sigmoidf_(v[2]), sigmoidf_(v[3]));
;                 *(u32x2*)(gates + (size_t)(b * SEQ + t - NMETA) * 2048 + (col - 3328)) = w;
;             }
;     __device__ __forceinline__ void half(int row, int col32, int fq, const f32x4& v0, const f32x4& v1) const {
;     ...
;             if (col32 >= 1536 && col32 < 3072) {
;                 const int c = col32 - 1536, pos = (c & ~63) + fq * 16 + ((c & 63) >> 4) * 4;
;                 h16x8 o;
; #pragma unroll
;                 for (int j = 0; j < 4; ++j) { o[j] = (_Float16)v0[j]; o[4 + j] = (_Float16)v1[j]; }
;                 *(h16x8*)(urw + (size_t)row * RWS + pos) = o;
;             } else { one(row, col32 + 4 * fq, v0); one(row, col32 + 16 + 4 * fq, v1); }
.LBB0_375:
	s_and_b64 vcc, exec, s[30:31]
	s_cbranch_vccz .LBB0_355
	v_cvt_pk_f16_f32 v59, v58, v59
	v_cvt_pk_f16_f32 v58, v56, v57
	v_cvt_pk_f16_f32 v56, v60, v61
	v_mov_b64_e32 v[60:61], s[50:51]
	v_mad_i64_i32 v[60:61], s[30:31], v64, s73, v[60:61]
	v_cvt_pk_f16_f32 v57, v62, v63
	v_lshl_add_u64 v[60:61], v[146:147], 1, v[60:61]
	global_store_dwordx4 v[60:61], v[56:59], off nt
	s_and_b64 vcc, exec, s[14:15]
	s_mov_b64 s[30:31], -1
	s_cbranch_vccz .LBB0_356
.LBB0_377:
	s_and_b64 vcc, exec, s[30:31]
	s_cbranch_vccz .LBB0_379
	v_cvt_pk_f16_f32 v51, v50, v51
	v_cvt_pk_f16_f32 v50, v48, v49
	v_cvt_pk_f16_f32 v48, v52, v53
	v_mov_b64_e32 v[52:53], s[50:51]
	v_mad_i64_i32 v[52:53], s[30:31], v64, s73, v[52:53]
	v_cvt_pk_f16_f32 v49, v54, v55
	v_lshl_add_u64 v[52:53], v[120:121], 1, v[52:53]
	global_store_dwordx4 v[52:53], v[48:51], off nt
.LBB0_379:
	s_nop 1
	v_add_u32_e32 v48, 0x90, v175
	s_and_b64 vcc, exec, s[12:13]
	s_mov_b64 s[30:31], -1
	s_cbranch_vccnz .LBB0_419
	s_and_saveexec_b64 s[30:31], s[8:9]
	s_xor_b64 s[30:31], exec, s[30:31]
	s_cbranch_execz .LBB0_387
	s_andn2_b64 vcc, exec, s[0:1]
	s_mov_b64 s[34:35], -1
	s_cbranch_vccnz .LBB0_385
	v_mul_hi_i32 v49, v48, s69
	v_lshrrev_b32_e32 v50, 31, v49
	v_ashrrev_i32_e32 v49, 12, v49
	v_add_u32_e32 v49, v49, v50
	v_mul_i32_i24_e32 v50, 0xffffdf80, v49
	v_add3_u32 v50, v50, v48, -16
	v_cmp_gt_u32_e32 vcc, s65, v50
	s_and_saveexec_b64 s[34:35], vcc
	s_cbranch_execz .LBB0_384
	v_mul_f32_e32 v51, 0xbfb8aa3b, v44
	v_mul_f32_e32 v52, 0xbfb8aa3b, v45
	v_exp_f32_e32 v51, v51
	v_exp_f32_e32 v52, v52
	v_mul_f32_e32 v53, 0xbfb8aa3b, v47
	v_exp_f32_e32 v53, v53
	v_add_f32_e32 v51, 1.0, v51
	v_add_f32_e32 v52, 1.0, v52
	v_rcp_f32_e32 v51, v51
	v_rcp_f32_e32 v52, v52
	v_add_f32_e32 v53, 1.0, v53
	v_rcp_f32_e32 v53, v53
	v_lshl_add_u32 v50, v49, 13, v50
	v_cvt_pk_bf16_f32 v52, v51, v52
	v_mul_f32_e32 v51, 0xbfb8aa3b, v46
	v_exp_f32_e32 v51, v51
	s_nop 0
	v_add_f32_e32 v51, 1.0, v51
	v_rcp_f32_e32 v51, v51
	s_nop 0
	v_cvt_pk_bf16_f32 v53, v51, v53
	v_ashrrev_i32_e32 v51, 31, v50
	v_lshlrev_b64 v[50:51], 12, v[50:51]
	v_lshl_add_u64 v[50:51], s[88:89], 0, v[50:51]
	v_lshl_add_u64 v[50:51], v[134:135], 1, v[50:51]
	v_add_co_u32_e32 v50, vcc, 0xfffff000, v50
	s_nop 1
	v_addc_co_u32_e32 v51, vcc, -1, v51, vcc
	global_store_dwordx2 v[50:51], v[52:53], off offset:-2560 nt

; __device__ __forceinline__ unsigned pk_bf16(float lo, float hi) { const f32x2 v = {lo, hi}; return __builtin_bit_cast(unsigned, __builtin_convertvector(v, b16x2)); }
; __device__ __forceinline__ float sigmoidf_(float x) { return __builtin_amdgcn_rcpf(1.0f + __expf(-x)); }
;     __device__ __forceinline__ void row(int r, int col32, int fq, const f32x4& a00, const f32x4& a01, const f32x4& a10, const f32x4& a11) const { half(r, col32, fq, a00, a01); half(r, col32 + HALF, fq, a10, a11); }
;     __device__ __forceinline__ void row(int r, int col32, int fq, const f32x4& a00, const f32x4& a01, const f32x4& a10, const f32x4& a11) const { half(r, col32, fq, a00, a01); half(r, col32 + HALF, fq, a10, a11); }
;     __device__ __forceinline__ void row(int r, int col32, int fq, const f32x4& a00, const f32x4& a01, const f32x4& a10, const f32x4& a11) const { half(r, col32, fq, a00, a01); half(r, col32 + HALF, fq, a10, a11); }
;     __device__ __forceinline__ void one(int row, int col, const f32x4& v) const {
;         if (col < 1536) {
;             const int which = col >> 9, hc = col & 511, h = hc >> 6, d = hc & 63, b = row / TP, t = row - b * TP;
;             const float s = which == 0 ? 0.125f : 1.0f;
;             u32x2 w; w.x = pk_bf16(v[0] * s, v[1] * s); w.y = pk_bf16(v[2] * s, v[3] * s);
;             *(u32x2*)(qkv + (size_t)which * (QKV_ONE / 2) + ((size_t)(b * NH + h) * TP + t) * 64 + d) = w;
;         } else if (col < 3328) {
;             h16x4 o; o[0] = (_Float16)v[0]; o[1] = (_Float16)v[1]; o[2] = (_Float16)v[2]; o[3] = (_Float16)v[3];
;             *(h16x4*)(urw + (size_t)row * RWS + (col - 1536)) = o;
;         } else {
;             const int b = row / TP, t = row - b * TP;
;             if (t >= NMETA && t < T) {
;                 u32x2 w; w.x = pk_bf16(sigmoidf_(v[0]), sigmoidf_(v[1])); w.y = pk_bf16(sigmoidf_(v[2]), sigmoidf_(v[3]));
;                 *(u32x2*)(gates + (size_t)(b * SEQ + t - NMETA) * 2048 + (col - 3328)) = w;
;             }
;         }
.LBB0_385:
	s_andn2_b64 vcc, exec, s[34:35]
	s_cbranch_vccnz .LBB0_387
	v_mov_b64_e32 v[52:53], s[50:51]
	v_mad_i64_i32 v[52:53], s[34:35], v48, s73, v[52:53]
	v_cvt_pk_f16_f32 v51, v46, v47
	v_cvt_pk_f16_f32 v50, v44, v45
	v_lshl_add_u64 v[52:53], v[134:135], 1, v[52:53]
	global_store_dwordx2 v[52:53], v[50:51], off offset:-3072 nt
.LBB0_387:
	s_andn2_saveexec_b64 s[30:31], s[30:31]
	s_cbranch_execz .LBB0_389
	v_mul_hi_i32 v49, v48, s69
	v_lshrrev_b32_e32 v50, 31, v49
	v_ashrrev_i32_e32 v49, 12, v49
	v_add_u32_e32 v49, v49, v50
	v_mad_i32_i24 v50, v49, s72, v48
	v_pk_mul_f32 v[52:53], v[144:145], v[44:45] op_sel_hi:[0,1]
	v_pk_mul_f32 v[54:55], v[144:145], v[46:47] op_sel_hi:[0,1]
	v_lshl_or_b32 v49, v49, 3, s96
	v_cvt_pk_bf16_f32 v52, v52, v53
	v_cvt_pk_bf16_f32 v53, v54, v55
	v_mul_hi_i32_i24_e32 v55, 0x2080, v49
	v_mul_i32_i24_e32 v54, 0x2080, v49
	v_ashrrev_i32_e32 v51, 31, v50
	s_add_u32 s34, s50, s77
	v_lshl_add_u64 v[50:51], v[54:55], 0, v[50:51]
	s_addc_u32 s35, s51, s25
	v_lshlrev_b64 v[50:51], 7, v[50:51]
	v_lshl_add_u64 v[50:51], s[34:35], 0, v[50:51]
	v_lshlrev_b32_e32 v54, 1, v174
	v_mov_b32_e32 v55, v135
	v_lshl_add_u64 v[50:51], v[50:51], 0, v[54:55]
	global_store_dwordx2 v[50:51], v[52:53], off nt
.LBB0_389:
	s_or_b64 exec, exec, s[30:31]
	s_and_saveexec_b64 s[30:31], s[6:7]
	s_xor_b64 s[30:31], exec, s[30:31]
	s_cbranch_execz .LBB0_396
	s_andn2_b64 vcc, exec, s[0:1]
	s_mov_b64 s[34:35], -1
	s_cbranch_vccnz .LBB0_394
	v_mul_hi_i32 v49, v48, s69
	v_lshrrev_b32_e32 v50, 31, v49
	v_ashrrev_i32_e32 v49, 12, v49
	v_add_u32_e32 v49, v49, v50
	v_mul_i32_i24_e32 v50, 0xffffdf80, v49
	v_add3_u32 v50, v50, v48, -16
	v_cmp_gt_u32_e32 vcc, s65, v50
	s_and_saveexec_b64 s[34:35], vcc
	s_cbranch_execz .LBB0_393
	v_mul_f32_e32 v51, 0xbfb8aa3b, v40
	v_mul_f32_e32 v52, 0xbfb8aa3b, v41
	v_exp_f32_e32 v51, v51
	v_exp_f32_e32 v52, v52
	v_mul_f32_e32 v53, 0xbfb8aa3b, v43
	v_exp_f32_e32 v53, v53
	v_add_f32_e32 v51, 1.0, v51
	v_add_f32_e32 v52, 1.0, v52
	v_rcp_f32_e32 v51, v51
	v_rcp_f32_e32 v52, v52
	v_add_f32_e32 v53, 1.0, v53
	v_rcp_f32_e32 v53, v53
	v_lshl_add_u32 v50, v49, 13, v50
	v_cvt_pk_bf16_f32 v52, v51, v52
	v_mul_f32_e32 v51, 0xbfb8aa3b, v42
	v_exp_f32_e32 v51, v51
	s_nop 0
	v_add_f32_e32 v51, 1.0, v51
	v_rcp_f32_e32 v51, v51
	s_nop 0
	v_cvt_pk_bf16_f32 v53, v51, v53
	v_ashrrev_i32_e32 v51, 31, v50
	v_lshlrev_b64 v[50:51], 12, v[50:51]
	v_lshl_add_u64 v[50:51], s[88:89], 0, v[50:51]
	v_lshl_add_u64 v[50:51], v[134:135], 1, v[50:51]
	v_add_co_u32_e32 v50, vcc, 0xfffff000, v50
	s_nop 1
	v_addc_co_u32_e32 v51, vcc, -1, v51, vcc
	global_store_dwordx2 v[50:51], v[52:53], off offset:-2528 nt

; __device__ __forceinline__ unsigned pk_bf16(float lo, float hi) { const f32x2 v = {lo, hi}; return __builtin_bit_cast(unsigned, __builtin_convertvector(v, b16x2)); }
;     __device__ __forceinline__ void row(int r, int col32, int fq, const f32x4& a00, const f32x4& a01, const f32x4& a10, const f32x4& a11) const { half(r, col32, fq, a00, a01); half(r, col32 + HALF, fq, a10, a11); }
;     __device__ __forceinline__ void row(int r, int col32, int fq, const f32x4& a00, const f32x4& a01, const f32x4& a10, const f32x4& a11) const { half(r, col32, fq, a00, a01); half(r, col32 + HALF, fq, a10, a11); }
;     __device__ __forceinline__ void row(int r, int col32, int fq, const f32x4& a00, const f32x4& a01, const f32x4& a10, const f32x4& a11) const { half(r, col32, fq, a00, a01); half(r, col32 + HALF, fq, a10, a11); }
;     __device__ __forceinline__ void one(int row, int col, const f32x4& v) const {
;         if (col < 1536) {
;             const int which = col >> 9, hc = col & 511, h = hc >> 6, d = hc & 63, b = row / TP, t = row - b * TP;
;             const float s = which == 0 ? 0.125f : 1.0f;
;             u32x2 w; w.x = pk_bf16(v[0] * s, v[1] * s); w.y = pk_bf16(v[2] * s, v[3] * s);
;             *(u32x2*)(qkv + (size_t)which * (QKV_ONE / 2) + ((size_t)(b * NH + h) * TP + t) * 64 + d) = w;
;         } else if (col < 3328) {
;             h16x4 o; o[0] = (_Float16)v[0]; o[1] = (_Float16)v[1]; o[2] = (_Float16)v[2]; o[3] = (_Float16)v[3];
;             *(h16x4*)(urw + (size_t)row * RWS + (col - 1536)) = o;
.LBB0_394:
	s_andn2_b64 vcc, exec, s[34:35]
	s_cbranch_vccnz .LBB0_396
	v_mov_b64_e32 v[52:53], s[50:51]
	v_mad_i64_i32 v[52:53], s[34:35], v48, s73, v[52:53]
	v_cvt_pk_f16_f32 v51, v42, v43
	v_cvt_pk_f16_f32 v50, v40, v41
	v_lshl_add_u64 v[52:53], v[134:135], 1, v[52:53]
	global_store_dwordx2 v[52:53], v[50:51], off offset:-3040 nt
.LBB0_396:
	s_andn2_saveexec_b64 s[30:31], s[30:31]
	s_cbranch_execz .LBB0_398
	v_mul_hi_i32 v49, v48, s69
	v_lshrrev_b32_e32 v50, 31, v49
	v_ashrrev_i32_e32 v49, 12, v49
	v_add_u32_e32 v49, v49, v50
	v_mad_i32_i24 v50, v49, s72, v48
	v_pk_mul_f32 v[52:53], v[144:145], v[40:41] op_sel_hi:[0,1]
	v_pk_mul_f32 v[54:55], v[144:145], v[42:43] op_sel_hi:[0,1]
	v_lshl_or_b32 v49, v49, 3, s96
	v_cvt_pk_bf16_f32 v52, v52, v53
	v_cvt_pk_bf16_f32 v53, v54, v55
	v_mul_hi_i32_i24_e32 v55, 0x2080, v49
	v_mul_i32_i24_e32 v54, 0x2080, v49
	v_ashrrev_i32_e32 v51, 31, v50
	s_add_u32 s34, s50, s77
	v_lshl_add_u64 v[50:51], v[54:55], 0, v[50:51]
	s_addc_u32 s35, s51, s25
	v_lshlrev_b64 v[50:51], 7, v[50:51]
	v_lshl_add_u64 v[50:51], s[34:35], 0, v[50:51]
	v_lshlrev_b32_e32 v54, 1, v173
	v_mov_b32_e32 v55, v135
	v_lshl_add_u64 v[50:51], v[50:51], 0, v[54:55]
	global_store_dwordx2 v[50:51], v[52:53], off nt

; __device__ __forceinline__ unsigned pk_bf16(float lo, float hi) { const f32x2 v = {lo, hi}; return __builtin_bit_cast(unsigned, __builtin_convertvector(v, b16x2)); }
; __device__ __forceinline__ float sigmoidf_(float x) { return __builtin_amdgcn_rcpf(1.0f + __expf(-x)); }
;     __device__ __forceinline__ void row(int r, int col32, int fq, const f32x4& a00, const f32x4& a01, const f32x4& a10, const f32x4& a11) const { half(r, col32, fq, a00, a01); half(r, col32 + HALF, fq, a10, a11); }
;     __device__ __forceinline__ void row(int r, int col32, int fq, const f32x4& a00, const f32x4& a01, const f32x4& a10, const f32x4& a11) const { half(r, col32, fq, a00, a01); half(r, col32 + HALF, fq, a10, a11); }
;     __device__ __forceinline__ void row(int r, int col32, int fq, const f32x4& a00, const f32x4& a01, const f32x4& a10, const f32x4& a11) const { half(r, col32, fq, a00, a01); half(r, col32 + HALF, fq, a10, a11); }
;     __device__ __forceinline__ void one(int row, int col, const f32x4& v) const {
;     ...
;         } else {
;             const int b = row / TP, t = row - b * TP;
;             if (t >= NMETA && t < T) {
;                 u32x2 w; w.x = pk_bf16(sigmoidf_(v[0]), sigmoidf_(v[1])); w.y = pk_bf16(sigmoidf_(v[2]), sigmoidf_(v[3]));
;                 *(u32x2*)(gates + (size_t)(b * SEQ + t - NMETA) * 2048 + (col - 3328)) = w;
;             }
.LBB0_400:
	s_and_saveexec_b64 s[30:31], s[10:11]
	s_xor_b64 s[30:31], exec, s[30:31]
	s_cbranch_execz .LBB0_407
	s_andn2_b64 vcc, exec, s[0:1]
	s_mov_b64 s[34:35], -1
	s_cbranch_vccnz .LBB0_405
	v_mul_hi_i32 v40, v48, s69
	v_lshrrev_b32_e32 v41, 31, v40
	v_ashrrev_i32_e32 v40, 12, v40
	v_add_u32_e32 v40, v40, v41
	v_mul_i32_i24_e32 v41, 0xffffdf80, v40
	v_add3_u32 v41, v41, v48, -16
	v_cmp_gt_u32_e32 vcc, s65, v41
	s_and_saveexec_b64 s[34:35], vcc
	s_cbranch_execz .LBB0_404
	v_mul_f32_e32 v42, 0xbfb8aa3b, v36
	v_mul_f32_e32 v43, 0xbfb8aa3b, v37
	v_mul_f32_e32 v44, 0xbfb8aa3b, v38
	v_mul_f32_e32 v45, 0xbfb8aa3b, v39
	v_exp_f32_e32 v42, v42
	v_exp_f32_e32 v43, v43
	v_exp_f32_e32 v44, v44
	v_exp_f32_e32 v45, v45
	v_add_f32_e32 v42, 1.0, v42
	v_add_f32_e32 v43, 1.0, v43
	v_add_f32_e32 v44, 1.0, v44
	v_add_f32_e32 v45, 1.0, v45
	v_rcp_f32_e32 v42, v42
	v_rcp_f32_e32 v43, v43
	v_rcp_f32_e32 v44, v44
	v_rcp_f32_e32 v45, v45
	v_lshl_add_u32 v40, v40, 13, v41
	v_ashrrev_i32_e32 v41, 31, v40
	v_lshlrev_b64 v[40:41], 12, v[40:41]
	v_cvt_pk_bf16_f32 v42, v42, v43
	v_cvt_pk_bf16_f32 v43, v44, v45
	v_lshl_add_u64 v[40:41], s[88:89], 0, v[40:41]
	v_add_u32_e32 v44, s97, v149
	v_mov_b32_e32 v45, v135
	v_lshl_add_u64 v[40:41], v[44:45], 1, v[40:41]
	v_add_co_u32_e32 v40, vcc, 0xfffff000, v40
	s_nop 1
	v_addc_co_u32_e32 v41, vcc, -1, v41, vcc
	global_store_dwordx2 v[40:41], v[42:43], off offset:-2304 nt

; __device__ __forceinline__ unsigned pk_bf16(float lo, float hi) { const f32x2 v = {lo, hi}; return __builtin_bit_cast(unsigned, __builtin_convertvector(v, b16x2)); }
; __device__ __forceinline__ float sigmoidf_(float x) { return __builtin_amdgcn_rcpf(1.0f + __expf(-x)); }
;     __device__ __forceinline__ void row(int r, int col32, int fq, const f32x4& a00, const f32x4& a01, const f32x4& a10, const f32x4& a11) const { half(r, col32, fq, a00, a01); half(r, col32 + HALF, fq, a10, a11); }
;     __device__ __forceinline__ void row(int r, int col32, int fq, const f32x4& a00, const f32x4& a01, const f32x4& a10, const f32x4& a11) const { half(r, col32, fq, a00, a01); half(r, col32 + HALF, fq, a10, a11); }
;     __device__ __forceinline__ void row(int r, int col32, int fq, const f32x4& a00, const f32x4& a01, const f32x4& a10, const f32x4& a11) const { half(r, col32, fq, a00, a01); half(r, col32 + HALF, fq, a10, a11); }
;     __device__ __forceinline__ void one(int row, int col, const f32x4& v) const {
;         if (col < 1536) {
;             const int which = col >> 9, hc = col & 511, h = hc >> 6, d = hc & 63, b = row / TP, t = row - b * TP;
;             const float s = which == 0 ? 0.125f : 1.0f;
;             u32x2 w; w.x = pk_bf16(v[0] * s, v[1] * s); w.y = pk_bf16(v[2] * s, v[3] * s);
;             *(u32x2*)(qkv + (size_t)which * (QKV_ONE / 2) + ((size_t)(b * NH + h) * TP + t) * 64 + d) = w;
;         } else if (col < 3328) {
;             h16x4 o; o[0] = (_Float16)v[0]; o[1] = (_Float16)v[1]; o[2] = (_Float16)v[2]; o[3] = (_Float16)v[3];
;             *(h16x4*)(urw + (size_t)row * RWS + (col - 1536)) = o;
;         } else {
;             const int b = row / TP, t = row - b * TP;
;             if (t >= NMETA && t < T) {
;                 u32x2 w; w.x = pk_bf16(sigmoidf_(v[0]), sigmoidf_(v[1])); w.y = pk_bf16(sigmoidf_(v[2]), sigmoidf_(v[3]));
;                 *(u32x2*)(gates + (size_t)(b * SEQ + t - NMETA) * 2048 + (col - 3328)) = w;
;             }
;         }
.LBB0_405:
	s_andn2_b64 vcc, exec, s[34:35]
	s_cbranch_vccnz .LBB0_407
	v_mov_b64_e32 v[42:43], s[50:51]
	v_mad_i64_i32 v[42:43], s[34:35], v48, s73, v[42:43]
	v_add_u32_e32 v44, s97, v149
	v_mov_b32_e32 v45, v135
	v_cvt_pk_f16_f32 v41, v38, v39
	v_cvt_pk_f16_f32 v40, v36, v37
	v_lshl_add_u64 v[42:43], v[44:45], 1, v[42:43]
	global_store_dwordx2 v[42:43], v[40:41], off offset:-2816 nt
.LBB0_407:
	s_or_saveexec_b64 s[30:31], s[30:31]
	v_mul_hi_i32 v41, v48, s69
	v_lshrrev_b32_e32 v40, 31, v41
	v_ashrrev_i32_e32 v41, 12, v41
	s_xor_b64 exec, exec, s[30:31]
	s_cbranch_execz .LBB0_409
	v_add_u32_e32 v43, v41, v40
	v_mad_i32_i24 v42, v43, s72, v48
	v_pk_mul_f32 v[44:45], v[144:145], v[36:37] op_sel_hi:[0,1]
	v_pk_mul_f32 v[46:47], v[144:145], v[38:39] op_sel_hi:[0,1]
	v_lshl_or_b32 v43, v43, 3, s94
	v_cvt_pk_bf16_f32 v44, v44, v45
	v_cvt_pk_bf16_f32 v45, v46, v47
	v_mul_hi_i32_i24_e32 v47, 0x2080, v43
	v_mul_i32_i24_e32 v46, 0x2080, v43
	v_ashrrev_i32_e32 v43, 31, v42
	s_add_u32 s34, s50, s77
	v_lshl_add_u64 v[42:43], v[46:47], 0, v[42:43]
	s_addc_u32 s35, s51, s25
	v_lshlrev_b64 v[42:43], 7, v[42:43]
	v_lshl_add_u64 v[42:43], s[34:35], 0, v[42:43]
	v_lshlrev_b32_e32 v46, 1, v124
	v_mov_b32_e32 v47, v135
	v_lshl_add_u64 v[42:43], v[42:43], 0, v[46:47]
	global_store_dwordx2 v[42:43], v[44:45], off nt
.LBB0_409:
	s_or_b64 exec, exec, s[30:31]
	s_and_saveexec_b64 s[30:31], s[4:5]
	s_xor_b64 s[30:31], exec, s[30:31]
	s_cbranch_execz .LBB0_416
	s_andn2_b64 vcc, exec, s[0:1]
	s_mov_b64 s[34:35], -1
	s_cbranch_vccnz .LBB0_414
	v_add_u32_e32 v40, v41, v40
	v_mul_i32_i24_e32 v41, 0xffffdf80, v40
	v_add3_u32 v41, v41, v48, -16
	v_cmp_gt_u32_e32 vcc, s65, v41
	s_and_saveexec_b64 s[34:35], vcc
	s_cbranch_execz .LBB0_413
	v_mul_f32_e32 v42, 0xbfb8aa3b, v32
	v_mul_f32_e32 v43, 0xbfb8aa3b, v33
	v_exp_f32_e32 v42, v42
	v_exp_f32_e32 v43, v43
	v_mul_f32_e32 v44, 0xbfb8aa3b, v35
	v_exp_f32_e32 v44, v44
	v_add_f32_e32 v42, 1.0, v42
	v_add_f32_e32 v43, 1.0, v43
	v_rcp_f32_e32 v42, v42
	v_rcp_f32_e32 v43, v43
	v_lshl_add_u32 v40, v40, 13, v41
	v_add_f32_e32 v44, 1.0, v44
	v_ashrrev_i32_e32 v41, 31, v40
	v_cvt_pk_bf16_f32 v42, v42, v43
	v_mul_f32_e32 v43, 0xbfb8aa3b, v34
	v_exp_f32_e32 v43, v43
	v_rcp_f32_e32 v44, v44
	v_lshlrev_b64 v[40:41], 12, v[40:41]
	v_lshl_add_u64 v[40:41], s[88:89], 0, v[40:41]
	v_add_f32_e32 v43, 1.0, v43
	v_rcp_f32_e32 v43, v43
	v_lshl_add_u64 v[40:41], v[134:135], 1, v[40:41]
	v_add_co_u32_e32 v40, vcc, 0xfffff000, v40
	v_cvt_pk_bf16_f32 v43, v43, v44
	s_nop 0
	v_addc_co_u32_e32 v41, vcc, -1, v41, vcc
	global_store_dwordx2 v[40:41], v[42:43], off offset:-2272 nt

; __device__ __forceinline__ unsigned pk_bf16(float lo, float hi) { const f32x2 v = {lo, hi}; return __builtin_bit_cast(unsigned, __builtin_convertvector(v, b16x2)); }
;     __device__ __forceinline__ void row(int r, int col32, int fq, const f32x4& a00, const f32x4& a01, const f32x4& a10, const f32x4& a11) const { half(r, col32, fq, a00, a01); half(r, col32 + HALF, fq, a10, a11); }
;     __device__ __forceinline__ void row(int r, int col32, int fq, const f32x4& a00, const f32x4& a01, const f32x4& a10, const f32x4& a11) const { half(r, col32, fq, a00, a01); half(r, col32 + HALF, fq, a10, a11); }
;     __device__ __forceinline__ void row(int r, int col32, int fq, const f32x4& a00, const f32x4& a01, const f32x4& a10, const f32x4& a11) const { half(r, col32, fq, a00, a01); half(r, col32 + HALF, fq, a10, a11); }
;     __device__ __forceinline__ void one(int row, int col, const f32x4& v) const {
;         if (col < 1536) {
;             const int which = col >> 9, hc = col & 511, h = hc >> 6, d = hc & 63, b = row / TP, t = row - b * TP;
;             const float s = which == 0 ? 0.125f : 1.0f;
;             u32x2 w; w.x = pk_bf16(v[0] * s, v[1] * s); w.y = pk_bf16(v[2] * s, v[3] * s);
;             *(u32x2*)(qkv + (size_t)which * (QKV_ONE / 2) + ((size_t)(b * NH + h) * TP + t) * 64 + d) = w;
;         } else if (col < 3328) {
;             h16x4 o; o[0] = (_Float16)v[0]; o[1] = (_Float16)v[1]; o[2] = (_Float16)v[2]; o[3] = (_Float16)v[3];
;             *(h16x4*)(urw + (size_t)row * RWS + (col - 1536)) = o;
.LBB0_414:
	s_andn2_b64 vcc, exec, s[34:35]
	s_cbranch_vccnz .LBB0_416
	v_mov_b64_e32 v[42:43], s[50:51]
	v_mad_i64_i32 v[42:43], s[34:35], v48, s73, v[42:43]
	v_cvt_pk_f16_f32 v41, v34, v35
	v_cvt_pk_f16_f32 v40, v32, v33
	v_lshl_add_u64 v[42:43], v[134:135], 1, v[42:43]
	global_store_dwordx2 v[42:43], v[40:41], off offset:-2784 nt
.LBB0_416:
	s_andn2_saveexec_b64 s[30:31], s[30:31]
	s_cbranch_execz .LBB0_418
	v_add_u32_e32 v41, v41, v40
	v_mad_i32_i24 v40, v41, s72, v48
	v_pk_mul_f32 v[42:43], v[144:145], v[32:33] op_sel_hi:[0,1]
	v_pk_mul_f32 v[44:45], v[144:145], v[34:35] op_sel_hi:[0,1]
	v_lshl_or_b32 v41, v41, 3, v123
	v_cvt_pk_bf16_f32 v42, v42, v43
	v_cvt_pk_bf16_f32 v43, v44, v45
	v_mul_hi_i32_i24_e32 v45, 0x2080, v41
	v_mul_i32_i24_e32 v44, 0x2080, v41
	v_ashrrev_i32_e32 v41, 31, v40
	s_add_u32 s34, s50, s77
	v_lshl_add_u64 v[40:41], v[44:45], 0, v[40:41]
	s_addc_u32 s35, s51, s25
	v_lshlrev_b64 v[40:41], 7, v[40:41]
	v_lshl_add_u64 v[40:41], s[34:35], 0, v[40:41]
	v_lshlrev_b32_e32 v44, 1, v122
	v_mov_b32_e32 v45, v135
	v_lshl_add_u64 v[40:41], v[40:41], 0, v[44:45]
	global_store_dwordx2 v[40:41], v[42:43], off nt

; __device__ __forceinline__ unsigned pk_bf16(float lo, float hi) { const f32x2 v = {lo, hi}; return __builtin_bit_cast(unsigned, __builtin_convertvector(v, b16x2)); }
; __device__ __forceinline__ float sigmoidf_(float x) { return __builtin_amdgcn_rcpf(1.0f + __expf(-x)); }
;     __device__ __forceinline__ void row(int r, int col32, int fq, const f32x4& a00, const f32x4& a01, const f32x4& a10, const f32x4& a11) const { half(r, col32, fq, a00, a01); half(r, col32 + HALF, fq, a10, a11); }
;     __device__ __forceinline__ void row(int r, int col32, int fq, const f32x4& a00, const f32x4& a01, const f32x4& a10, const f32x4& a11) const { half(r, col32, fq, a00, a01); half(r, col32 + HALF, fq, a10, a11); }
;     __device__ __forceinline__ void row(int r, int col32, int fq, const f32x4& a00, const f32x4& a01, const f32x4& a10, const f32x4& a11) const { half(r, col32, fq, a00, a01); half(r, col32 + HALF, fq, a10, a11); }
;     __device__ __forceinline__ void one(int row, int col, const f32x4& v) const {
;     ...
;         } else {
;             const int b = row / TP, t = row - b * TP;
;             if (t >= NMETA && t < T) {
;                 u32x2 w; w.x = pk_bf16(sigmoidf_(v[0]), sigmoidf_(v[1])); w.y = pk_bf16(sigmoidf_(v[2]), sigmoidf_(v[3]));
;                 *(u32x2*)(gates + (size_t)(b * SEQ + t - NMETA) * 2048 + (col - 3328)) = w;
;             }
;     __device__ __forceinline__ void half(int row, int col32, int fq, const f32x4& v0, const f32x4& v1) const {
;     ...
;             if (col32 >= 1536 && col32 < 3072) {
;                 const int c = col32 - 1536, pos = (c & ~63) + fq * 16 + ((c & 63) >> 4) * 4;
;                 h16x8 o;
; #pragma unroll
;                 for (int j = 0; j < 4; ++j) { o[j] = (_Float16)v0[j]; o[4 + j] = (_Float16)v1[j]; }
;                 *(h16x8*)(urw + (size_t)row * RWS + pos) = o;
;             } else { one(row, col32 + 4 * fq, v0); one(row, col32 + 16 + 4 * fq, v1); }
.LBB0_419:
	s_and_b64 vcc, exec, s[30:31]
	s_cbranch_vccz .LBB0_399
	v_cvt_pk_f16_f32 v43, v42, v43
	v_cvt_pk_f16_f32 v42, v40, v41
	v_cvt_pk_f16_f32 v40, v44, v45
	v_mov_b64_e32 v[44:45], s[50:51]
	v_mad_i64_i32 v[44:45], s[30:31], v48, s73, v[44:45]
	v_cvt_pk_f16_f32 v41, v46, v47
	v_lshl_add_u64 v[44:45], v[146:147], 1, v[44:45]
	global_store_dwordx4 v[44:45], v[40:43], off nt
	s_and_b64 vcc, exec, s[14:15]
	s_mov_b64 s[30:31], -1
	s_cbranch_vccz .LBB0_400
.LBB0_421:
	s_and_b64 vcc, exec, s[30:31]
	s_cbranch_vccz .LBB0_423
	v_cvt_pk_f16_f32 v35, v34, v35
	v_cvt_pk_f16_f32 v34, v32, v33
	v_cvt_pk_f16_f32 v32, v36, v37
	v_mov_b64_e32 v[36:37], s[50:51]
	v_mad_i64_i32 v[36:37], s[30:31], v48, s73, v[36:37]
	v_cvt_pk_f16_f32 v33, v38, v39
	v_lshl_add_u64 v[36:37], v[120:121], 1, v[36:37]
	global_store_dwordx4 v[36:37], v[32:35], off nt
.LBB0_423:
	s_nop 1
	v_add_u32_e32 v32, 0xa0, v175
	s_and_b64 vcc, exec, s[12:13]
	s_mov_b64 s[30:31], -1
	s_cbranch_vccnz .LBB0_463
	s_and_saveexec_b64 s[30:31], s[8:9]
	s_xor_b64 s[30:31], exec, s[30:31]
	s_cbranch_execz .LBB0_431
	s_andn2_b64 vcc, exec, s[0:1]
	s_mov_b64 s[34:35], -1
	s_cbranch_vccnz .LBB0_429
	v_mul_hi_i32 v33, v32, s69
	v_lshrrev_b32_e32 v34, 31, v33
	v_ashrrev_i32_e32 v33, 12, v33
	v_add_u32_e32 v33, v33, v34
	v_mul_i32_i24_e32 v34, 0xffffdf80, v33
	v_add3_u32 v34, v34, v32, -16
	v_cmp_gt_u32_e32 vcc, s65, v34
	s_and_saveexec_b64 s[34:35], vcc
	s_cbranch_execz .LBB0_428
	v_mul_f32_e32 v35, 0xbfb8aa3b, v28
	v_mul_f32_e32 v36, 0xbfb8aa3b, v29
	v_exp_f32_e32 v35, v35
	v_exp_f32_e32 v36, v36
	v_mul_f32_e32 v37, 0xbfb8aa3b, v31
	v_exp_f32_e32 v37, v37
	v_add_f32_e32 v35, 1.0, v35
	v_add_f32_e32 v36, 1.0, v36
	v_rcp_f32_e32 v35, v35
	v_rcp_f32_e32 v36, v36
	v_add_f32_e32 v37, 1.0, v37
	v_rcp_f32_e32 v37, v37
	v_lshl_add_u32 v34, v33, 13, v34
	v_cvt_pk_bf16_f32 v36, v35, v36
	v_mul_f32_e32 v35, 0xbfb8aa3b, v30
	v_exp_f32_e32 v35, v35
	s_nop 0
	v_add_f32_e32 v35, 1.0, v35
	v_rcp_f32_e32 v35, v35
	s_nop 0
	v_cvt_pk_bf16_f32 v37, v35, v37
	v_ashrrev_i32_e32 v35, 31, v34
	v_lshlrev_b64 v[34:35], 12, v[34:35]
	v_lshl_add_u64 v[34:35], s[88:89], 0, v[34:35]
	v_lshl_add_u64 v[34:35], v[134:135], 1, v[34:35]
	v_add_co_u32_e32 v34, vcc, 0xfffff000, v34
	s_nop 1
	v_addc_co_u32_e32 v35, vcc, -1, v35, vcc
	global_store_dwordx2 v[34:35], v[36:37], off offset:-2560 nt

; __device__ __forceinline__ unsigned pk_bf16(float lo, float hi) { const f32x2 v = {lo, hi}; return __builtin_bit_cast(unsigned, __builtin_convertvector(v, b16x2)); }
; __device__ __forceinline__ float sigmoidf_(float x) { return __builtin_amdgcn_rcpf(1.0f + __expf(-x)); }
;     __device__ __forceinline__ void row(int r, int col32, int fq, const f32x4& a00, const f32x4& a01, const f32x4& a10, const f32x4& a11) const { half(r, col32, fq, a00, a01); half(r, col32 + HALF, fq, a10, a11); }
;     __device__ __forceinline__ void row(int r, int col32, int fq, const f32x4& a00, const f32x4& a01, const f32x4& a10, const f32x4& a11) const { half(r, col32, fq, a00, a01); half(r, col32 + HALF, fq, a10, a11); }
;     __device__ __forceinline__ void row(int r, int col32, int fq, const f32x4& a00, const f32x4& a01, const f32x4& a10, const f32x4& a11) const { half(r, col32, fq, a00, a01); half(r, col32 + HALF, fq, a10, a11); }
;     __device__ __forceinline__ void one(int row, int col, const f32x4& v) const {
;         if (col < 1536) {
;             const int which = col >> 9, hc = col & 511, h = hc >> 6, d = hc & 63, b = row / TP, t = row - b * TP;
;             const float s = which == 0 ? 0.125f : 1.0f;
;             u32x2 w; w.x = pk_bf16(v[0] * s, v[1] * s); w.y = pk_bf16(v[2] * s, v[3] * s);
;             *(u32x2*)(qkv + (size_t)which * (QKV_ONE / 2) + ((size_t)(b * NH + h) * TP + t) * 64 + d) = w;
;         } else if (col < 3328) {
;             h16x4 o; o[0] = (_Float16)v[0]; o[1] = (_Float16)v[1]; o[2] = (_Float16)v[2]; o[3] = (_Float16)v[3];
;             *(h16x4*)(urw + (size_t)row * RWS + (col - 1536)) = o;
;         } else {
;             const int b = row / TP, t = row - b * TP;
;             if (t >= NMETA && t < T) {
;                 u32x2 w; w.x = pk_bf16(sigmoidf_(v[0]), sigmoidf_(v[1])); w.y = pk_bf16(sigmoidf_(v[2]), sigmoidf_(v[3]));
;                 *(u32x2*)(gates + (size_t)(b * SEQ + t - NMETA) * 2048 + (col - 3328)) = w;
;             }
.LBB0_429:
	s_andn2_b64 vcc, exec, s[34:35]
	s_cbranch_vccnz .LBB0_431
	v_mov_b64_e32 v[36:37], s[50:51]
	v_mad_i64_i32 v[36:37], s[34:35], v32, s73, v[36:37]
	v_cvt_pk_f16_f32 v35, v30, v31
	v_cvt_pk_f16_f32 v34, v28, v29
	v_lshl_add_u64 v[36:37], v[134:135], 1, v[36:37]
	global_store_dwordx2 v[36:37], v[34:35], off offset:-3072 nt
.LBB0_431:
	s_andn2_saveexec_b64 s[30:31], s[30:31]
	s_cbranch_execz .LBB0_433
	v_mul_hi_i32 v33, v32, s69
	v_lshrrev_b32_e32 v34, 31, v33
	v_ashrrev_i32_e32 v33, 12, v33
	v_add_u32_e32 v33, v33, v34
	v_mad_i32_i24 v34, v33, s72, v32
	v_pk_mul_f32 v[36:37], v[144:145], v[28:29] op_sel_hi:[0,1]
	v_pk_mul_f32 v[38:39], v[144:145], v[30:31] op_sel_hi:[0,1]
	v_lshl_or_b32 v33, v33, 3, s96
	v_cvt_pk_bf16_f32 v36, v36, v37
	v_cvt_pk_bf16_f32 v37, v38, v39
	v_mul_hi_i32_i24_e32 v39, 0x2080, v33
	v_mul_i32_i24_e32 v38, 0x2080, v33
	v_ashrrev_i32_e32 v35, 31, v34
	s_add_u32 s34, s50, s77
	v_lshl_add_u64 v[34:35], v[38:39], 0, v[34:35]
	s_addc_u32 s35, s51, s25
	v_lshlrev_b64 v[34:35], 7, v[34:35]
	v_lshl_add_u64 v[34:35], s[34:35], 0, v[34:35]
	v_lshlrev_b32_e32 v38, 1, v174
	v_mov_b32_e32 v39, v135
	v_lshl_add_u64 v[34:35], v[34:35], 0, v[38:39]
	global_store_dwordx2 v[34:35], v[36:37], off nt
.LBB0_433:
	s_or_b64 exec, exec, s[30:31]
	s_and_saveexec_b64 s[30:31], s[6:7]
	s_xor_b64 s[30:31], exec, s[30:31]
	s_cbranch_execz .LBB0_440
	s_andn2_b64 vcc, exec, s[0:1]
	s_mov_b64 s[34:35], -1
	s_cbranch_vccnz .LBB0_438
	v_mul_hi_i32 v33, v32, s69
	v_lshrrev_b32_e32 v34, 31, v33
	v_ashrrev_i32_e32 v33, 12, v33
	v_add_u32_e32 v33, v33, v34
	v_mul_i32_i24_e32 v34, 0xffffdf80, v33
	v_add3_u32 v34, v34, v32, -16
	v_cmp_gt_u32_e32 vcc, s65, v34
	s_and_saveexec_b64 s[34:35], vcc
	s_cbranch_execz .LBB0_437
	v_mul_f32_e32 v35, 0xbfb8aa3b, v24
	v_mul_f32_e32 v36, 0xbfb8aa3b, v25
	v_exp_f32_e32 v35, v35
	v_exp_f32_e32 v36, v36
	v_mul_f32_e32 v37, 0xbfb8aa3b, v27
	v_exp_f32_e32 v37, v37
	v_add_f32_e32 v35, 1.0, v35
	v_add_f32_e32 v36, 1.0, v36
	v_rcp_f32_e32 v35, v35
	v_rcp_f32_e32 v36, v36
	v_add_f32_e32 v37, 1.0, v37
	v_rcp_f32_e32 v37, v37
	v_lshl_add_u32 v34, v33, 13, v34
	v_cvt_pk_bf16_f32 v36, v35, v36
	v_mul_f32_e32 v35, 0xbfb8aa3b, v26
	v_exp_f32_e32 v35, v35
	s_nop 0
	v_add_f32_e32 v35, 1.0, v35
	v_rcp_f32_e32 v35, v35
	s_nop 0
	v_cvt_pk_bf16_f32 v37, v35, v37
	v_ashrrev_i32_e32 v35, 31, v34
	v_lshlrev_b64 v[34:35], 12, v[34:35]
	v_lshl_add_u64 v[34:35], s[88:89], 0, v[34:35]
	v_lshl_add_u64 v[34:35], v[134:135], 1, v[34:35]
	v_add_co_u32_e32 v34, vcc, 0xfffff000, v34
	s_nop 1
	v_addc_co_u32_e32 v35, vcc, -1, v35, vcc
	global_store_dwordx2 v[34:35], v[36:37], off offset:-2528 nt

; __device__ __forceinline__ unsigned pk_bf16(float lo, float hi) { const f32x2 v = {lo, hi}; return __builtin_bit_cast(unsigned, __builtin_convertvector(v, b16x2)); }
;     __device__ __forceinline__ void row(int r, int col32, int fq, const f32x4& a00, const f32x4& a01, const f32x4& a10, const f32x4& a11) const { half(r, col32, fq, a00, a01); half(r, col32 + HALF, fq, a10, a11); }
;     __device__ __forceinline__ void row(int r, int col32, int fq, const f32x4& a00, const f32x4& a01, const f32x4& a10, const f32x4& a11) const { half(r, col32, fq, a00, a01); half(r, col32 + HALF, fq, a10, a11); }
;     __device__ __forceinline__ void row(int r, int col32, int fq, const f32x4& a00, const f32x4& a01, const f32x4& a10, const f32x4& a11) const { half(r, col32, fq, a00, a01); half(r, col32 + HALF, fq, a10, a11); }
;     __device__ __forceinline__ void one(int row, int col, const f32x4& v) const {
;         if (col < 1536) {
;             const int which = col >> 9, hc = col & 511, h = hc >> 6, d = hc & 63, b = row / TP, t = row - b * TP;
;             const float s = which == 0 ? 0.125f : 1.0f;
;             u32x2 w; w.x = pk_bf16(v[0] * s, v[1] * s); w.y = pk_bf16(v[2] * s, v[3] * s);
;             *(u32x2*)(qkv + (size_t)which * (QKV_ONE / 2) + ((size_t)(b * NH + h) * TP + t) * 64 + d) = w;
;         } else if (col < 3328) {
;             h16x4 o; o[0] = (_Float16)v[0]; o[1] = (_Float16)v[1]; o[2] = (_Float16)v[2]; o[3] = (_Float16)v[3];
;             *(h16x4*)(urw + (size_t)row * RWS + (col - 1536)) = o;
.LBB0_438:
	s_andn2_b64 vcc, exec, s[34:35]
	s_cbranch_vccnz .LBB0_440
	v_mov_b64_e32 v[36:37], s[50:51]
	v_mad_i64_i32 v[36:37], s[34:35], v32, s73, v[36:37]
	v_cvt_pk_f16_f32 v35, v26, v27
	v_cvt_pk_f16_f32 v34, v24, v25
	v_lshl_add_u64 v[36:37], v[134:135], 1, v[36:37]
	global_store_dwordx2 v[36:37], v[34:35], off offset:-3040 nt
.LBB0_440:
	s_andn2_saveexec_b64 s[30:31], s[30:31]
	s_cbranch_execz .LBB0_442
	v_mul_hi_i32 v33, v32, s69
	v_lshrrev_b32_e32 v34, 31, v33
	v_ashrrev_i32_e32 v33, 12, v33
	v_add_u32_e32 v33, v33, v34
	v_mad_i32_i24 v34, v33, s72, v32
	v_pk_mul_f32 v[36:37], v[144:145], v[24:25] op_sel_hi:[0,1]
	v_pk_mul_f32 v[38:39], v[144:145], v[26:27] op_sel_hi:[0,1]
	v_lshl_or_b32 v33, v33, 3, s96
	v_cvt_pk_bf16_f32 v36, v36, v37
	v_cvt_pk_bf16_f32 v37, v38, v39
	v_mul_hi_i32_i24_e32 v39, 0x2080, v33
	v_mul_i32_i24_e32 v38, 0x2080, v33
	v_ashrrev_i32_e32 v35, 31, v34
	s_add_u32 s34, s50, s77
	v_lshl_add_u64 v[34:35], v[38:39], 0, v[34:35]
	s_addc_u32 s35, s51, s25
	v_lshlrev_b64 v[34:35], 7, v[34:35]
	v_lshl_add_u64 v[34:35], s[34:35], 0, v[34:35]
	v_lshlrev_b32_e32 v38, 1, v173
	v_mov_b32_e32 v39, v135
	v_lshl_add_u64 v[34:35], v[34:35], 0, v[38:39]
	global_store_dwordx2 v[34:35], v[36:37], off nt

; __device__ __forceinline__ unsigned pk_bf16(float lo, float hi) { const f32x2 v = {lo, hi}; return __builtin_bit_cast(unsigned, __builtin_convertvector(v, b16x2)); }
; __device__ __forceinline__ float sigmoidf_(float x) { return __builtin_amdgcn_rcpf(1.0f + __expf(-x)); }
;     __device__ __forceinline__ void row(int r, int col32, int fq, const f32x4& a00, const f32x4& a01, const f32x4& a10, const f32x4& a11) const { half(r, col32, fq, a00, a01); half(r, col32 + HALF, fq, a10, a11); }
;     __device__ __forceinline__ void row(int r, int col32, int fq, const f32x4& a00, const f32x4& a01, const f32x4& a10, const f32x4& a11) const { half(r, col32, fq, a00, a01); half(r, col32 + HALF, fq, a10, a11); }
;     __device__ __forceinline__ void row(int r, int col32, int fq, const f32x4& a00, const f32x4& a01, const f32x4& a10, const f32x4& a11) const { half(r, col32, fq, a00, a01); half(r, col32 + HALF, fq, a10, a11); }
;     __device__ __forceinline__ void one(int row, int col, const f32x4& v) const {
;     ...
;         } else {
;             const int b = row / TP, t = row - b * TP;
;             if (t >= NMETA && t < T) {
;                 u32x2 w; w.x = pk_bf16(sigmoidf_(v[0]), sigmoidf_(v[1])); w.y = pk_bf16(sigmoidf_(v[2]), sigmoidf_(v[3]));
;                 *(u32x2*)(gates + (size_t)(b * SEQ + t - NMETA) * 2048 + (col - 3328)) = w;
;             }
.LBB0_444:
	s_and_saveexec_b64 s[30:31], s[10:11]
	s_xor_b64 s[30:31], exec, s[30:31]
	s_cbranch_execz .LBB0_451
	s_andn2_b64 vcc, exec, s[0:1]
	s_mov_b64 s[34:35], -1
	s_cbranch_vccnz .LBB0_449
	v_mul_hi_i32 v24, v32, s69
	v_lshrrev_b32_e32 v25, 31, v24
	v_ashrrev_i32_e32 v24, 12, v24
	v_add_u32_e32 v24, v24, v25
	v_mul_i32_i24_e32 v25, 0xffffdf80, v24
	v_add3_u32 v25, v25, v32, -16
	v_cmp_gt_u32_e32 vcc, s65, v25
	s_and_saveexec_b64 s[34:35], vcc
	s_cbranch_execz .LBB0_448
	v_mul_f32_e32 v26, 0xbfb8aa3b, v20
	v_mul_f32_e32 v27, 0xbfb8aa3b, v21
	v_mul_f32_e32 v28, 0xbfb8aa3b, v22
	v_mul_f32_e32 v29, 0xbfb8aa3b, v23
	v_exp_f32_e32 v26, v26
	v_exp_f32_e32 v27, v27
	v_exp_f32_e32 v28, v28
	v_exp_f32_e32 v29, v29
	v_add_f32_e32 v26, 1.0, v26
	v_add_f32_e32 v27, 1.0, v27
	v_add_f32_e32 v28, 1.0, v28
	v_add_f32_e32 v29, 1.0, v29
	v_rcp_f32_e32 v26, v26
	v_rcp_f32_e32 v27, v27
	v_rcp_f32_e32 v28, v28
	v_rcp_f32_e32 v29, v29
	v_lshl_add_u32 v24, v24, 13, v25
	v_ashrrev_i32_e32 v25, 31, v24
	v_lshlrev_b64 v[24:25], 12, v[24:25]
	v_cvt_pk_bf16_f32 v26, v26, v27
	v_cvt_pk_bf16_f32 v27, v28, v29
	v_lshl_add_u64 v[24:25], s[88:89], 0, v[24:25]
	v_add_u32_e32 v28, s97, v149
	v_mov_b32_e32 v29, v135
	v_lshl_add_u64 v[24:25], v[28:29], 1, v[24:25]
	v_add_co_u32_e32 v24, vcc, 0xfffff000, v24
	s_nop 1
	v_addc_co_u32_e32 v25, vcc, -1, v25, vcc
	global_store_dwordx2 v[24:25], v[26:27], off offset:-2304 nt

; __device__ __forceinline__ unsigned pk_bf16(float lo, float hi) { const f32x2 v = {lo, hi}; return __builtin_bit_cast(unsigned, __builtin_convertvector(v, b16x2)); }
; __device__ __forceinline__ float sigmoidf_(float x) { return __builtin_amdgcn_rcpf(1.0f + __expf(-x)); }
;     __device__ __forceinline__ void row(int r, int col32, int fq, const f32x4& a00, const f32x4& a01, const f32x4& a10, const f32x4& a11) const { half(r, col32, fq, a00, a01); half(r, col32 + HALF, fq, a10, a11); }
;     __device__ __forceinline__ void row(int r, int col32, int fq, const f32x4& a00, const f32x4& a01, const f32x4& a10, const f32x4& a11) const { half(r, col32, fq, a00, a01); half(r, col32 + HALF, fq, a10, a11); }
;     __device__ __forceinline__ void row(int r, int col32, int fq, const f32x4& a00, const f32x4& a01, const f32x4& a10, const f32x4& a11) const { half(r, col32, fq, a00, a01); half(r, col32 + HALF, fq, a10, a11); }
;     __device__ __forceinline__ void one(int row, int col, const f32x4& v) const {
;         if (col < 1536) {
;             const int which = col >> 9, hc = col & 511, h = hc >> 6, d = hc & 63, b = row / TP, t = row - b * TP;
;             const float s = which == 0 ? 0.125f : 1.0f;
;             u32x2 w; w.x = pk_bf16(v[0] * s, v[1] * s); w.y = pk_bf16(v[2] * s, v[3] * s);
;             *(u32x2*)(qkv + (size_t)which * (QKV_ONE / 2) + ((size_t)(b * NH + h) * TP + t) * 64 + d) = w;
;         } else if (col < 3328) {
;             h16x4 o; o[0] = (_Float16)v[0]; o[1] = (_Float16)v[1]; o[2] = (_Float16)v[2]; o[3] = (_Float16)v[3];
;             *(h16x4*)(urw + (size_t)row * RWS + (col - 1536)) = o;
;         } else {
;             const int b = row / TP, t = row - b * TP;
;             if (t >= NMETA && t < T) {
;                 u32x2 w; w.x = pk_bf16(sigmoidf_(v[0]), sigmoidf_(v[1])); w.y = pk_bf16(sigmoidf_(v[2]), sigmoidf_(v[3]));
;                 *(u32x2*)(gates + (size_t)(b * SEQ + t - NMETA) * 2048 + (col - 3328)) = w;
;             }
.LBB0_449:
	s_andn2_b64 vcc, exec, s[34:35]
	s_cbranch_vccnz .LBB0_451
	v_mov_b64_e32 v[26:27], s[50:51]
	v_mad_i64_i32 v[26:27], s[34:35], v32, s73, v[26:27]
	v_add_u32_e32 v28, s97, v149
	v_mov_b32_e32 v29, v135
	v_cvt_pk_f16_f32 v25, v22, v23
	v_cvt_pk_f16_f32 v24, v20, v21
	v_lshl_add_u64 v[26:27], v[28:29], 1, v[26:27]
	global_store_dwordx2 v[26:27], v[24:25], off offset:-2816 nt
.LBB0_451:
	s_or_saveexec_b64 s[30:31], s[30:31]
	v_mul_hi_i32 v25, v32, s69
	v_lshrrev_b32_e32 v24, 31, v25
	v_ashrrev_i32_e32 v25, 12, v25
	s_xor_b64 exec, exec, s[30:31]
	s_cbranch_execz .LBB0_453
	v_add_u32_e32 v27, v25, v24
	v_mad_i32_i24 v26, v27, s72, v32
	v_pk_mul_f32 v[28:29], v[144:145], v[20:21] op_sel_hi:[0,1]
	v_pk_mul_f32 v[30:31], v[144:145], v[22:23] op_sel_hi:[0,1]
	v_lshl_or_b32 v27, v27, 3, s94
	v_cvt_pk_bf16_f32 v28, v28, v29
	v_cvt_pk_bf16_f32 v29, v30, v31
	v_mul_hi_i32_i24_e32 v31, 0x2080, v27
	v_mul_i32_i24_e32 v30, 0x2080, v27
	v_ashrrev_i32_e32 v27, 31, v26
	s_add_u32 s34, s50, s77
	v_lshl_add_u64 v[26:27], v[30:31], 0, v[26:27]
	s_addc_u32 s35, s51, s25
	v_lshlrev_b64 v[26:27], 7, v[26:27]
	v_lshl_add_u64 v[26:27], s[34:35], 0, v[26:27]
	v_lshlrev_b32_e32 v30, 1, v124
	v_mov_b32_e32 v31, v135
	v_lshl_add_u64 v[26:27], v[26:27], 0, v[30:31]
	global_store_dwordx2 v[26:27], v[28:29], off nt
.LBB0_453:
	s_or_b64 exec, exec, s[30:31]
	s_and_saveexec_b64 s[30:31], s[4:5]
	s_xor_b64 s[30:31], exec, s[30:31]
	s_cbranch_execz .LBB0_460
	s_andn2_b64 vcc, exec, s[0:1]
	s_mov_b64 s[34:35], -1
	s_cbranch_vccnz .LBB0_458
	v_add_u32_e32 v24, v25, v24
	v_mul_i32_i24_e32 v25, 0xffffdf80, v24
	v_add3_u32 v25, v25, v32, -16
	v_cmp_gt_u32_e32 vcc, s65, v25
	s_and_saveexec_b64 s[34:35], vcc
	s_cbranch_execz .LBB0_457
	v_mul_f32_e32 v26, 0xbfb8aa3b, v16
	v_mul_f32_e32 v27, 0xbfb8aa3b, v17
	v_exp_f32_e32 v26, v26
	v_exp_f32_e32 v27, v27
	v_mul_f32_e32 v28, 0xbfb8aa3b, v19
	v_exp_f32_e32 v28, v28
	v_add_f32_e32 v26, 1.0, v26
	v_add_f32_e32 v27, 1.0, v27
	v_rcp_f32_e32 v26, v26
	v_rcp_f32_e32 v27, v27
	v_lshl_add_u32 v24, v24, 13, v25
	v_add_f32_e32 v28, 1.0, v28
	v_ashrrev_i32_e32 v25, 31, v24
	v_cvt_pk_bf16_f32 v26, v26, v27
	v_mul_f32_e32 v27, 0xbfb8aa3b, v18
	v_exp_f32_e32 v27, v27
	v_rcp_f32_e32 v28, v28
	v_lshlrev_b64 v[24:25], 12, v[24:25]
	v_lshl_add_u64 v[24:25], s[88:89], 0, v[24:25]
	v_add_f32_e32 v27, 1.0, v27
	v_rcp_f32_e32 v27, v27
	v_lshl_add_u64 v[24:25], v[134:135], 1, v[24:25]
	v_add_co_u32_e32 v24, vcc, 0xfffff000, v24
	v_cvt_pk_bf16_f32 v27, v27, v28
	s_nop 0
	v_addc_co_u32_e32 v25, vcc, -1, v25, vcc
	global_store_dwordx2 v[24:25], v[26:27], off offset:-2272 nt

; __device__ __forceinline__ unsigned pk_bf16(float lo, float hi) { const f32x2 v = {lo, hi}; return __builtin_bit_cast(unsigned, __builtin_convertvector(v, b16x2)); }
;     __device__ __forceinline__ void row(int r, int col32, int fq, const f32x4& a00, const f32x4& a01, const f32x4& a10, const f32x4& a11) const { half(r, col32, fq, a00, a01); half(r, col32 + HALF, fq, a10, a11); }
;     __device__ __forceinline__ void row(int r, int col32, int fq, const f32x4& a00, const f32x4& a01, const f32x4& a10, const f32x4& a11) const { half(r, col32, fq, a00, a01); half(r, col32 + HALF, fq, a10, a11); }
;     __device__ __forceinline__ void row(int r, int col32, int fq, const f32x4& a00, const f32x4& a01, const f32x4& a10, const f32x4& a11) const { half(r, col32, fq, a00, a01); half(r, col32 + HALF, fq, a10, a11); }
;     __device__ __forceinline__ void one(int row, int col, const f32x4& v) const {
;         if (col < 1536) {
;             const int which = col >> 9, hc = col & 511, h = hc >> 6, d = hc & 63, b = row / TP, t = row - b * TP;
;             const float s = which == 0 ? 0.125f : 1.0f;
;             u32x2 w; w.x = pk_bf16(v[0] * s, v[1] * s); w.y = pk_bf16(v[2] * s, v[3] * s);
;             *(u32x2*)(qkv + (size_t)which * (QKV_ONE / 2) + ((size_t)(b * NH + h) * TP + t) * 64 + d) = w;
;         } else if (col < 3328) {
;             h16x4 o; o[0] = (_Float16)v[0]; o[1] = (_Float16)v[1]; o[2] = (_Float16)v[2]; o[3] = (_Float16)v[3];
;             *(h16x4*)(urw + (size_t)row * RWS + (col - 1536)) = o;
.LBB0_458:
	s_andn2_b64 vcc, exec, s[34:35]
	s_cbranch_vccnz .LBB0_460
	v_mov_b64_e32 v[26:27], s[50:51]
	v_mad_i64_i32 v[26:27], s[34:35], v32, s73, v[26:27]
	v_cvt_pk_f16_f32 v25, v18, v19
	v_cvt_pk_f16_f32 v24, v16, v17
	v_lshl_add_u64 v[26:27], v[134:135], 1, v[26:27]
	global_store_dwordx2 v[26:27], v[24:25], off offset:-2784 nt
.LBB0_460:
	s_andn2_saveexec_b64 s[30:31], s[30:31]
	s_cbranch_execz .LBB0_462
	v_add_u32_e32 v25, v25, v24
	v_mad_i32_i24 v24, v25, s72, v32
	v_pk_mul_f32 v[26:27], v[144:145], v[16:17] op_sel_hi:[0,1]
	v_pk_mul_f32 v[28:29], v[144:145], v[18:19] op_sel_hi:[0,1]
	v_lshl_or_b32 v25, v25, 3, v123
	v_cvt_pk_bf16_f32 v26, v26, v27
	v_cvt_pk_bf16_f32 v27, v28, v29
	v_mul_hi_i32_i24_e32 v29, 0x2080, v25
	v_mul_i32_i24_e32 v28, 0x2080, v25
	v_ashrrev_i32_e32 v25, 31, v24
	s_add_u32 s34, s50, s77
	v_lshl_add_u64 v[24:25], v[28:29], 0, v[24:25]
	s_addc_u32 s35, s51, s25
	v_lshlrev_b64 v[24:25], 7, v[24:25]
	v_lshl_add_u64 v[24:25], s[34:35], 0, v[24:25]
	v_lshlrev_b32_e32 v28, 1, v122
	v_mov_b32_e32 v29, v135
	v_lshl_add_u64 v[24:25], v[24:25], 0, v[28:29]
	global_store_dwordx2 v[24:25], v[26:27], off nt

; __device__ __forceinline__ unsigned pk_bf16(float lo, float hi) { const f32x2 v = {lo, hi}; return __builtin_bit_cast(unsigned, __builtin_convertvector(v, b16x2)); }
; __device__ __forceinline__ float sigmoidf_(float x) { return __builtin_amdgcn_rcpf(1.0f + __expf(-x)); }
;     __device__ __forceinline__ void row(int r, int col32, int fq, const f32x4& a00, const f32x4& a01, const f32x4& a10, const f32x4& a11) const { half(r, col32, fq, a00, a01); half(r, col32 + HALF, fq, a10, a11); }
;     __device__ __forceinline__ void row(int r, int col32, int fq, const f32x4& a00, const f32x4& a01, const f32x4& a10, const f32x4& a11) const { half(r, col32, fq, a00, a01); half(r, col32 + HALF, fq, a10, a11); }
;     __device__ __forceinline__ void row(int r, int col32, int fq, const f32x4& a00, const f32x4& a01, const f32x4& a10, const f32x4& a11) const { half(r, col32, fq, a00, a01); half(r, col32 + HALF, fq, a10, a11); }
;     __device__ __forceinline__ void one(int row, int col, const f32x4& v) const {
;     ...
;         } else {
;             const int b = row / TP, t = row - b * TP;
;             if (t >= NMETA && t < T) {
;                 u32x2 w; w.x = pk_bf16(sigmoidf_(v[0]), sigmoidf_(v[1])); w.y = pk_bf16(sigmoidf_(v[2]), sigmoidf_(v[3]));
;                 *(u32x2*)(gates + (size_t)(b * SEQ + t - NMETA) * 2048 + (col - 3328)) = w;
;             }
;     __device__ __forceinline__ void half(int row, int col32, int fq, const f32x4& v0, const f32x4& v1) const {
;     ...
;             if (col32 >= 1536 && col32 < 3072) {
;                 const int c = col32 - 1536, pos = (c & ~63) + fq * 16 + ((c & 63) >> 4) * 4;
;                 h16x8 o;
; #pragma unroll
;                 for (int j = 0; j < 4; ++j) { o[j] = (_Float16)v0[j]; o[4 + j] = (_Float16)v1[j]; }
;                 *(h16x8*)(urw + (size_t)row * RWS + pos) = o;
;             } else { one(row, col32 + 4 * fq, v0); one(row, col32 + 16 + 4 * fq, v1); }
.LBB0_463:
	s_and_b64 vcc, exec, s[30:31]
	s_cbranch_vccz .LBB0_443
	v_cvt_pk_f16_f32 v27, v26, v27
	v_cvt_pk_f16_f32 v26, v24, v25
	v_cvt_pk_f16_f32 v24, v28, v29
	v_mov_b64_e32 v[28:29], s[50:51]
	v_mad_i64_i32 v[28:29], s[30:31], v32, s73, v[28:29]
	v_cvt_pk_f16_f32 v25, v30, v31
	v_lshl_add_u64 v[28:29], v[146:147], 1, v[28:29]
	global_store_dwordx4 v[28:29], v[24:27], off nt
	s_and_b64 vcc, exec, s[14:15]
	s_mov_b64 s[30:31], -1
	s_cbranch_vccz .LBB0_444
.LBB0_465:
	s_and_b64 vcc, exec, s[30:31]
	s_cbranch_vccz .LBB0_467
	v_cvt_pk_f16_f32 v19, v18, v19
	v_cvt_pk_f16_f32 v18, v16, v17
	v_cvt_pk_f16_f32 v16, v20, v21
	v_mov_b64_e32 v[20:21], s[50:51]
	v_mad_i64_i32 v[20:21], s[30:31], v32, s73, v[20:21]
	v_cvt_pk_f16_f32 v17, v22, v23
	v_lshl_add_u64 v[20:21], v[120:121], 1, v[20:21]
	global_store_dwordx4 v[20:21], v[16:19], off nt
.LBB0_467:
	s_nop 1
	v_add_u32_e32 v16, 0xb0, v175
	s_and_b64 vcc, exec, s[12:13]
	s_mov_b64 s[12:13], -1
	s_cbranch_vccnz .LBB0_507
	s_and_saveexec_b64 s[12:13], s[8:9]
	s_xor_b64 s[8:9], exec, s[12:13]
	s_cbranch_execz .LBB0_475
	s_andn2_b64 vcc, exec, s[0:1]
	s_mov_b64 s[12:13], -1
	s_cbranch_vccnz .LBB0_473
	v_mul_hi_i32 v17, v16, s69
	v_lshrrev_b32_e32 v18, 31, v17
	v_ashrrev_i32_e32 v17, 12, v17
	v_add_u32_e32 v17, v17, v18
	v_mul_i32_i24_e32 v18, 0xffffdf80, v17
	v_add3_u32 v18, v18, v16, -16
	v_cmp_gt_u32_e32 vcc, s65, v18
	s_and_saveexec_b64 s[12:13], vcc
	s_cbranch_execz .LBB0_472
	v_mul_f32_e32 v19, 0xbfb8aa3b, v12
	v_mul_f32_e32 v20, 0xbfb8aa3b, v13
	v_exp_f32_e32 v19, v19
	v_exp_f32_e32 v20, v20
	v_mul_f32_e32 v21, 0xbfb8aa3b, v14
	v_mul_f32_e32 v22, 0xbfb8aa3b, v15
	v_add_f32_e32 v19, 1.0, v19
	v_add_f32_e32 v20, 1.0, v20
	v_rcp_f32_e32 v19, v19
	v_exp_f32_e32 v21, v21
	v_exp_f32_e32 v22, v22
	v_rcp_f32_e32 v20, v20
	v_lshl_add_u32 v18, v17, 13, v18
	v_add_f32_e32 v21, 1.0, v21
	v_add_f32_e32 v22, 1.0, v22
	v_cvt_pk_bf16_f32 v20, v19, v20
	v_ashrrev_i32_e32 v19, 31, v18
	v_rcp_f32_e32 v21, v21
	v_rcp_f32_e32 v22, v22
	v_lshlrev_b64 v[18:19], 12, v[18:19]
	v_lshl_add_u64 v[18:19], s[88:89], 0, v[18:19]
	v_lshl_add_u64 v[18:19], v[134:135], 1, v[18:19]
	v_add_co_u32_e32 v18, vcc, 0xfffff000, v18
	v_cvt_pk_bf16_f32 v21, v21, v22
	s_nop 0
	v_addc_co_u32_e32 v19, vcc, -1, v19, vcc
	global_store_dwordx2 v[18:19], v[20:21], off offset:-2560 nt

; __device__ __forceinline__ unsigned pk_bf16(float lo, float hi) { const f32x2 v = {lo, hi}; return __builtin_bit_cast(unsigned, __builtin_convertvector(v, b16x2)); }
; __device__ __forceinline__ float sigmoidf_(float x) { return __builtin_amdgcn_rcpf(1.0f + __expf(-x)); }
;     __device__ __forceinline__ void row(int r, int col32, int fq, const f32x4& a00, const f32x4& a01, const f32x4& a10, const f32x4& a11) const { half(r, col32, fq, a00, a01); half(r, col32 + HALF, fq, a10, a11); }
;     __device__ __forceinline__ void row(int r, int col32, int fq, const f32x4& a00, const f32x4& a01, const f32x4& a10, const f32x4& a11) const { half(r, col32, fq, a00, a01); half(r, col32 + HALF, fq, a10, a11); }
;     __device__ __forceinline__ void row(int r, int col32, int fq, const f32x4& a00, const f32x4& a01, const f32x4& a10, const f32x4& a11) const { half(r, col32, fq, a00, a01); half(r, col32 + HALF, fq, a10, a11); }
;     __device__ __forceinline__ void one(int row, int col, const f32x4& v) const {
;         if (col < 1536) {
;             const int which = col >> 9, hc = col & 511, h = hc >> 6, d = hc & 63, b = row / TP, t = row - b * TP;
;             const float s = which == 0 ? 0.125f : 1.0f;
;             u32x2 w; w.x = pk_bf16(v[0] * s, v[1] * s); w.y = pk_bf16(v[2] * s, v[3] * s);
;             *(u32x2*)(qkv + (size_t)which * (QKV_ONE / 2) + ((size_t)(b * NH + h) * TP + t) * 64 + d) = w;
;         } else if (col < 3328) {
;             h16x4 o; o[0] = (_Float16)v[0]; o[1] = (_Float16)v[1]; o[2] = (_Float16)v[2]; o[3] = (_Float16)v[3];
;             *(h16x4*)(urw + (size_t)row * RWS + (col - 1536)) = o;
;         } else {
;             const int b = row / TP, t = row - b * TP;
;             if (t >= NMETA && t < T) {
;                 u32x2 w; w.x = pk_bf16(sigmoidf_(v[0]), sigmoidf_(v[1])); w.y = pk_bf16(sigmoidf_(v[2]), sigmoidf_(v[3]));
;                 *(u32x2*)(gates + (size_t)(b * SEQ + t - NMETA) * 2048 + (col - 3328)) = w;
;             }
.LBB0_473:
	s_andn2_b64 vcc, exec, s[12:13]
	s_cbranch_vccnz .LBB0_475
	v_mov_b64_e32 v[20:21], s[50:51]
	v_mad_i64_i32 v[20:21], s[12:13], v16, s73, v[20:21]
	v_cvt_pk_f16_f32 v19, v14, v15
	v_cvt_pk_f16_f32 v18, v12, v13
	v_lshl_add_u64 v[20:21], v[134:135], 1, v[20:21]
	global_store_dwordx2 v[20:21], v[18:19], off offset:-3072 nt
.LBB0_475:
	s_andn2_saveexec_b64 s[8:9], s[8:9]
	s_cbranch_execz .LBB0_477
	v_mul_hi_i32 v17, v16, s69
	v_lshrrev_b32_e32 v18, 31, v17
	v_ashrrev_i32_e32 v17, 12, v17
	v_add_u32_e32 v17, v17, v18
	v_mad_i32_i24 v18, v17, s72, v16
	v_pk_mul_f32 v[20:21], v[144:145], v[12:13] op_sel_hi:[0,1]
	v_pk_mul_f32 v[22:23], v[144:145], v[14:15] op_sel_hi:[0,1]
	v_lshl_or_b32 v17, v17, 3, s96
	v_cvt_pk_bf16_f32 v20, v20, v21
	v_cvt_pk_bf16_f32 v21, v22, v23
	v_mul_hi_i32_i24_e32 v23, 0x2080, v17
	v_mul_i32_i24_e32 v22, 0x2080, v17
	v_ashrrev_i32_e32 v19, 31, v18
	s_add_u32 s12, s50, s77
	v_lshl_add_u64 v[18:19], v[22:23], 0, v[18:19]
	s_addc_u32 s13, s51, s25
	v_lshlrev_b64 v[18:19], 7, v[18:19]
	v_lshl_add_u64 v[18:19], s[12:13], 0, v[18:19]
	v_lshlrev_b32_e32 v22, 1, v174
	v_mov_b32_e32 v23, v135
	v_lshl_add_u64 v[18:19], v[18:19], 0, v[22:23]
	global_store_dwordx2 v[18:19], v[20:21], off nt
.LBB0_477:
	s_or_b64 exec, exec, s[8:9]
	s_and_saveexec_b64 s[8:9], s[6:7]
	s_xor_b64 s[6:7], exec, s[8:9]
	s_cbranch_execz .LBB0_484
	s_andn2_b64 vcc, exec, s[0:1]
	s_mov_b64 s[8:9], -1
	s_cbranch_vccnz .LBB0_482
	v_mul_hi_i32 v17, v16, s69
	v_lshrrev_b32_e32 v18, 31, v17
	v_ashrrev_i32_e32 v17, 12, v17
	v_add_u32_e32 v17, v17, v18
	v_mul_i32_i24_e32 v18, 0xffffdf80, v17
	v_add3_u32 v18, v18, v16, -16
	v_cmp_gt_u32_e32 vcc, s65, v18
	s_and_saveexec_b64 s[8:9], vcc
	s_cbranch_execz .LBB0_481
	v_mul_f32_e32 v19, 0xbfb8aa3b, v8
	v_mul_f32_e32 v20, 0xbfb8aa3b, v9
	v_exp_f32_e32 v19, v19
	v_exp_f32_e32 v20, v20
	v_mul_f32_e32 v21, 0xbfb8aa3b, v10
	v_mul_f32_e32 v22, 0xbfb8aa3b, v11
	v_add_f32_e32 v19, 1.0, v19
	v_add_f32_e32 v20, 1.0, v20
	v_rcp_f32_e32 v19, v19
	v_exp_f32_e32 v21, v21
	v_exp_f32_e32 v22, v22
	v_rcp_f32_e32 v20, v20
	v_lshl_add_u32 v18, v17, 13, v18
	v_add_f32_e32 v21, 1.0, v21
	v_add_f32_e32 v22, 1.0, v22
	v_cvt_pk_bf16_f32 v20, v19, v20
	v_ashrrev_i32_e32 v19, 31, v18
	v_rcp_f32_e32 v21, v21
	v_rcp_f32_e32 v22, v22
	v_lshlrev_b64 v[18:19], 12, v[18:19]
	v_lshl_add_u64 v[18:19], s[88:89], 0, v[18:19]
	v_lshl_add_u64 v[18:19], v[134:135], 1, v[18:19]
	v_add_co_u32_e32 v18, vcc, 0xfffff000, v18
	v_cvt_pk_bf16_f32 v21, v21, v22
	s_nop 0
	v_addc_co_u32_e32 v19, vcc, -1, v19, vcc
	global_store_dwordx2 v[18:19], v[20:21], off offset:-2528 nt

; __device__ __forceinline__ unsigned pk_bf16(float lo, float hi) { const f32x2 v = {lo, hi}; return __builtin_bit_cast(unsigned, __builtin_convertvector(v, b16x2)); }
;     __device__ __forceinline__ void row(int r, int col32, int fq, const f32x4& a00, const f32x4& a01, const f32x4& a10, const f32x4& a11) const { half(r, col32, fq, a00, a01); half(r, col32 + HALF, fq, a10, a11); }
;     __device__ __forceinline__ void row(int r, int col32, int fq, const f32x4& a00, const f32x4& a01, const f32x4& a10, const f32x4& a11) const { half(r, col32, fq, a00, a01); half(r, col32 + HALF, fq, a10, a11); }
;     __device__ __forceinline__ void row(int r, int col32, int fq, const f32x4& a00, const f32x4& a01, const f32x4& a10, const f32x4& a11) const { half(r, col32, fq, a00, a01); half(r, col32 + HALF, fq, a10, a11); }
;     __device__ __forceinline__ void one(int row, int col, const f32x4& v) const {
;         if (col < 1536) {
;             const int which = col >> 9, hc = col & 511, h = hc >> 6, d = hc & 63, b = row / TP, t = row - b * TP;
;             const float s = which == 0 ? 0.125f : 1.0f;
;             u32x2 w; w.x = pk_bf16(v[0] * s, v[1] * s); w.y = pk_bf16(v[2] * s, v[3] * s);
;             *(u32x2*)(qkv + (size_t)which * (QKV_ONE / 2) + ((size_t)(b * NH + h) * TP + t) * 64 + d) = w;
;         } else if (col < 3328) {
;             h16x4 o; o[0] = (_Float16)v[0]; o[1] = (_Float16)v[1]; o[2] = (_Float16)v[2]; o[3] = (_Float16)v[3];
;             *(h16x4*)(urw + (size_t)row * RWS + (col - 1536)) = o;
.LBB0_482:
	s_andn2_b64 vcc, exec, s[8:9]
	s_cbranch_vccnz .LBB0_484
	v_mov_b64_e32 v[20:21], s[50:51]
	v_mad_i64_i32 v[20:21], s[8:9], v16, s73, v[20:21]
	v_cvt_pk_f16_f32 v19, v10, v11
	v_cvt_pk_f16_f32 v18, v8, v9
	v_lshl_add_u64 v[20:21], v[134:135], 1, v[20:21]
	global_store_dwordx2 v[20:21], v[18:19], off offset:-3040 nt
.LBB0_484:
	s_andn2_saveexec_b64 s[6:7], s[6:7]
	s_cbranch_execz .LBB0_486
	v_mul_hi_i32 v17, v16, s69
	v_lshrrev_b32_e32 v18, 31, v17
	v_ashrrev_i32_e32 v17, 12, v17
	v_add_u32_e32 v17, v17, v18
	v_mad_i32_i24 v18, v17, s72, v16
	v_pk_mul_f32 v[20:21], v[144:145], v[8:9] op_sel_hi:[0,1]
	v_pk_mul_f32 v[22:23], v[144:145], v[10:11] op_sel_hi:[0,1]
	v_lshl_or_b32 v17, v17, 3, s96
	v_cvt_pk_bf16_f32 v20, v20, v21
	v_cvt_pk_bf16_f32 v21, v22, v23
	v_mul_hi_i32_i24_e32 v23, 0x2080, v17
	v_mul_i32_i24_e32 v22, 0x2080, v17
	v_ashrrev_i32_e32 v19, 31, v18
	s_add_u32 s8, s50, s77
	v_lshl_add_u64 v[18:19], v[22:23], 0, v[18:19]
	s_addc_u32 s9, s51, s25
	v_lshlrev_b64 v[18:19], 7, v[18:19]
	v_lshl_add_u64 v[18:19], s[8:9], 0, v[18:19]
	v_lshlrev_b32_e32 v22, 1, v173
	v_mov_b32_e32 v23, v135
	v_lshl_add_u64 v[18:19], v[18:19], 0, v[22:23]
	global_store_dwordx2 v[18:19], v[20:21], off nt

; __device__ __forceinline__ unsigned pk_bf16(float lo, float hi) { const f32x2 v = {lo, hi}; return __builtin_bit_cast(unsigned, __builtin_convertvector(v, b16x2)); }
; __device__ __forceinline__ float sigmoidf_(float x) { return __builtin_amdgcn_rcpf(1.0f + __expf(-x)); }
;     __device__ __forceinline__ void row(int r, int col32, int fq, const f32x4& a00, const f32x4& a01, const f32x4& a10, const f32x4& a11) const { half(r, col32, fq, a00, a01); half(r, col32 + HALF, fq, a10, a11); }
;     __device__ __forceinline__ void row(int r, int col32, int fq, const f32x4& a00, const f32x4& a01, const f32x4& a10, const f32x4& a11) const { half(r, col32, fq, a00, a01); half(r, col32 + HALF, fq, a10, a11); }
;     __device__ __forceinline__ void row(int r, int col32, int fq, const f32x4& a00, const f32x4& a01, const f32x4& a10, const f32x4& a11) const { half(r, col32, fq, a00, a01); half(r, col32 + HALF, fq, a10, a11); }
;     __device__ __forceinline__ void one(int row, int col, const f32x4& v) const {
;     ...
;         } else {
;             const int b = row / TP, t = row - b * TP;
;             if (t >= NMETA && t < T) {
;                 u32x2 w; w.x = pk_bf16(sigmoidf_(v[0]), sigmoidf_(v[1])); w.y = pk_bf16(sigmoidf_(v[2]), sigmoidf_(v[3]));
;                 *(u32x2*)(gates + (size_t)(b * SEQ + t - NMETA) * 2048 + (col - 3328)) = w;
;             }
.LBB0_488:
	v_cndmask_b32_e64 v8, 0, 1, s[0:1]
	v_cmp_ne_u32_e64 s[0:1], 1, v8
	s_and_saveexec_b64 s[6:7], s[10:11]
	s_xor_b64 s[6:7], exec, s[6:7]
	s_cbranch_execz .LBB0_495
	s_and_b64 vcc, exec, s[0:1]
	s_mov_b64 s[8:9], -1
	s_cbranch_vccnz .LBB0_493
	v_mul_hi_i32 v8, v16, s69
	v_lshrrev_b32_e32 v9, 31, v8
	v_ashrrev_i32_e32 v8, 12, v8
	v_add_u32_e32 v8, v8, v9
	v_mul_i32_i24_e32 v9, 0xffffdf80, v8
	v_add3_u32 v9, v9, v16, -16
	v_cmp_gt_u32_e32 vcc, s65, v9
	s_and_saveexec_b64 s[8:9], vcc
	s_cbranch_execz .LBB0_492
	v_mul_f32_e32 v10, 0xbfb8aa3b, v4
	v_mul_f32_e32 v11, 0xbfb8aa3b, v5
	v_mul_f32_e32 v12, 0xbfb8aa3b, v6
	v_mul_f32_e32 v13, 0xbfb8aa3b, v7
	v_exp_f32_e32 v10, v10
	v_exp_f32_e32 v11, v11
	v_exp_f32_e32 v12, v12
	v_exp_f32_e32 v13, v13
	v_add_f32_e32 v10, 1.0, v10
	v_add_f32_e32 v11, 1.0, v11
	v_add_f32_e32 v12, 1.0, v12
	v_add_f32_e32 v13, 1.0, v13
	v_rcp_f32_e32 v10, v10
	v_rcp_f32_e32 v11, v11
	v_rcp_f32_e32 v12, v12
	v_rcp_f32_e32 v13, v13
	v_lshl_add_u32 v8, v8, 13, v9
	v_ashrrev_i32_e32 v9, 31, v8
	v_lshlrev_b64 v[8:9], 12, v[8:9]
	v_cvt_pk_bf16_f32 v10, v10, v11
	v_cvt_pk_bf16_f32 v11, v12, v13
	v_lshl_add_u64 v[8:9], s[88:89], 0, v[8:9]
	v_add_u32_e32 v12, s97, v149
	v_mov_b32_e32 v13, v135
	v_lshl_add_u64 v[8:9], v[12:13], 1, v[8:9]
	v_add_co_u32_e32 v8, vcc, 0xfffff000, v8
	s_nop 1
	v_addc_co_u32_e32 v9, vcc, -1, v9, vcc
	global_store_dwordx2 v[8:9], v[10:11], off offset:-2304 nt

; __device__ __forceinline__ unsigned pk_bf16(float lo, float hi) { const f32x2 v = {lo, hi}; return __builtin_bit_cast(unsigned, __builtin_convertvector(v, b16x2)); }
; __device__ __forceinline__ float sigmoidf_(float x) { return __builtin_amdgcn_rcpf(1.0f + __expf(-x)); }
;     __device__ __forceinline__ void row(int r, int col32, int fq, const f32x4& a00, const f32x4& a01, const f32x4& a10, const f32x4& a11) const { half(r, col32, fq, a00, a01); half(r, col32 + HALF, fq, a10, a11); }
;     __device__ __forceinline__ void row(int r, int col32, int fq, const f32x4& a00, const f32x4& a01, const f32x4& a10, const f32x4& a11) const { half(r, col32, fq, a00, a01); half(r, col32 + HALF, fq, a10, a11); }
;     __device__ __forceinline__ void row(int r, int col32, int fq, const f32x4& a00, const f32x4& a01, const f32x4& a10, const f32x4& a11) const { half(r, col32, fq, a00, a01); half(r, col32 + HALF, fq, a10, a11); }
;     __device__ __forceinline__ void one(int row, int col, const f32x4& v) const {
;         if (col < 1536) {
;             const int which = col >> 9, hc = col & 511, h = hc >> 6, d = hc & 63, b = row / TP, t = row - b * TP;
;             const float s = which == 0 ? 0.125f : 1.0f;
;             u32x2 w; w.x = pk_bf16(v[0] * s, v[1] * s); w.y = pk_bf16(v[2] * s, v[3] * s);
;             *(u32x2*)(qkv + (size_t)which * (QKV_ONE / 2) + ((size_t)(b * NH + h) * TP + t) * 64 + d) = w;
;         } else if (col < 3328) {
;             h16x4 o; o[0] = (_Float16)v[0]; o[1] = (_Float16)v[1]; o[2] = (_Float16)v[2]; o[3] = (_Float16)v[3];
;             *(h16x4*)(urw + (size_t)row * RWS + (col - 1536)) = o;
;         } else {
;             const int b = row / TP, t = row - b * TP;
;             if (t >= NMETA && t < T) {
;                 u32x2 w; w.x = pk_bf16(sigmoidf_(v[0]), sigmoidf_(v[1])); w.y = pk_bf16(sigmoidf_(v[2]), sigmoidf_(v[3]));
;                 *(u32x2*)(gates + (size_t)(b * SEQ + t - NMETA) * 2048 + (col - 3328)) = w;
;             }
.LBB0_493:
	s_andn2_b64 vcc, exec, s[8:9]
	s_cbranch_vccnz .LBB0_495
	v_mov_b64_e32 v[10:11], s[50:51]
	v_mad_i64_i32 v[10:11], s[8:9], v16, s73, v[10:11]
	v_add_u32_e32 v12, s97, v149
	v_mov_b32_e32 v13, v135
	v_cvt_pk_f16_f32 v9, v6, v7
	v_cvt_pk_f16_f32 v8, v4, v5
	v_lshl_add_u64 v[10:11], v[12:13], 1, v[10:11]
	global_store_dwordx2 v[10:11], v[8:9], off offset:-2816 nt
.LBB0_495:
	s_or_saveexec_b64 s[6:7], s[6:7]
	v_mul_hi_i32 v9, v16, s69
	v_lshrrev_b32_e32 v8, 31, v9
	v_ashrrev_i32_e32 v9, 12, v9
	s_xor_b64 exec, exec, s[6:7]
	s_cbranch_execz .LBB0_497
	v_add_u32_e32 v11, v9, v8
	v_mad_i32_i24 v10, v11, s72, v16
	v_pk_mul_f32 v[12:13], v[144:145], v[4:5] op_sel_hi:[0,1]
	v_pk_mul_f32 v[14:15], v[144:145], v[6:7] op_sel_hi:[0,1]
	v_lshl_or_b32 v11, v11, 3, s94
	v_cvt_pk_bf16_f32 v12, v12, v13
	v_cvt_pk_bf16_f32 v13, v14, v15
	v_mul_hi_i32_i24_e32 v15, 0x2080, v11
	v_mul_i32_i24_e32 v14, 0x2080, v11
	v_ashrrev_i32_e32 v11, 31, v10
	s_add_u32 s8, s50, s77
	v_lshl_add_u64 v[10:11], v[14:15], 0, v[10:11]
	s_addc_u32 s9, s51, s25
	v_lshlrev_b64 v[10:11], 7, v[10:11]
	v_lshl_add_u64 v[10:11], s[8:9], 0, v[10:11]
	v_lshlrev_b32_e32 v14, 1, v124
	v_mov_b32_e32 v15, v135
	v_lshl_add_u64 v[10:11], v[10:11], 0, v[14:15]
	global_store_dwordx2 v[10:11], v[12:13], off nt
.LBB0_497:
	s_or_b64 exec, exec, s[6:7]
	s_and_saveexec_b64 s[6:7], s[4:5]
	s_xor_b64 s[4:5], exec, s[6:7]
	s_cbranch_execz .LBB0_504
	s_and_b64 vcc, exec, s[0:1]
	s_mov_b64 s[0:1], -1
	s_cbranch_vccnz .LBB0_502
	v_add_u32_e32 v8, v9, v8
	v_mul_i32_i24_e32 v9, 0xffffdf80, v8
	v_add3_u32 v9, v9, v16, -16
	v_cmp_gt_u32_e32 vcc, s65, v9
	s_and_saveexec_b64 s[0:1], vcc
	s_cbranch_execz .LBB0_501
	v_mul_f32_e32 v10, 0xbfb8aa3b, v0
	v_mul_f32_e32 v11, 0xbfb8aa3b, v1
	v_mul_f32_e32 v12, 0xbfb8aa3b, v2
	v_mul_f32_e32 v13, 0xbfb8aa3b, v3
	v_exp_f32_e32 v10, v10
	v_exp_f32_e32 v11, v11
	v_exp_f32_e32 v12, v12
	v_exp_f32_e32 v13, v13
	v_lshl_add_u32 v8, v8, 13, v9
	v_add_f32_e32 v10, 1.0, v10
	v_add_f32_e32 v11, 1.0, v11
	v_add_f32_e32 v12, 1.0, v12
	v_add_f32_e32 v13, 1.0, v13
	v_ashrrev_i32_e32 v9, 31, v8
	v_rcp_f32_e32 v10, v10
	v_rcp_f32_e32 v11, v11
	v_rcp_f32_e32 v12, v12
	v_rcp_f32_e32 v13, v13
	v_lshlrev_b64 v[8:9], 12, v[8:9]
	v_lshl_add_u64 v[8:9], s[88:89], 0, v[8:9]
	v_lshl_add_u64 v[8:9], v[134:135], 1, v[8:9]
	v_add_co_u32_e32 v8, vcc, 0xfffff000, v8
	v_cvt_pk_bf16_f32 v10, v10, v11
	v_cvt_pk_bf16_f32 v11, v12, v13
	v_addc_co_u32_e32 v9, vcc, -1, v9, vcc
	global_store_dwordx2 v[8:9], v[10:11], off offset:-2272 nt

; __device__ __forceinline__ unsigned pk_bf16(float lo, float hi) { const f32x2 v = {lo, hi}; return __builtin_bit_cast(unsigned, __builtin_convertvector(v, b16x2)); }
;     __device__ __forceinline__ void row(int r, int col32, int fq, const f32x4& a00, const f32x4& a01, const f32x4& a10, const f32x4& a11) const { half(r, col32, fq, a00, a01); half(r, col32 + HALF, fq, a10, a11); }
;     __device__ __forceinline__ void row(int r, int col32, int fq, const f32x4& a00, const f32x4& a01, const f32x4& a10, const f32x4& a11) const { half(r, col32, fq, a00, a01); half(r, col32 + HALF, fq, a10, a11); }
;     __device__ __forceinline__ void row(int r, int col32, int fq, const f32x4& a00, const f32x4& a01, const f32x4& a10, const f32x4& a11) const { half(r, col32, fq, a00, a01); half(r, col32 + HALF, fq, a10, a11); }
;     __device__ __forceinline__ void one(int row, int col, const f32x4& v) const {
;         if (col < 1536) {
;             const int which = col >> 9, hc = col & 511, h = hc >> 6, d = hc & 63, b = row / TP, t = row - b * TP;
;             const float s = which == 0 ? 0.125f : 1.0f;
;             u32x2 w; w.x = pk_bf16(v[0] * s, v[1] * s); w.y = pk_bf16(v[2] * s, v[3] * s);
;             *(u32x2*)(qkv + (size_t)which * (QKV_ONE / 2) + ((size_t)(b * NH + h) * TP + t) * 64 + d) = w;
;         } else if (col < 3328) {
;             h16x4 o; o[0] = (_Float16)v[0]; o[1] = (_Float16)v[1]; o[2] = (_Float16)v[2]; o[3] = (_Float16)v[3];
;             *(h16x4*)(urw + (size_t)row * RWS + (col - 1536)) = o;
.LBB0_502:
	s_andn2_b64 vcc, exec, s[0:1]
	s_cbranch_vccnz .LBB0_504
	v_mov_b64_e32 v[10:11], s[50:51]
	v_mad_i64_i32 v[10:11], s[0:1], v16, s73, v[10:11]
	v_cvt_pk_f16_f32 v9, v2, v3
	v_cvt_pk_f16_f32 v8, v0, v1
	v_lshl_add_u64 v[10:11], v[134:135], 1, v[10:11]
	global_store_dwordx2 v[10:11], v[8:9], off offset:-2784 nt
.LBB0_504:
	s_andn2_saveexec_b64 s[0:1], s[4:5]
	s_cbranch_execz .LBB0_506
	v_add_u32_e32 v9, v9, v8
	v_mad_i32_i24 v8, v9, s72, v16
	v_pk_mul_f32 v[10:11], v[144:145], v[0:1] op_sel_hi:[0,1]
	v_pk_mul_f32 v[12:13], v[144:145], v[2:3] op_sel_hi:[0,1]
	v_lshl_or_b32 v9, v9, 3, v123
	v_cvt_pk_bf16_f32 v10, v10, v11
	v_cvt_pk_bf16_f32 v11, v12, v13
	v_mul_hi_i32_i24_e32 v13, 0x2080, v9
	v_mul_i32_i24_e32 v12, 0x2080, v9
	v_ashrrev_i32_e32 v9, 31, v8
	s_add_u32 s4, s50, s77
	v_lshl_add_u64 v[8:9], v[12:13], 0, v[8:9]
	s_addc_u32 s5, s51, s25
	v_lshlrev_b64 v[8:9], 7, v[8:9]
	v_lshl_add_u64 v[8:9], s[4:5], 0, v[8:9]
	v_lshlrev_b32_e32 v134, 1, v122
	v_lshl_add_u64 v[8:9], v[8:9], 0, v[134:135]
	global_store_dwordx2 v[8:9], v[10:11], off nt

;     __device__ __forceinline__ void row(int r, int col32, int fq, const f32x4& a00, const f32x4& a01, const f32x4& a10, const f32x4& a11) const { half(r, col32, fq, a00, a01); half(r, col32 + HALF, fq, a10, a11); }
;     __device__ __forceinline__ void row(int r, int col32, int fq, const f32x4& a00, const f32x4& a01, const f32x4& a10, const f32x4& a11) const { half(r, col32, fq, a00, a01); half(r, col32 + HALF, fq, a10, a11); }
;     __device__ __forceinline__ void row(int r, int col32, int fq, const f32x4& a00, const f32x4& a01, const f32x4& a10, const f32x4& a11) const { half(r, col32, fq, a00, a01); half(r, col32 + HALF, fq, a10, a11); }
;     __device__ __forceinline__ void half(int row, int col32, int fq, const f32x4& v0, const f32x4& v1) const {
;     ...
;             if (col32 >= 1536 && col32 < 3072) {
;                 const int c = col32 - 1536, pos = (c & ~63) + fq * 16 + ((c & 63) >> 4) * 4;
;                 h16x8 o;
; #pragma unroll
;                 for (int j = 0; j < 4; ++j) { o[j] = (_Float16)v0[j]; o[4 + j] = (_Float16)v1[j]; }
;                 *(h16x8*)(urw + (size_t)row * RWS + pos) = o;
;             } else { one(row, col32 + 4 * fq, v0); one(row, col32 + 16 + 4 * fq, v1); }
.LBB0_507:
	s_and_b64 vcc, exec, s[12:13]
	s_cbranch_vccz .LBB0_487
	v_cvt_pk_f16_f32 v11, v10, v11
	v_cvt_pk_f16_f32 v10, v8, v9
	v_cvt_pk_f16_f32 v8, v12, v13
	v_mov_b64_e32 v[12:13], s[50:51]
	v_mad_i64_i32 v[12:13], s[6:7], v16, s73, v[12:13]
	v_cvt_pk_f16_f32 v9, v14, v15
	v_lshl_add_u64 v[12:13], v[146:147], 1, v[12:13]
	global_store_dwordx4 v[12:13], v[8:11], off nt
	s_and_b64 vcc, exec, s[14:15]
	s_mov_b64 s[6:7], -1
	s_cbranch_vccz .LBB0_488
.LBB0_509:
	s_and_b64 vcc, exec, s[6:7]
	s_cbranch_vccz .LBB0_511
	v_cvt_pk_f16_f32 v3, v2, v3
	v_cvt_pk_f16_f32 v2, v0, v1
	v_cvt_pk_f16_f32 v0, v4, v5
	v_mov_b64_e32 v[4:5], s[50:51]
	v_mad_i64_i32 v[4:5], s[0:1], v16, s73, v[4:5]
	v_cvt_pk_f16_f32 v1, v6, v7
	v_lshl_add_u64 v[4:5], v[120:121], 1, v[4:5]
	global_store_dwordx4 v[4:5], v[0:3], off nt
